# GEMM epilogues: rstd via one v_rsq_f32 instead of IEEE sqrt+divide expansion (32 sites)
# speedup vs baseline: 1.0147x; 1.0147x over previous
; #define LAS __attribute__((address_space(3)))
; __device__ __forceinline__ unsigned pk2(float lo, float hi) { f32x2 f = {lo, hi}; bf16x2_t b = __builtin_convertvector(f, bf16x2_t); return __builtin_bit_cast(unsigned, b); }
; __device__ __forceinline__ float siluf_(float x) { return x * sigmoidf_(x); }
; __device__ __forceinline__ float row_rstd(const LAS float* RS, int ord, int lrow) {
;     const float ssum = RS[ord * 256 + lrow] + RS[2048 + ord * 256 + lrow];
;     return 1.0f / sqrtf(ssum * (1.0f / D) + 1e-6f);
; }
;     __device__ __forceinline__ void operator()(const AccT& acc, const Unit& u, int wr, int wc, int fr, int fq) const {
;         const int row0 = u.pm * 256 + wr * 64 + fr, col0 = u.pn * 128 + wc * 32 + 8 * fq;
; #pragma unroll
;         for (int ai = 0; ai < 2; ++ai)
; #pragma unroll
;             for (int m = 0; m < 4; ++m) {
;                 const int row = row0 + ai * 128 + m * 16;
;                 const float rstd = row_rstd(RS, u.ord, wr * 64 + fr + ai * 128 + m * 16);
;                 bf16_t* rowp = H + (size_t)row * DFF + col0;
;                 float v[8];
; #pragma unroll
;                 for (int n = 0; n < 2; ++n)
; #pragma unroll
;                     for (int e = 0; e < 4; ++e) v[4 * n + e] = siluf_(acc[ai][0][m][n][e] * rstd) * (acc[ai][1][m][n][e] * rstd);
;                 u32x4 w; w.x = pk2(v[0], v[1]); w.y = pk2(v[2], v[3]); w.z = pk2(v[4], v[5]); w.w = pk2(v[6], v[7]);
;                 *(u32x4*)((char*)H + tiled_off(row, col0, DFF / 64)) = w;
;             }
;     }
.LBB0_154:
	v_lshl_add_u32 v144, s52, 10, v141
	v_add_u32_e32 v145, 0x2000, v144
	ds_read2_b32 v[134:135], v144 offset1:16
	ds_read2_b32 v[136:137], v145 offset1:16
	s_lshl_b32 s0, s53, 7
	s_or_b32 s0, s0, s41
	s_ashr_i32 s24, s0, 6
	v_lshl_add_u32 v143, s54, 8, v139
	s_waitcnt lgkmcnt(0)
	v_add_f32_e32 v134, v134, v136
	v_fmamk_f32 v134, v134, 0x3a000000, v236
	v_cmp_gt_f32_e32 vcc, s73, v134
	v_mul_f32_e32 v136, 0x4f800000, v134
	v_ashrrev_i32_e32 v132, 7, v143
	v_cndmask_b32_e32 v134, v134, v136, vcc
	v_rsq_f32_e32 v136, v134
	s_nop 0
	v_mul_lo_u32 v132, v132, s58
	s_ashr_i32 s25, s24, 31
	v_ashrrev_i32_e32 v133, 31, v132
	v_lshl_add_u64 v[132:133], v[132:133], 0, s[24:25]
	v_lshlrev_b64 v[132:133], 14, v[132:133]
	s_mov_b32 s92, 0x55555555
	s_mov_b32 s88, 0xffda0d24
	s_mov_b32 s93, 0x3fe55555
	s_mov_b32 s89, 0x3c7777d0
	s_mov_b32 s79, 0x30000
	v_mov_b32_e32 v134, v136
	v_pk_mul_f32 v[124:125], v[124:125], v[134:135] op_sel_hi:[1,0]
	v_pk_mul_f32 v[120:121], v[120:121], v[134:135] op_sel_hi:[1,0]
	v_mul_f32_e32 v136, 0xbfb8aa3b, v124
	v_exp_f32_e32 v136, v136
	v_pk_mul_f32 v[122:123], v[122:123], v[134:135] op_sel_hi:[1,0]
	v_pk_mul_f32 v[116:117], v[116:117], v[134:135] op_sel_hi:[1,0]
	v_pk_mul_f32 v[112:113], v[112:113], v[134:135] op_sel_hi:[1,0]
	v_add_f32_e32 v136, 1.0, v136
	v_rcp_f32_e32 v146, v136
	v_mul_f32_e32 v136, 0xbfb8aa3b, v125
	v_exp_f32_e32 v136, v136
	v_pk_mul_f32 v[114:115], v[114:115], v[134:135] op_sel_hi:[1,0]
	v_add_f32_e32 v136, 1.0, v136
	v_rcp_f32_e32 v147, v136
	s_nop 0
	v_pk_mul_f32 v[124:125], v[124:125], v[146:147]
	s_nop 0
	v_pk_mul_f32 v[120:121], v[120:121], v[124:125]
	v_pk_mul_f32 v[124:125], v[126:127], v[134:135] op_sel_hi:[1,0]
	s_nop 0
	v_mul_f32_e32 v126, 0xbfb8aa3b, v124
	v_mul_f32_e32 v127, 0xbfb8aa3b, v125
	v_exp_f32_e32 v126, v126
	v_exp_f32_e32 v127, v127
	v_add_f32_e32 v126, 1.0, v126
	v_add_f32_e32 v127, 1.0, v127
	v_rcp_f32_e32 v126, v126
	v_rcp_f32_e32 v127, v127
	s_nop 0
	v_pk_mul_f32 v[124:125], v[124:125], v[126:127]
	s_nop 0
	v_pk_mul_f32 v[122:123], v[122:123], v[124:125]
	v_mul_f32_e32 v124, 0xbfb8aa3b, v116
	v_mul_f32_e32 v125, 0xbfb8aa3b, v117
	v_exp_f32_e32 v124, v124
	v_exp_f32_e32 v125, v125
	v_add_f32_e32 v124, 1.0, v124
	v_add_f32_e32 v125, 1.0, v125
	v_rcp_f32_e32 v124, v124
	v_rcp_f32_e32 v125, v125
	s_nop 0
	v_pk_mul_f32 v[116:117], v[116:117], v[124:125]
	s_nop 0
	v_pk_mul_f32 v[112:113], v[112:113], v[116:117]
	v_pk_mul_f32 v[116:117], v[118:119], v[134:135] op_sel_hi:[1,0]
	s_nop 0
	v_mul_f32_e32 v118, 0xbfb8aa3b, v116
	v_mul_f32_e32 v119, 0xbfb8aa3b, v117
	v_exp_f32_e32 v118, v118
	v_exp_f32_e32 v119, v119
	v_add_f32_e32 v118, 1.0, v118
	v_add_f32_e32 v119, 1.0, v119
	v_rcp_f32_e32 v118, v118
	v_rcp_f32_e32 v119, v119
	s_nop 0
	v_pk_mul_f32 v[116:117], v[116:117], v[118:119]
	s_nop 0
	v_pk_mul_f32 v[114:115], v[114:115], v[116:117]
	v_cvt_pk_bf16_f32 v118, v112, v113
	v_lshlrev_b32_e32 v112, 6, v143
	v_cvt_pk_bf16_f32 v119, v114, v115
	v_and_or_b32 v114, v112, s87, v138
	v_lshlrev_b32_e32 v112, 2, v143
	v_and_b32_e32 v115, 32, v112
	v_bitop3_b32 v192, v114, s45, v115 bitop3:0xde
	v_lshl_add_u64 v[112:113], s[8:9], 0, v[132:133]
	v_cvt_pk_bf16_f32 v116, v120, v121
	v_cvt_pk_bf16_f32 v117, v122, v123
	v_lshl_add_u64 v[120:121], v[112:113], 0, v[192:193]
	global_store_dwordx4 v[120:121], v[116:119], off
	s_nop 1
	v_add_f32_e32 v116, v135, v137
	v_fmamk_f32 v116, v116, 0x3a000000, v236
	v_cmp_gt_f32_e32 vcc, s73, v116
	v_mul_f32_e32 v117, 0x4f800000, v116
	s_nop 0
	v_cndmask_b32_e32 v116, v116, v117, vcc
	v_rsq_f32_e32 v117, v116
	s_nop 0
	s_nop 0
	s_nop 0
	s_nop 1
	s_nop 1
	s_nop 0
	v_mov_b32_e32 v116, v117
	v_pk_mul_f32 v[108:109], v[108:109], v[116:117] op_sel_hi:[1,0]
	s_nop 0
	v_mul_f32_e32 v117, 0xbfb8aa3b, v108
	v_exp_f32_e32 v117, v117
	s_nop 0
	v_add_f32_e32 v117, 1.0, v117
	v_rcp_f32_e32 v118, v117
	v_mul_f32_e32 v117, 0xbfb8aa3b, v109
	v_exp_f32_e32 v117, v117
	s_nop 0
	v_add_f32_e32 v117, 1.0, v117
	v_rcp_f32_e32 v119, v117
	v_pk_mul_f32 v[104:105], v[104:105], v[116:117] op_sel_hi:[1,0]
	v_pk_mul_f32 v[106:107], v[106:107], v[116:117] op_sel_hi:[1,0]
	v_pk_mul_f32 v[100:101], v[100:101], v[116:117] op_sel_hi:[1,0]
	v_pk_mul_f32 v[108:109], v[108:109], v[118:119]
	v_pk_mul_f32 v[96:97], v[96:97], v[116:117] op_sel_hi:[1,0]
	v_pk_mul_f32 v[104:105], v[104:105], v[108:109]
	v_pk_mul_f32 v[108:109], v[110:111], v[116:117] op_sel_hi:[1,0]
	v_pk_mul_f32 v[98:99], v[98:99], v[116:117] op_sel_hi:[1,0]
	v_mul_f32_e32 v110, 0xbfb8aa3b, v108
	v_mul_f32_e32 v111, 0xbfb8aa3b, v109
	v_exp_f32_e32 v110, v110
	v_exp_f32_e32 v111, v111
	v_add_f32_e32 v110, 1.0, v110
	v_add_f32_e32 v111, 1.0, v111
	v_rcp_f32_e32 v110, v110
	v_rcp_f32_e32 v111, v111
	s_nop 0
	v_pk_mul_f32 v[108:109], v[108:109], v[110:111]
	s_nop 0
	v_pk_mul_f32 v[106:107], v[106:107], v[108:109]
	v_mul_f32_e32 v108, 0xbfb8aa3b, v100
	v_mul_f32_e32 v109, 0xbfb8aa3b, v101
	v_exp_f32_e32 v108, v108
	v_exp_f32_e32 v109, v109
	v_add_f32_e32 v108, 1.0, v108
	v_add_f32_e32 v109, 1.0, v109
	v_rcp_f32_e32 v108, v108
	v_rcp_f32_e32 v109, v109
	s_nop 0
	v_pk_mul_f32 v[100:101], v[100:101], v[108:109]
	s_nop 0
	v_pk_mul_f32 v[100:101], v[96:97], v[100:101]
	v_pk_mul_f32 v[96:97], v[102:103], v[116:117] op_sel_hi:[1,0]
	v_or_b32_e32 v108, 16, v143
	v_mul_f32_e32 v102, 0xbfb8aa3b, v96
	v_mul_f32_e32 v103, 0xbfb8aa3b, v97
	v_exp_f32_e32 v102, v102
	v_exp_f32_e32 v103, v103
	v_add_f32_e32 v102, 1.0, v102
	v_add_f32_e32 v103, 1.0, v103
	v_rcp_f32_e32 v102, v102
	v_rcp_f32_e32 v103, v103
	s_nop 0
	v_pk_mul_f32 v[96:97], v[96:97], v[102:103]
	s_nop 0
	v_pk_mul_f32 v[102:103], v[98:99], v[96:97]
	v_cvt_pk_bf16_f32 v98, v100, v101
	v_lshrrev_b32_e32 v100, 3, v108
	v_and_or_b32 v100, v100, 10, s44
	v_lshlrev_b32_e32 v100, 10, v100
	v_bitop3_b32 v192, v114, v100, v115 bitop3:0xde
	v_cvt_pk_bf16_f32 v96, v104, v105
	v_cvt_pk_bf16_f32 v97, v106, v107
	v_cvt_pk_bf16_f32 v99, v102, v103
	v_lshl_add_u64 v[100:101], v[112:113], 0, v[192:193]
	global_store_dwordx4 v[100:101], v[96:99], off
	ds_read2_b32 v[96:97], v144 offset0:32 offset1:48
	ds_read2_b32 v[98:99], v145 offset0:32 offset1:48
	s_waitcnt lgkmcnt(0)
; #define LAS __attribute__((address_space(3)))
; __device__ __forceinline__ unsigned pk2(float lo, float hi) { f32x2 f = {lo, hi}; bf16x2_t b = __builtin_convertvector(f, bf16x2_t); return __builtin_bit_cast(unsigned, b); }
; __device__ __forceinline__ float siluf_(float x) { return x * sigmoidf_(x); }
; __device__ __forceinline__ float row_rstd(const LAS float* RS, int ord, int lrow) {
;     const float ssum = RS[ord * 256 + lrow] + RS[2048 + ord * 256 + lrow];
;     return 1.0f / sqrtf(ssum * (1.0f / D) + 1e-6f);
; }
;     __device__ __forceinline__ void operator()(const AccT& acc, const Unit& u, int wr, int wc, int fr, int fq) const {
;         const int row0 = u.pm * 256 + wr * 64 + fr, col0 = u.pn * 128 + wc * 32 + 8 * fq;
; #pragma unroll
;         for (int ai = 0; ai < 2; ++ai)
; #pragma unroll
;             for (int m = 0; m < 4; ++m) {
;                 const int row = row0 + ai * 128 + m * 16;
;                 const float rstd = row_rstd(RS, u.ord, wr * 64 + fr + ai * 128 + m * 16);
;                 bf16_t* rowp = H + (size_t)row * DFF + col0;
;                 float v[8];
; #pragma unroll
;                 for (int n = 0; n < 2; ++n)
; #pragma unroll
;                     for (int e = 0; e < 4; ++e) v[4 * n + e] = siluf_(acc[ai][0][m][n][e] * rstd) * (acc[ai][1][m][n][e] * rstd);
;                 u32x4 w; w.x = pk2(v[0], v[1]); w.y = pk2(v[2], v[3]); w.z = pk2(v[4], v[5]); w.w = pk2(v[6], v[7]);
;                 *(u32x4*)((char*)H + tiled_off(row, col0, DFF / 64)) = w;
;             }
;     }
	v_add_f32_e32 v96, v96, v98
	v_fmamk_f32 v96, v96, 0x3a000000, v236
	v_cmp_gt_f32_e32 vcc, s73, v96
	v_mul_f32_e32 v98, 0x4f800000, v96
	s_nop 0
	v_cndmask_b32_e32 v96, v96, v98, vcc
	v_rsq_f32_e32 v98, v96
	s_nop 0
	s_nop 0
	s_nop 0
	s_nop 1
	s_nop 1
	s_nop 0
	v_mov_b32_e32 v96, v98
	v_pk_mul_f32 v[92:93], v[92:93], v[96:97] op_sel_hi:[1,0]
	v_pk_mul_f32 v[88:89], v[88:89], v[96:97] op_sel_hi:[1,0]
	v_mul_f32_e32 v98, 0xbfb8aa3b, v92
	v_exp_f32_e32 v98, v98
	v_pk_mul_f32 v[90:91], v[90:91], v[96:97] op_sel_hi:[1,0]
	v_pk_mul_f32 v[84:85], v[84:85], v[96:97] op_sel_hi:[1,0]
	v_pk_mul_f32 v[80:81], v[80:81], v[96:97] op_sel_hi:[1,0]
	v_add_f32_e32 v98, 1.0, v98
	v_rcp_f32_e32 v100, v98
	v_mul_f32_e32 v98, 0xbfb8aa3b, v93
	v_exp_f32_e32 v98, v98
	v_pk_mul_f32 v[82:83], v[82:83], v[96:97] op_sel_hi:[1,0]
	v_add_f32_e32 v98, 1.0, v98
	v_rcp_f32_e32 v101, v98
	s_nop 0
	v_pk_mul_f32 v[92:93], v[92:93], v[100:101]
	s_nop 0
	v_pk_mul_f32 v[88:89], v[88:89], v[92:93]
	v_pk_mul_f32 v[92:93], v[94:95], v[96:97] op_sel_hi:[1,0]
	s_nop 0
	v_mul_f32_e32 v94, 0xbfb8aa3b, v92
	v_mul_f32_e32 v95, 0xbfb8aa3b, v93
	v_exp_f32_e32 v94, v94
	v_exp_f32_e32 v95, v95
	v_add_f32_e32 v94, 1.0, v94
	v_add_f32_e32 v95, 1.0, v95
	v_rcp_f32_e32 v94, v94
	v_rcp_f32_e32 v95, v95
	s_nop 0
	v_pk_mul_f32 v[92:93], v[92:93], v[94:95]
	s_nop 0
	v_pk_mul_f32 v[90:91], v[90:91], v[92:93]
	v_mul_f32_e32 v92, 0xbfb8aa3b, v84
	v_mul_f32_e32 v93, 0xbfb8aa3b, v85
	v_exp_f32_e32 v92, v92
	v_exp_f32_e32 v93, v93
	v_add_f32_e32 v92, 1.0, v92
	v_add_f32_e32 v93, 1.0, v93
	v_rcp_f32_e32 v92, v92
	v_rcp_f32_e32 v93, v93
	s_nop 0
	v_pk_mul_f32 v[84:85], v[84:85], v[92:93]
	s_nop 0
	v_pk_mul_f32 v[84:85], v[80:81], v[84:85]
	v_pk_mul_f32 v[80:81], v[86:87], v[96:97] op_sel_hi:[1,0]
	v_or_b32_e32 v92, 32, v143
	v_mul_f32_e32 v86, 0xbfb8aa3b, v80
	v_mul_f32_e32 v87, 0xbfb8aa3b, v81
	v_exp_f32_e32 v86, v86
	v_exp_f32_e32 v87, v87
	v_add_f32_e32 v86, 1.0, v86
	v_add_f32_e32 v87, 1.0, v87
	v_rcp_f32_e32 v86, v86
	v_rcp_f32_e32 v87, v87
	s_nop 0
	v_pk_mul_f32 v[80:81], v[80:81], v[86:87]
	s_nop 0
	v_pk_mul_f32 v[86:87], v[82:83], v[80:81]
	v_cvt_pk_bf16_f32 v82, v84, v85
	v_lshrrev_b32_e32 v84, 3, v92
	v_and_or_b32 v84, v84, 12, s44
	v_lshlrev_b32_e32 v84, 10, v84
	v_bitop3_b32 v192, v114, v84, v115 bitop3:0xde
	v_cvt_pk_bf16_f32 v80, v88, v89
	v_cvt_pk_bf16_f32 v81, v90, v91
	v_cvt_pk_bf16_f32 v83, v86, v87
	v_lshl_add_u64 v[84:85], v[112:113], 0, v[192:193]
	global_store_dwordx4 v[84:85], v[80:83], off
	s_nop 1
	v_add_f32_e32 v80, v97, v99
	v_fmamk_f32 v80, v80, 0x3a000000, v236
	v_cmp_gt_f32_e32 vcc, s73, v80
	v_mul_f32_e32 v81, 0x4f800000, v80
	s_nop 0
	v_cndmask_b32_e32 v80, v80, v81, vcc
	v_rsq_f32_e32 v81, v80
	s_nop 0
	s_nop 0
	s_nop 0
	s_nop 1
	s_nop 1
	s_nop 0
	v_mov_b32_e32 v80, v81
	v_pk_mul_f32 v[76:77], v[76:77], v[80:81] op_sel_hi:[1,0]
	s_nop 0
	v_mul_f32_e32 v81, 0xbfb8aa3b, v76
	v_exp_f32_e32 v81, v81
	s_nop 0
	v_add_f32_e32 v81, 1.0, v81
	v_rcp_f32_e32 v82, v81
	v_mul_f32_e32 v81, 0xbfb8aa3b, v77
	v_exp_f32_e32 v81, v81
	s_nop 0
	v_add_f32_e32 v81, 1.0, v81
	v_rcp_f32_e32 v83, v81
	v_pk_mul_f32 v[72:73], v[72:73], v[80:81] op_sel_hi:[1,0]
	v_pk_mul_f32 v[74:75], v[74:75], v[80:81] op_sel_hi:[1,0]
	v_pk_mul_f32 v[68:69], v[68:69], v[80:81] op_sel_hi:[1,0]
	v_pk_mul_f32 v[76:77], v[76:77], v[82:83]
	v_pk_mul_f32 v[64:65], v[64:65], v[80:81] op_sel_hi:[1,0]
	v_pk_mul_f32 v[72:73], v[72:73], v[76:77]
	v_pk_mul_f32 v[76:77], v[78:79], v[80:81] op_sel_hi:[1,0]
	v_pk_mul_f32 v[66:67], v[66:67], v[80:81] op_sel_hi:[1,0]
	v_mul_f32_e32 v78, 0xbfb8aa3b, v76
	v_mul_f32_e32 v79, 0xbfb8aa3b, v77
	v_exp_f32_e32 v78, v78
	v_exp_f32_e32 v79, v79
	v_add_f32_e32 v78, 1.0, v78
	v_add_f32_e32 v79, 1.0, v79
	v_rcp_f32_e32 v78, v78
	v_rcp_f32_e32 v79, v79
	s_nop 0
	v_pk_mul_f32 v[76:77], v[76:77], v[78:79]
	s_nop 0
	v_pk_mul_f32 v[74:75], v[74:75], v[76:77]
	v_mul_f32_e32 v76, 0xbfb8aa3b, v68
	v_mul_f32_e32 v77, 0xbfb8aa3b, v69
	v_exp_f32_e32 v76, v76
	v_exp_f32_e32 v77, v77
	v_add_f32_e32 v76, 1.0, v76
	v_add_f32_e32 v77, 1.0, v77
	v_rcp_f32_e32 v76, v76
	v_rcp_f32_e32 v77, v77
	s_nop 0
	v_pk_mul_f32 v[68:69], v[68:69], v[76:77]
	s_nop 0
	v_pk_mul_f32 v[68:69], v[64:65], v[68:69]
	v_pk_mul_f32 v[64:65], v[70:71], v[80:81] op_sel_hi:[1,0]
	v_or_b32_e32 v76, 48, v143
	v_mul_f32_e32 v70, 0xbfb8aa3b, v64
	v_mul_f32_e32 v71, 0xbfb8aa3b, v65
	v_exp_f32_e32 v70, v70
	v_exp_f32_e32 v71, v71
	v_add_f32_e32 v70, 1.0, v70
	v_add_f32_e32 v71, 1.0, v71
	v_rcp_f32_e32 v70, v70
	v_rcp_f32_e32 v71, v71
	s_nop 0
	v_pk_mul_f32 v[64:65], v[64:65], v[70:71]
	s_nop 0
	v_pk_mul_f32 v[70:71], v[66:67], v[64:65]
	v_cvt_pk_bf16_f32 v66, v68, v69
	v_lshrrev_b32_e32 v68, 3, v76
	v_and_or_b32 v68, v68, 14, s44
	v_lshlrev_b32_e32 v68, 10, v68
	v_bitop3_b32 v192, v114, v68, v115 bitop3:0xde
	v_cvt_pk_bf16_f32 v64, v72, v73
	v_cvt_pk_bf16_f32 v65, v74, v75
	v_cvt_pk_bf16_f32 v67, v70, v71
	v_lshl_add_u64 v[68:69], v[112:113], 0, v[192:193]
	global_store_dwordx4 v[68:69], v[64:67], off
	ds_read2_b32 v[66:67], v144 offset0:128 offset1:144
	ds_read2_b32 v[68:69], v145 offset0:128 offset1:144
	v_add_u32_e32 v72, 0x80, v143
	v_ashrrev_i32_e32 v64, 7, v72
	v_mul_lo_u32 v64, v64, s58
	v_ashrrev_i32_e32 v65, 31, v64
	s_waitcnt lgkmcnt(0)
; #define LAS __attribute__((address_space(3)))
; __device__ __forceinline__ unsigned pk2(float lo, float hi) { f32x2 f = {lo, hi}; bf16x2_t b = __builtin_convertvector(f, bf16x2_t); return __builtin_bit_cast(unsigned, b); }
; __device__ __forceinline__ float siluf_(float x) { return x * sigmoidf_(x); }
; __device__ __forceinline__ float row_rstd(const LAS float* RS, int ord, int lrow) {
;     const float ssum = RS[ord * 256 + lrow] + RS[2048 + ord * 256 + lrow];
;     return 1.0f / sqrtf(ssum * (1.0f / D) + 1e-6f);
; }
;     __device__ __forceinline__ void operator()(const AccT& acc, const Unit& u, int wr, int wc, int fr, int fq) const {
;         const int row0 = u.pm * 256 + wr * 64 + fr, col0 = u.pn * 128 + wc * 32 + 8 * fq;
; #pragma unroll
;         for (int ai = 0; ai < 2; ++ai)
; #pragma unroll
;             for (int m = 0; m < 4; ++m) {
;                 const int row = row0 + ai * 128 + m * 16;
;                 const float rstd = row_rstd(RS, u.ord, wr * 64 + fr + ai * 128 + m * 16);
;                 bf16_t* rowp = H + (size_t)row * DFF + col0;
;                 float v[8];
; #pragma unroll
;                 for (int n = 0; n < 2; ++n)
; #pragma unroll
;                     for (int e = 0; e < 4; ++e) v[4 * n + e] = siluf_(acc[ai][0][m][n][e] * rstd) * (acc[ai][1][m][n][e] * rstd);
;                 u32x4 w; w.x = pk2(v[0], v[1]); w.y = pk2(v[2], v[3]); w.z = pk2(v[4], v[5]); w.w = pk2(v[6], v[7]);
;                 *(u32x4*)((char*)H + tiled_off(row, col0, DFF / 64)) = w;
;             }
;     }
	v_add_f32_e32 v66, v66, v68
	v_fmamk_f32 v66, v66, 0x3a000000, v236
	v_cmp_gt_f32_e32 vcc, s73, v66
	v_mul_f32_e32 v68, 0x4f800000, v66
	v_lshl_add_u64 v[64:65], v[64:65], 0, s[24:25]
	v_cndmask_b32_e32 v66, v66, v68, vcc
	v_rsq_f32_e32 v68, v66
	s_nop 0
	v_lshlrev_b64 v[64:65], 14, v[64:65]
	s_nop 0
	s_nop 1
	s_nop 1
	s_nop 0
	v_mov_b32_e32 v66, v68
	v_pk_mul_f32 v[60:61], v[60:61], v[66:67] op_sel_hi:[1,0]
	v_pk_mul_f32 v[56:57], v[56:57], v[66:67] op_sel_hi:[1,0]
	v_mul_f32_e32 v68, 0xbfb8aa3b, v60
	v_exp_f32_e32 v68, v68
	v_pk_mul_f32 v[58:59], v[58:59], v[66:67] op_sel_hi:[1,0]
	v_pk_mul_f32 v[52:53], v[52:53], v[66:67] op_sel_hi:[1,0]
	v_pk_mul_f32 v[48:49], v[48:49], v[66:67] op_sel_hi:[1,0]
	v_add_f32_e32 v68, 1.0, v68
	v_rcp_f32_e32 v70, v68
	v_mul_f32_e32 v68, 0xbfb8aa3b, v61
	v_exp_f32_e32 v68, v68
	v_pk_mul_f32 v[50:51], v[50:51], v[66:67] op_sel_hi:[1,0]
	v_add_f32_e32 v68, 1.0, v68
	v_rcp_f32_e32 v71, v68
	s_nop 0
	v_pk_mul_f32 v[60:61], v[60:61], v[70:71]
	s_nop 0
	v_pk_mul_f32 v[56:57], v[56:57], v[60:61]
	v_pk_mul_f32 v[60:61], v[62:63], v[66:67] op_sel_hi:[1,0]
	s_nop 0
	v_mul_f32_e32 v62, 0xbfb8aa3b, v60
	v_mul_f32_e32 v63, 0xbfb8aa3b, v61
	v_exp_f32_e32 v62, v62
	v_exp_f32_e32 v63, v63
	v_add_f32_e32 v62, 1.0, v62
	v_add_f32_e32 v63, 1.0, v63
	v_rcp_f32_e32 v62, v62
	v_rcp_f32_e32 v63, v63
	s_nop 0
	v_pk_mul_f32 v[60:61], v[60:61], v[62:63]
	s_nop 0
	v_pk_mul_f32 v[58:59], v[58:59], v[60:61]
	v_mul_f32_e32 v60, 0xbfb8aa3b, v52
	v_mul_f32_e32 v61, 0xbfb8aa3b, v53
	v_exp_f32_e32 v60, v60
	v_exp_f32_e32 v61, v61
	v_add_f32_e32 v60, 1.0, v60
	v_add_f32_e32 v61, 1.0, v61
	v_rcp_f32_e32 v60, v60
	v_rcp_f32_e32 v61, v61
	s_nop 0
	v_pk_mul_f32 v[52:53], v[52:53], v[60:61]
	s_nop 0
	v_pk_mul_f32 v[48:49], v[48:49], v[52:53]
	v_pk_mul_f32 v[52:53], v[54:55], v[66:67] op_sel_hi:[1,0]
	s_nop 0
	v_mul_f32_e32 v54, 0xbfb8aa3b, v52
	v_mul_f32_e32 v55, 0xbfb8aa3b, v53
	v_exp_f32_e32 v54, v54
	v_exp_f32_e32 v55, v55
	v_add_f32_e32 v54, 1.0, v54
	v_add_f32_e32 v55, 1.0, v55
	v_rcp_f32_e32 v54, v54
	v_rcp_f32_e32 v55, v55
	s_nop 0
	v_pk_mul_f32 v[52:53], v[52:53], v[54:55]
	s_nop 0
	v_pk_mul_f32 v[50:51], v[50:51], v[52:53]
	v_cvt_pk_bf16_f32 v54, v48, v49
	v_lshlrev_b32_e32 v48, 6, v72
	v_cvt_pk_bf16_f32 v55, v50, v51
	v_and_or_b32 v50, v48, s87, v138
	v_lshlrev_b32_e32 v48, 2, v72
	v_and_b32_e32 v51, 32, v48
	v_bitop3_b32 v192, v50, s45, v51 bitop3:0xde
	v_lshl_add_u64 v[48:49], s[8:9], 0, v[64:65]
	v_cvt_pk_bf16_f32 v52, v56, v57
	v_cvt_pk_bf16_f32 v53, v58, v59
	v_lshl_add_u64 v[56:57], v[48:49], 0, v[192:193]
	global_store_dwordx4 v[56:57], v[52:55], off
	s_nop 1
	v_add_f32_e32 v52, v67, v69
	v_fmamk_f32 v52, v52, 0x3a000000, v236
	v_cmp_gt_f32_e32 vcc, s73, v52
	v_mul_f32_e32 v53, 0x4f800000, v52
	s_nop 0
	v_cndmask_b32_e32 v52, v52, v53, vcc
	v_rsq_f32_e32 v53, v52
	s_nop 0
	s_nop 0
	s_nop 0
	s_nop 1
	s_nop 1
	s_nop 0
	v_mov_b32_e32 v52, v53
	v_pk_mul_f32 v[44:45], v[44:45], v[52:53] op_sel_hi:[1,0]
	s_nop 0
	v_mul_f32_e32 v53, 0xbfb8aa3b, v44
	v_exp_f32_e32 v53, v53
	s_nop 0
	v_add_f32_e32 v53, 1.0, v53
	v_rcp_f32_e32 v54, v53
	v_mul_f32_e32 v53, 0xbfb8aa3b, v45
	v_exp_f32_e32 v53, v53
	s_nop 0
	v_add_f32_e32 v53, 1.0, v53
	v_rcp_f32_e32 v55, v53
	v_pk_mul_f32 v[40:41], v[40:41], v[52:53] op_sel_hi:[1,0]
	v_pk_mul_f32 v[42:43], v[42:43], v[52:53] op_sel_hi:[1,0]
	v_pk_mul_f32 v[36:37], v[36:37], v[52:53] op_sel_hi:[1,0]
	v_pk_mul_f32 v[44:45], v[44:45], v[54:55]
	v_pk_mul_f32 v[32:33], v[32:33], v[52:53] op_sel_hi:[1,0]
	v_pk_mul_f32 v[40:41], v[40:41], v[44:45]
	v_pk_mul_f32 v[44:45], v[46:47], v[52:53] op_sel_hi:[1,0]
	v_pk_mul_f32 v[34:35], v[34:35], v[52:53] op_sel_hi:[1,0]
	v_mul_f32_e32 v46, 0xbfb8aa3b, v44
	v_mul_f32_e32 v47, 0xbfb8aa3b, v45
	v_exp_f32_e32 v46, v46
	v_exp_f32_e32 v47, v47
	v_add_f32_e32 v46, 1.0, v46
	v_add_f32_e32 v47, 1.0, v47
	v_rcp_f32_e32 v46, v46
	v_rcp_f32_e32 v47, v47
	s_nop 0
	v_pk_mul_f32 v[44:45], v[44:45], v[46:47]
	s_nop 0
	v_pk_mul_f32 v[42:43], v[42:43], v[44:45]
	v_mul_f32_e32 v44, 0xbfb8aa3b, v36
	v_mul_f32_e32 v45, 0xbfb8aa3b, v37
	v_exp_f32_e32 v44, v44
	v_exp_f32_e32 v45, v45
	v_add_f32_e32 v44, 1.0, v44
	v_add_f32_e32 v45, 1.0, v45
	v_rcp_f32_e32 v44, v44
	v_rcp_f32_e32 v45, v45
	s_nop 0
	v_pk_mul_f32 v[36:37], v[36:37], v[44:45]
	s_nop 0
	v_pk_mul_f32 v[36:37], v[32:33], v[36:37]
	v_pk_mul_f32 v[32:33], v[38:39], v[52:53] op_sel_hi:[1,0]
	v_add_u32_e32 v44, 0x90, v143
	v_mul_f32_e32 v38, 0xbfb8aa3b, v32
	v_mul_f32_e32 v39, 0xbfb8aa3b, v33
	v_exp_f32_e32 v38, v38
	v_exp_f32_e32 v39, v39
	v_add_f32_e32 v38, 1.0, v38
	v_add_f32_e32 v39, 1.0, v39
	v_rcp_f32_e32 v38, v38
	v_rcp_f32_e32 v39, v39
	s_nop 0
	v_pk_mul_f32 v[32:33], v[32:33], v[38:39]
	s_nop 0
	v_pk_mul_f32 v[38:39], v[34:35], v[32:33]
	v_cvt_pk_bf16_f32 v34, v36, v37
	v_lshrrev_b32_e32 v36, 3, v44
	v_and_or_b32 v36, v36, 14, s44
	v_lshlrev_b32_e32 v36, 10, v36
	v_bitop3_b32 v192, v50, v36, v51 bitop3:0xde
	v_cvt_pk_bf16_f32 v32, v40, v41
	v_cvt_pk_bf16_f32 v33, v42, v43
	v_cvt_pk_bf16_f32 v35, v38, v39
	v_lshl_add_u64 v[36:37], v[48:49], 0, v[192:193]
	global_store_dwordx4 v[36:37], v[32:35], off
	ds_read2_b32 v[32:33], v144 offset0:160 offset1:176
	ds_read2_b32 v[34:35], v145 offset0:160 offset1:176
	s_waitcnt lgkmcnt(0)
; __device__ __forceinline__ unsigned pk2(float lo, float hi) { f32x2 f = {lo, hi}; bf16x2_t b = __builtin_convertvector(f, bf16x2_t); return __builtin_bit_cast(unsigned, b); }
; __device__ __forceinline__ float siluf_(float x) { return x * sigmoidf_(x); }
; #define PG8_BAR __builtin_amdgcn_s_barrier()
; template <class Epi>
; __device__ __forceinline__ void gemm_phase(LAS unsigned char* lds, const Gemm g, const StaticOrder& S, const Epi& E) {
;     ...
;         if (!has_next) break;
; #pragma unroll
;         for (int a = 0; a < 2; ++a)
; #pragma unroll
;             for (int b = 0; b < 2; ++b)
; #pragma unroll
;                 for (int m = 0; m < 4; ++m)
; #pragma unroll
;                     for (int n = 0; n < 2; ++n) acc[a][b][m][n] = (f32x4){0.f, 0.f, 0.f, 0.f};
;         cur = nxt; cA = nA; cB = nB; ++ui;
;         if (wr == 1) PG8_BAR;
;     __device__ __forceinline__ void operator()(const AccT& acc, const Unit& u, int wr, int wc, int fr, int fq) const {
;         const int row0 = u.pm * 256 + wr * 64 + fr, col0 = u.pn * 128 + wc * 32 + 8 * fq;
; #pragma unroll
;         for (int ai = 0; ai < 2; ++ai)
; #pragma unroll
;             for (int m = 0; m < 4; ++m) {
;                 const int row = row0 + ai * 128 + m * 16;
;                 const float rstd = row_rstd(RS, u.ord, wr * 64 + fr + ai * 128 + m * 16);
;                 bf16_t* rowp = H + (size_t)row * DFF + col0;
;                 float v[8];
; #pragma unroll
;                 for (int n = 0; n < 2; ++n)
; #pragma unroll
;                     for (int e = 0; e < 4; ++e) v[4 * n + e] = siluf_(acc[ai][0][m][n][e] * rstd) * (acc[ai][1][m][n][e] * rstd);
;                 u32x4 w; w.x = pk2(v[0], v[1]); w.y = pk2(v[2], v[3]); w.z = pk2(v[4], v[5]); w.w = pk2(v[6], v[7]);
;                 *(u32x4*)((char*)H + tiled_off(row, col0, DFF / 64)) = w;
;             }
;     }
	v_add_f32_e32 v32, v32, v34
	v_fmamk_f32 v32, v32, 0x3a000000, v236
	v_cmp_gt_f32_e32 vcc, s73, v32
	v_mul_f32_e32 v34, 0x4f800000, v32
	s_nop 0
	v_cndmask_b32_e32 v32, v32, v34, vcc
	v_rsq_f32_e32 v34, v32
	s_nop 0
	s_nop 0
	s_nop 0
	s_nop 1
	s_nop 1
	s_nop 0
	v_mov_b32_e32 v32, v34
	v_pk_mul_f32 v[28:29], v[28:29], v[32:33] op_sel_hi:[1,0]
	v_pk_mul_f32 v[24:25], v[24:25], v[32:33] op_sel_hi:[1,0]
	v_mul_f32_e32 v34, 0xbfb8aa3b, v28
	v_exp_f32_e32 v34, v34
	v_pk_mul_f32 v[26:27], v[26:27], v[32:33] op_sel_hi:[1,0]
	v_pk_mul_f32 v[20:21], v[20:21], v[32:33] op_sel_hi:[1,0]
	v_pk_mul_f32 v[16:17], v[16:17], v[32:33] op_sel_hi:[1,0]
	v_add_f32_e32 v34, 1.0, v34
	v_rcp_f32_e32 v36, v34
	v_mul_f32_e32 v34, 0xbfb8aa3b, v29
	v_exp_f32_e32 v34, v34
	v_pk_mul_f32 v[18:19], v[18:19], v[32:33] op_sel_hi:[1,0]
	v_add_f32_e32 v34, 1.0, v34
	v_rcp_f32_e32 v37, v34
	s_nop 0
	v_pk_mul_f32 v[28:29], v[28:29], v[36:37]
	s_nop 0
	v_pk_mul_f32 v[24:25], v[24:25], v[28:29]
	v_pk_mul_f32 v[28:29], v[30:31], v[32:33] op_sel_hi:[1,0]
	s_nop 0
	v_mul_f32_e32 v30, 0xbfb8aa3b, v28
	v_mul_f32_e32 v31, 0xbfb8aa3b, v29
	v_exp_f32_e32 v30, v30
	v_exp_f32_e32 v31, v31
	v_add_f32_e32 v30, 1.0, v30
	v_add_f32_e32 v31, 1.0, v31
	v_rcp_f32_e32 v30, v30
	v_rcp_f32_e32 v31, v31
	s_nop 0
	v_pk_mul_f32 v[28:29], v[28:29], v[30:31]
	s_nop 0
	v_pk_mul_f32 v[26:27], v[26:27], v[28:29]
	v_mul_f32_e32 v28, 0xbfb8aa3b, v20
	v_mul_f32_e32 v29, 0xbfb8aa3b, v21
	v_exp_f32_e32 v28, v28
	v_exp_f32_e32 v29, v29
	v_add_f32_e32 v28, 1.0, v28
	v_add_f32_e32 v29, 1.0, v29
	v_rcp_f32_e32 v28, v28
	v_rcp_f32_e32 v29, v29
	s_nop 0
	v_pk_mul_f32 v[20:21], v[20:21], v[28:29]
	s_nop 0
	v_pk_mul_f32 v[20:21], v[16:17], v[20:21]
	v_pk_mul_f32 v[16:17], v[22:23], v[32:33] op_sel_hi:[1,0]
	v_add_u32_e32 v28, 0xa0, v143
	v_mul_f32_e32 v22, 0xbfb8aa3b, v16
	v_mul_f32_e32 v23, 0xbfb8aa3b, v17
	v_exp_f32_e32 v22, v22
	v_exp_f32_e32 v23, v23
	v_add_f32_e32 v22, 1.0, v22
	v_add_f32_e32 v23, 1.0, v23
	v_rcp_f32_e32 v22, v22
	v_rcp_f32_e32 v23, v23
	s_nop 0
	v_pk_mul_f32 v[16:17], v[16:17], v[22:23]
	s_nop 0
	v_pk_mul_f32 v[22:23], v[18:19], v[16:17]
	v_cvt_pk_bf16_f32 v18, v20, v21
	v_lshrrev_b32_e32 v20, 3, v28
	v_and_or_b32 v20, v20, 14, s44
	v_lshlrev_b32_e32 v20, 10, v20
	v_bitop3_b32 v192, v50, v20, v51 bitop3:0xde
	v_cvt_pk_bf16_f32 v16, v24, v25
	v_cvt_pk_bf16_f32 v17, v26, v27
	v_cvt_pk_bf16_f32 v19, v22, v23
	v_lshl_add_u64 v[20:21], v[48:49], 0, v[192:193]
	global_store_dwordx4 v[20:21], v[16:19], off
	s_nop 1
	v_add_f32_e32 v16, v33, v35
	v_fmamk_f32 v16, v16, 0x3a000000, v236
	v_cmp_gt_f32_e32 vcc, s73, v16
	v_mul_f32_e32 v17, 0x4f800000, v16
	s_nop 0
	v_cndmask_b32_e32 v16, v16, v17, vcc
	v_rsq_f32_e32 v17, v16
	s_nop 0
	s_nop 0
	s_nop 0
	s_nop 1
	s_nop 1
	s_mov_b64 s[0:1], -1
	v_mov_b32_e32 v16, v17
	v_pk_mul_f32 v[12:13], v[12:13], v[16:17] op_sel_hi:[1,0]
	s_andn2_b64 vcc, exec, s[4:5]
	v_mul_f32_e32 v17, 0xbfb8aa3b, v12
	v_exp_f32_e32 v17, v17
	s_nop 0
	v_add_f32_e32 v17, 1.0, v17
	v_rcp_f32_e32 v18, v17
	v_mul_f32_e32 v17, 0xbfb8aa3b, v13
	v_exp_f32_e32 v17, v17
	s_nop 0
	v_add_f32_e32 v17, 1.0, v17
	v_rcp_f32_e32 v19, v17
	v_pk_mul_f32 v[8:9], v[8:9], v[16:17] op_sel_hi:[1,0]
	v_pk_mul_f32 v[10:11], v[10:11], v[16:17] op_sel_hi:[1,0]
	v_pk_mul_f32 v[4:5], v[4:5], v[16:17] op_sel_hi:[1,0]
	v_pk_mul_f32 v[12:13], v[12:13], v[18:19]
	v_pk_mul_f32 v[0:1], v[0:1], v[16:17] op_sel_hi:[1,0]
	v_pk_mul_f32 v[8:9], v[8:9], v[12:13]
	v_pk_mul_f32 v[12:13], v[14:15], v[16:17] op_sel_hi:[1,0]
	v_pk_mul_f32 v[2:3], v[2:3], v[16:17] op_sel_hi:[1,0]
	v_mul_f32_e32 v14, 0xbfb8aa3b, v12
	v_mul_f32_e32 v15, 0xbfb8aa3b, v13
	v_exp_f32_e32 v14, v14
	v_exp_f32_e32 v15, v15
	v_add_f32_e32 v14, 1.0, v14
	v_add_f32_e32 v15, 1.0, v15
	v_rcp_f32_e32 v14, v14
	v_rcp_f32_e32 v15, v15
	s_nop 0
	v_pk_mul_f32 v[12:13], v[12:13], v[14:15]
	s_nop 0
	v_pk_mul_f32 v[10:11], v[10:11], v[12:13]
	v_mul_f32_e32 v12, 0xbfb8aa3b, v4
	v_mul_f32_e32 v13, 0xbfb8aa3b, v5
	v_exp_f32_e32 v12, v12
	v_exp_f32_e32 v13, v13
	v_add_f32_e32 v12, 1.0, v12
	v_add_f32_e32 v13, 1.0, v13
	v_rcp_f32_e32 v12, v12
	v_rcp_f32_e32 v13, v13
	s_nop 0
	v_pk_mul_f32 v[4:5], v[4:5], v[12:13]
	s_nop 0
	v_pk_mul_f32 v[4:5], v[0:1], v[4:5]
	v_pk_mul_f32 v[0:1], v[6:7], v[16:17] op_sel_hi:[1,0]
	v_add_u32_e32 v12, 0xb0, v143
	v_mul_f32_e32 v6, 0xbfb8aa3b, v0
	v_mul_f32_e32 v7, 0xbfb8aa3b, v1
	v_exp_f32_e32 v6, v6
	v_exp_f32_e32 v7, v7
	v_add_f32_e32 v6, 1.0, v6
	v_add_f32_e32 v7, 1.0, v7
	v_rcp_f32_e32 v6, v6
	v_rcp_f32_e32 v7, v7
	s_nop 0
	v_pk_mul_f32 v[0:1], v[0:1], v[6:7]
	s_nop 0
	v_pk_mul_f32 v[6:7], v[2:3], v[0:1]
	v_cvt_pk_bf16_f32 v2, v4, v5
	v_lshrrev_b32_e32 v4, 3, v12
	v_and_or_b32 v4, v4, 14, s44
	v_lshlrev_b32_e32 v4, 10, v4
	v_bitop3_b32 v192, v50, v4, v51 bitop3:0xde
	v_cvt_pk_bf16_f32 v0, v8, v9
	v_cvt_pk_bf16_f32 v1, v10, v11
	v_cvt_pk_bf16_f32 v3, v6, v7
	v_lshl_add_u64 v[4:5], v[48:49], 0, v[192:193]
	global_store_dwordx4 v[4:5], v[0:3], off
	s_cbranch_vccnz .LBB0_147
	s_andn2_b64 vcc, exec, s[6:7]
	s_cbranch_vccnz .LBB0_146
	s_barrier
	s_branch .LBB0_146

; #define LAS __attribute__((address_space(3)))
; __device__ __forceinline__ unsigned pk2(float lo, float hi) { f32x2 f = {lo, hi}; bf16x2_t b = __builtin_convertvector(f, bf16x2_t); return __builtin_bit_cast(unsigned, b); }
; __device__ __forceinline__ float row_rstd(const LAS float* RS, int ord, int lrow) {
;     const float ssum = RS[ord * 256 + lrow] + RS[2048 + ord * 256 + lrow];
;     return 1.0f / sqrtf(ssum * (1.0f / D) + 1e-6f);
;     __device__ __forceinline__ void operator()(const AccT& acc, const Unit& u, int wr, int wc, int fr, int fq) const {
;     ...
;         if (!rot) {
; #pragma unroll
;             for (int ai = 0; ai < 2; ++ai)
; #pragma unroll
;                 for (int m = 0; m < 4; ++m) {
;                     const int row = row0 + ai * 128 + m * 16;
;                     const float rstd = row_rstd(RS, u.ord, wr * 64 + fr + ai * 128 + m * 16);
;                     bf16_t* rowp = P + (size_t)row * INW + col0;
; #pragma unroll
;                     for (int bj = 0; bj < 2; ++bj) {
;                         const f32x4 v0 = acc[ai][bj][m][0] * rstd, v1 = acc[ai][bj][m][1] * rstd;
;                         u32x4 w; w.x = pk2(v0[0], v0[1]); w.y = pk2(v0[2], v0[3]); w.z = pk2(v1[0], v1[1]); w.w = pk2(v1[2], v1[3]);
;                         if (isgr) {
;                             const int sp = row & (S - 1), tl = sp & 127;
;                             bf16_t* gb = GRL + ((size_t)(((row >> 12) * 8 + (pn - 28)) * 32 + (sp >> 7))) * 32768
;                                        + (size_t)((((((bj * 4 + wc) * 4 + fq) * 4 + (tl >> 5)) * 2) * 32 + (tl & 31)) * 4);
;                             u32x2 lo2; lo2.x = w.x; lo2.y = w.y; u32x2 hi2; hi2.x = w.z; hi2.y = w.w;
;                             *(u32x2*)gb = lo2; *(u32x2*)(gb + 32 * 4) = hi2;
;                         } else *(u32x4*)(rowp + bj * 128) = w;
;                     }
;                 }
.LBB0_305:
	s_sub_i32 s25, s92, 28
	s_cmp_gt_u32 s25, 7
	s_cselect_b64 s[36:37], -1, 0
	s_lshl_b32 s0, s29, 10
	v_add_u32_e32 v138, s0, v233
	ds_read2st64_b32 v[128:129], v138 offset1:32
	s_waitcnt lgkmcnt(0)
	v_add_f32_e32 v128, v128, v129
	v_fmamk_f32 v128, v128, 0x3a000000, v236
	v_mul_f32_e32 v129, 0x4f800000, v128
	v_cmp_gt_f32_e32 vcc, s73, v128
	s_nop 1
	v_cndmask_b32_e32 v128, v128, v129, vcc
	v_rsq_f32_e32 v129, v128
	s_nop 0
	s_nop 0
	s_nop 1
	s_nop 1
	s_nop 1
	v_mov_b32_e32 v134, v129
	v_mov_b64_e32 v[128:129], s[18:19]
	v_mad_i64_i32 v[128:129], s[0:1], v227, s74, v[128:129]
	v_lshl_add_u64 v[132:133], v[192:193], 1, v[128:129]
	v_pk_mul_f32 v[130:131], v[126:127], v[134:135] op_sel_hi:[1,0]
	v_pk_mul_f32 v[128:129], v[124:125], v[134:135] op_sel_hi:[1,0]
	v_pk_mul_f32 v[136:137], v[122:123], v[134:135] op_sel_hi:[1,0]
	v_pk_mul_f32 v[140:141], v[120:121], v[134:135] op_sel_hi:[1,0]
	v_cvt_pk_bf16_f32 v128, v128, v129
	v_cvt_pk_bf16_f32 v129, v130, v131
	v_cvt_pk_bf16_f32 v130, v140, v141
	v_cvt_pk_bf16_f32 v131, v136, v137
	s_mov_b64 s[0:1], -1
	s_and_b64 vcc, exec, s[36:37]
	s_cbranch_vccz .LBB0_307
	global_store_dwordx4 v[132:133], v[128:131], off
	s_mov_b64 s[0:1], 0

; #define LAS __attribute__((address_space(3)))
; __device__ __forceinline__ unsigned pk2(float lo, float hi) { f32x2 f = {lo, hi}; bf16x2_t b = __builtin_convertvector(f, bf16x2_t); return __builtin_bit_cast(unsigned, b); }
; __device__ __forceinline__ float row_rstd(const LAS float* RS, int ord, int lrow) {
;     const float ssum = RS[ord * 256 + lrow] + RS[2048 + ord * 256 + lrow];
;     return 1.0f / sqrtf(ssum * (1.0f / D) + 1e-6f);
;     __device__ __forceinline__ void operator()(const AccT& acc, const Unit& u, int wr, int wc, int fr, int fq) const {
;     ...
;         if (!rot) {
; #pragma unroll
;             for (int ai = 0; ai < 2; ++ai)
; #pragma unroll
;                 for (int m = 0; m < 4; ++m) {
;                     const int row = row0 + ai * 128 + m * 16;
;                     const float rstd = row_rstd(RS, u.ord, wr * 64 + fr + ai * 128 + m * 16);
;                     bf16_t* rowp = P + (size_t)row * INW + col0;
; #pragma unroll
;                     for (int bj = 0; bj < 2; ++bj) {
;                         const f32x4 v0 = acc[ai][bj][m][0] * rstd, v1 = acc[ai][bj][m][1] * rstd;
;                         u32x4 w; w.x = pk2(v0[0], v0[1]); w.y = pk2(v0[2], v0[3]); w.z = pk2(v1[0], v1[1]); w.w = pk2(v1[2], v1[3]);
;                         if (isgr) {
;                             const int sp = row & (S - 1), tl = sp & 127;
;                             bf16_t* gb = GRL + ((size_t)(((row >> 12) * 8 + (pn - 28)) * 32 + (sp >> 7))) * 32768
;                                        + (size_t)((((((bj * 4 + wc) * 4 + fq) * 4 + (tl >> 5)) * 2) * 32 + (tl & 31)) * 4);
;                             u32x2 lo2; lo2.x = w.x; lo2.y = w.y; u32x2 hi2; hi2.x = w.z; hi2.y = w.w;
;                             *(u32x2*)gb = lo2; *(u32x2*)(gb + 32 * 4) = hi2;
;                         } else *(u32x4*)(rowp + bj * 128) = w;
;                     }
;                 }
.LBB0_313:
	v_add_u32_e32 v140, 64, v138
	ds_read2st64_b32 v[128:129], v140 offset1:32
	s_waitcnt lgkmcnt(0)
	v_add_f32_e32 v128, v128, v129
	v_fmamk_f32 v128, v128, 0x3a000000, v236
	v_mul_f32_e32 v129, 0x4f800000, v128
	v_cmp_gt_f32_e32 vcc, s73, v128
	s_nop 1
	v_cndmask_b32_e32 v128, v128, v129, vcc
	v_rsq_f32_e32 v129, v128
	s_nop 0
	s_nop 0
	s_nop 1
	s_nop 1
	v_or_b32_e32 v131, 16, v227
	s_nop 0
	v_mov_b32_e32 v134, v129
	v_mov_b64_e32 v[128:129], s[18:19]
	v_mad_i64_i32 v[128:129], s[0:1], v131, s74, v[128:129]
	v_lshl_add_u64 v[132:133], v[192:193], 1, v[128:129]
	v_pk_mul_f32 v[130:131], v[110:111], v[134:135] op_sel_hi:[1,0]
	v_pk_mul_f32 v[128:129], v[108:109], v[134:135] op_sel_hi:[1,0]
	v_pk_mul_f32 v[136:137], v[106:107], v[134:135] op_sel_hi:[1,0]
	v_pk_mul_f32 v[142:143], v[104:105], v[134:135] op_sel_hi:[1,0]
	v_cvt_pk_bf16_f32 v128, v128, v129
	v_cvt_pk_bf16_f32 v129, v130, v131
	v_cvt_pk_bf16_f32 v130, v142, v143
	v_cvt_pk_bf16_f32 v131, v136, v137
	s_and_b64 vcc, exec, s[10:11]
	s_mov_b64 s[0:1], -1
	s_cbranch_vccnz .LBB0_315
	s_mov_b64 s[0:1], 0
	global_store_dwordx4 v[132:133], v[128:131], off

; #define LAS __attribute__((address_space(3)))
; __device__ __forceinline__ unsigned pk2(float lo, float hi) { f32x2 f = {lo, hi}; bf16x2_t b = __builtin_convertvector(f, bf16x2_t); return __builtin_bit_cast(unsigned, b); }
; __device__ __forceinline__ float row_rstd(const LAS float* RS, int ord, int lrow) {
;     const float ssum = RS[ord * 256 + lrow] + RS[2048 + ord * 256 + lrow];
;     return 1.0f / sqrtf(ssum * (1.0f / D) + 1e-6f);
;     __device__ __forceinline__ void operator()(const AccT& acc, const Unit& u, int wr, int wc, int fr, int fq) const {
;     ...
;         if (!rot) {
; #pragma unroll
;             for (int ai = 0; ai < 2; ++ai)
; #pragma unroll
;                 for (int m = 0; m < 4; ++m) {
;                     const int row = row0 + ai * 128 + m * 16;
;                     const float rstd = row_rstd(RS, u.ord, wr * 64 + fr + ai * 128 + m * 16);
;                     bf16_t* rowp = P + (size_t)row * INW + col0;
; #pragma unroll
;                     for (int bj = 0; bj < 2; ++bj) {
;                         const f32x4 v0 = acc[ai][bj][m][0] * rstd, v1 = acc[ai][bj][m][1] * rstd;
;                         u32x4 w; w.x = pk2(v0[0], v0[1]); w.y = pk2(v0[2], v0[3]); w.z = pk2(v1[0], v1[1]); w.w = pk2(v1[2], v1[3]);
;                         if (isgr) {
;                             const int sp = row & (S - 1), tl = sp & 127;
;                             bf16_t* gb = GRL + ((size_t)(((row >> 12) * 8 + (pn - 28)) * 32 + (sp >> 7))) * 32768
;                                        + (size_t)((((((bj * 4 + wc) * 4 + fq) * 4 + (tl >> 5)) * 2) * 32 + (tl & 31)) * 4);
;                             u32x2 lo2; lo2.x = w.x; lo2.y = w.y; u32x2 hi2; hi2.x = w.z; hi2.y = w.w;
;                             *(u32x2*)gb = lo2; *(u32x2*)(gb + 32 * 4) = hi2;
;                         } else *(u32x4*)(rowp + bj * 128) = w;
;                     }
;                 }
.LBB0_321:
	v_add_u32_e32 v141, 0x80, v138
	ds_read2st64_b32 v[128:129], v141 offset1:32
	v_or_b32_e32 v135, 32, v227
	s_waitcnt lgkmcnt(0)
	v_add_f32_e32 v128, v128, v129
	v_fmamk_f32 v128, v128, 0x3a000000, v236
	v_mul_f32_e32 v129, 0x4f800000, v128
	v_cmp_gt_f32_e32 vcc, s73, v128
	s_nop 1
	v_cndmask_b32_e32 v128, v128, v129, vcc
	v_rsq_f32_e32 v129, v128
	s_nop 0
	s_nop 0
	s_nop 1
	s_nop 1
	s_nop 1
	v_mov_b32_e32 v134, v129
	v_mov_b64_e32 v[128:129], s[18:19]
	v_mad_i64_i32 v[128:129], s[0:1], v135, s74, v[128:129]
	v_lshl_add_u64 v[132:133], v[192:193], 1, v[128:129]
	v_pk_mul_f32 v[130:131], v[94:95], v[134:135] op_sel_hi:[1,0]
	v_pk_mul_f32 v[128:129], v[92:93], v[134:135] op_sel_hi:[1,0]
	v_pk_mul_f32 v[136:137], v[90:91], v[134:135] op_sel_hi:[1,0]
	v_pk_mul_f32 v[142:143], v[88:89], v[134:135] op_sel_hi:[1,0]
	v_cvt_pk_bf16_f32 v128, v128, v129
	v_cvt_pk_bf16_f32 v129, v130, v131
	v_cvt_pk_bf16_f32 v130, v142, v143
	v_cvt_pk_bf16_f32 v131, v136, v137
	s_and_b64 vcc, exec, s[10:11]
	s_mov_b64 s[0:1], -1
	s_cbranch_vccnz .LBB0_323
	s_mov_b64 s[0:1], 0
	global_store_dwordx4 v[132:133], v[128:131], off

; #define LAS __attribute__((address_space(3)))
; __device__ __forceinline__ unsigned pk2(float lo, float hi) { f32x2 f = {lo, hi}; bf16x2_t b = __builtin_convertvector(f, bf16x2_t); return __builtin_bit_cast(unsigned, b); }
; __device__ __forceinline__ float row_rstd(const LAS float* RS, int ord, int lrow) {
;     const float ssum = RS[ord * 256 + lrow] + RS[2048 + ord * 256 + lrow];
;     return 1.0f / sqrtf(ssum * (1.0f / D) + 1e-6f);
;     __device__ __forceinline__ void operator()(const AccT& acc, const Unit& u, int wr, int wc, int fr, int fq) const {
;     ...
;         if (!rot) {
; #pragma unroll
;             for (int ai = 0; ai < 2; ++ai)
; #pragma unroll
;                 for (int m = 0; m < 4; ++m) {
;                     const int row = row0 + ai * 128 + m * 16;
;                     const float rstd = row_rstd(RS, u.ord, wr * 64 + fr + ai * 128 + m * 16);
;                     bf16_t* rowp = P + (size_t)row * INW + col0;
; #pragma unroll
;                     for (int bj = 0; bj < 2; ++bj) {
;                         const f32x4 v0 = acc[ai][bj][m][0] * rstd, v1 = acc[ai][bj][m][1] * rstd;
;                         u32x4 w; w.x = pk2(v0[0], v0[1]); w.y = pk2(v0[2], v0[3]); w.z = pk2(v1[0], v1[1]); w.w = pk2(v1[2], v1[3]);
;                         if (isgr) {
;                             const int sp = row & (S - 1), tl = sp & 127;
;                             bf16_t* gb = GRL + ((size_t)(((row >> 12) * 8 + (pn - 28)) * 32 + (sp >> 7))) * 32768
;                                        + (size_t)((((((bj * 4 + wc) * 4 + fq) * 4 + (tl >> 5)) * 2) * 32 + (tl & 31)) * 4);
;                             u32x2 lo2; lo2.x = w.x; lo2.y = w.y; u32x2 hi2; hi2.x = w.z; hi2.y = w.w;
;                             *(u32x2*)gb = lo2; *(u32x2*)(gb + 32 * 4) = hi2;
;                         } else *(u32x4*)(rowp + bj * 128) = w;
;                     }
;                 }
.LBB0_329:
	v_add_u32_e32 v142, 0xc0, v138
	ds_read2st64_b32 v[128:129], v142 offset1:32
	v_or_b32_e32 v135, 48, v227
	s_waitcnt lgkmcnt(0)
	v_add_f32_e32 v128, v128, v129
	v_fmamk_f32 v128, v128, 0x3a000000, v236
	v_mul_f32_e32 v129, 0x4f800000, v128
	v_cmp_gt_f32_e32 vcc, s73, v128
	s_nop 1
	v_cndmask_b32_e32 v128, v128, v129, vcc
	v_rsq_f32_e32 v129, v128
	s_nop 0
	s_nop 0
	s_nop 1
	s_nop 1
	s_nop 1
	v_mov_b32_e32 v134, v129
	v_mov_b64_e32 v[128:129], s[18:19]
	v_mad_i64_i32 v[128:129], s[0:1], v135, s74, v[128:129]
	v_lshl_add_u64 v[132:133], v[192:193], 1, v[128:129]
	v_pk_mul_f32 v[130:131], v[78:79], v[134:135] op_sel_hi:[1,0]
	v_pk_mul_f32 v[128:129], v[76:77], v[134:135] op_sel_hi:[1,0]
	v_pk_mul_f32 v[136:137], v[74:75], v[134:135] op_sel_hi:[1,0]
	v_pk_mul_f32 v[144:145], v[72:73], v[134:135] op_sel_hi:[1,0]
	v_cvt_pk_bf16_f32 v128, v128, v129
	v_cvt_pk_bf16_f32 v129, v130, v131
	v_cvt_pk_bf16_f32 v130, v144, v145
	v_cvt_pk_bf16_f32 v131, v136, v137
	s_and_b64 vcc, exec, s[10:11]
	s_mov_b64 s[0:1], -1
	s_cbranch_vccnz .LBB0_331
	s_mov_b64 s[0:1], 0
	global_store_dwordx4 v[132:133], v[128:131], off

; #define LAS __attribute__((address_space(3)))
; __device__ __forceinline__ unsigned pk2(float lo, float hi) { f32x2 f = {lo, hi}; bf16x2_t b = __builtin_convertvector(f, bf16x2_t); return __builtin_bit_cast(unsigned, b); }
; __device__ __forceinline__ float row_rstd(const LAS float* RS, int ord, int lrow) {
;     const float ssum = RS[ord * 256 + lrow] + RS[2048 + ord * 256 + lrow];
;     return 1.0f / sqrtf(ssum * (1.0f / D) + 1e-6f);
;     __device__ __forceinline__ void operator()(const AccT& acc, const Unit& u, int wr, int wc, int fr, int fq) const {
;     ...
;         if (!rot) {
; #pragma unroll
;             for (int ai = 0; ai < 2; ++ai)
; #pragma unroll
;                 for (int m = 0; m < 4; ++m) {
;                     const int row = row0 + ai * 128 + m * 16;
;                     const float rstd = row_rstd(RS, u.ord, wr * 64 + fr + ai * 128 + m * 16);
;                     bf16_t* rowp = P + (size_t)row * INW + col0;
; #pragma unroll
;                     for (int bj = 0; bj < 2; ++bj) {
;                         const f32x4 v0 = acc[ai][bj][m][0] * rstd, v1 = acc[ai][bj][m][1] * rstd;
;                         u32x4 w; w.x = pk2(v0[0], v0[1]); w.y = pk2(v0[2], v0[3]); w.z = pk2(v1[0], v1[1]); w.w = pk2(v1[2], v1[3]);
;                         if (isgr) {
;                             const int sp = row & (S - 1), tl = sp & 127;
;                             bf16_t* gb = GRL + ((size_t)(((row >> 12) * 8 + (pn - 28)) * 32 + (sp >> 7))) * 32768
;                                        + (size_t)((((((bj * 4 + wc) * 4 + fq) * 4 + (tl >> 5)) * 2) * 32 + (tl & 31)) * 4);
;                             u32x2 lo2; lo2.x = w.x; lo2.y = w.y; u32x2 hi2; hi2.x = w.z; hi2.y = w.w;
;                             *(u32x2*)gb = lo2; *(u32x2*)(gb + 32 * 4) = hi2;
;                         } else *(u32x4*)(rowp + bj * 128) = w;
;                     }
;                 }
.LBB0_337:
	ds_read2st64_b32 v[128:129], v138 offset0:2 offset1:34
	v_add_u32_e32 v143, 0x80, v227
	s_waitcnt lgkmcnt(0)
	v_add_f32_e32 v128, v128, v129
	v_fmamk_f32 v128, v128, 0x3a000000, v236
	v_mul_f32_e32 v129, 0x4f800000, v128
	v_cmp_gt_f32_e32 vcc, s73, v128
	s_nop 1
	v_cndmask_b32_e32 v128, v128, v129, vcc
	v_rsq_f32_e32 v129, v128
	s_nop 0
	s_nop 0
	s_nop 1
	s_nop 1
	s_nop 1
	v_mov_b32_e32 v136, v129
	v_mov_b64_e32 v[128:129], s[18:19]
	v_mad_i64_i32 v[128:129], s[0:1], v143, s74, v[128:129]
	v_lshl_add_u64 v[134:135], v[192:193], 1, v[128:129]
	v_pk_mul_f32 v[130:131], v[62:63], v[136:137] op_sel_hi:[1,0]
	v_pk_mul_f32 v[128:129], v[60:61], v[136:137] op_sel_hi:[1,0]
	v_pk_mul_f32 v[132:133], v[58:59], v[136:137] op_sel_hi:[1,0]
	v_pk_mul_f32 v[138:139], v[56:57], v[136:137] op_sel_hi:[1,0]
	v_cvt_pk_bf16_f32 v128, v128, v129
	v_cvt_pk_bf16_f32 v129, v130, v131
	v_cvt_pk_bf16_f32 v130, v138, v139
	v_cvt_pk_bf16_f32 v131, v132, v133
	s_and_b64 vcc, exec, s[10:11]
	s_mov_b64 s[0:1], -1
	s_cbranch_vccnz .LBB0_339
	s_mov_b64 s[0:1], 0
	global_store_dwordx4 v[134:135], v[128:131], off

; #define LAS __attribute__((address_space(3)))
; __device__ __forceinline__ unsigned pk2(float lo, float hi) { f32x2 f = {lo, hi}; bf16x2_t b = __builtin_convertvector(f, bf16x2_t); return __builtin_bit_cast(unsigned, b); }
; __device__ __forceinline__ float row_rstd(const LAS float* RS, int ord, int lrow) {
;     const float ssum = RS[ord * 256 + lrow] + RS[2048 + ord * 256 + lrow];
;     return 1.0f / sqrtf(ssum * (1.0f / D) + 1e-6f);
;     __device__ __forceinline__ void operator()(const AccT& acc, const Unit& u, int wr, int wc, int fr, int fq) const {
;     ...
;         if (!rot) {
; #pragma unroll
;             for (int ai = 0; ai < 2; ++ai)
; #pragma unroll
;                 for (int m = 0; m < 4; ++m) {
;                     const int row = row0 + ai * 128 + m * 16;
;                     const float rstd = row_rstd(RS, u.ord, wr * 64 + fr + ai * 128 + m * 16);
;                     bf16_t* rowp = P + (size_t)row * INW + col0;
; #pragma unroll
;                     for (int bj = 0; bj < 2; ++bj) {
;                         const f32x4 v0 = acc[ai][bj][m][0] * rstd, v1 = acc[ai][bj][m][1] * rstd;
;                         u32x4 w; w.x = pk2(v0[0], v0[1]); w.y = pk2(v0[2], v0[3]); w.z = pk2(v1[0], v1[1]); w.w = pk2(v1[2], v1[3]);
;                         if (isgr) {
;                             const int sp = row & (S - 1), tl = sp & 127;
;                             bf16_t* gb = GRL + ((size_t)(((row >> 12) * 8 + (pn - 28)) * 32 + (sp >> 7))) * 32768
;                                        + (size_t)((((((bj * 4 + wc) * 4 + fq) * 4 + (tl >> 5)) * 2) * 32 + (tl & 31)) * 4);
;                             u32x2 lo2; lo2.x = w.x; lo2.y = w.y; u32x2 hi2; hi2.x = w.z; hi2.y = w.w;
;                             *(u32x2*)gb = lo2; *(u32x2*)(gb + 32 * 4) = hi2;
;                         } else *(u32x4*)(rowp + bj * 128) = w;
;                     }
;                 }
.LBB0_345:
	ds_read2st64_b32 v[128:129], v140 offset0:2 offset1:34
	s_waitcnt lgkmcnt(0)
	v_add_f32_e32 v128, v128, v129
	v_fmamk_f32 v128, v128, 0x3a000000, v236
	v_mul_f32_e32 v129, 0x4f800000, v128
	v_cmp_gt_f32_e32 vcc, s73, v128
	s_nop 1
	v_cndmask_b32_e32 v128, v128, v129, vcc
	v_rsq_f32_e32 v129, v128
	s_nop 0
	s_nop 0
	s_nop 1
	s_nop 1
	v_or_b32_e32 v131, 16, v143
	s_nop 0
	v_mov_b32_e32 v136, v129
	v_mov_b64_e32 v[128:129], s[18:19]
	v_mad_i64_i32 v[128:129], s[0:1], v131, s74, v[128:129]
	v_lshl_add_u64 v[134:135], v[192:193], 1, v[128:129]
	v_pk_mul_f32 v[130:131], v[46:47], v[136:137] op_sel_hi:[1,0]
	v_pk_mul_f32 v[128:129], v[44:45], v[136:137] op_sel_hi:[1,0]
	v_pk_mul_f32 v[138:139], v[42:43], v[136:137] op_sel_hi:[1,0]
	v_pk_mul_f32 v[144:145], v[40:41], v[136:137] op_sel_hi:[1,0]
	v_cvt_pk_bf16_f32 v128, v128, v129
	v_cvt_pk_bf16_f32 v129, v130, v131
	v_cvt_pk_bf16_f32 v130, v144, v145
	v_cvt_pk_bf16_f32 v131, v138, v139
	s_and_b64 vcc, exec, s[10:11]
	s_mov_b64 s[0:1], -1
	s_cbranch_vccnz .LBB0_347
	s_mov_b64 s[0:1], 0
	global_store_dwordx4 v[134:135], v[128:131], off

; #define LAS __attribute__((address_space(3)))
; __device__ __forceinline__ unsigned pk2(float lo, float hi) { f32x2 f = {lo, hi}; bf16x2_t b = __builtin_convertvector(f, bf16x2_t); return __builtin_bit_cast(unsigned, b); }
; __device__ __forceinline__ float row_rstd(const LAS float* RS, int ord, int lrow) {
;     const float ssum = RS[ord * 256 + lrow] + RS[2048 + ord * 256 + lrow];
;     return 1.0f / sqrtf(ssum * (1.0f / D) + 1e-6f);
;     __device__ __forceinline__ void operator()(const AccT& acc, const Unit& u, int wr, int wc, int fr, int fq) const {
;     ...
;         if (!rot) {
; #pragma unroll
;             for (int ai = 0; ai < 2; ++ai)
; #pragma unroll
;                 for (int m = 0; m < 4; ++m) {
;                     const int row = row0 + ai * 128 + m * 16;
;                     const float rstd = row_rstd(RS, u.ord, wr * 64 + fr + ai * 128 + m * 16);
;                     bf16_t* rowp = P + (size_t)row * INW + col0;
; #pragma unroll
;                     for (int bj = 0; bj < 2; ++bj) {
;                         const f32x4 v0 = acc[ai][bj][m][0] * rstd, v1 = acc[ai][bj][m][1] * rstd;
;                         u32x4 w; w.x = pk2(v0[0], v0[1]); w.y = pk2(v0[2], v0[3]); w.z = pk2(v1[0], v1[1]); w.w = pk2(v1[2], v1[3]);
;                         if (isgr) {
;                             const int sp = row & (S - 1), tl = sp & 127;
;                             bf16_t* gb = GRL + ((size_t)(((row >> 12) * 8 + (pn - 28)) * 32 + (sp >> 7))) * 32768
;                                        + (size_t)((((((bj * 4 + wc) * 4 + fq) * 4 + (tl >> 5)) * 2) * 32 + (tl & 31)) * 4);
;                             u32x2 lo2; lo2.x = w.x; lo2.y = w.y; u32x2 hi2; hi2.x = w.z; hi2.y = w.w;
;                             *(u32x2*)gb = lo2; *(u32x2*)(gb + 32 * 4) = hi2;
;                         } else *(u32x4*)(rowp + bj * 128) = w;
;                     }
;                 }
.LBB0_353:
	ds_read2st64_b32 v[128:129], v141 offset0:2 offset1:34
	v_or_b32_e32 v137, 32, v143
	s_waitcnt lgkmcnt(0)
	v_add_f32_e32 v128, v128, v129
	v_fmamk_f32 v128, v128, 0x3a000000, v236
	v_mul_f32_e32 v129, 0x4f800000, v128
	v_cmp_gt_f32_e32 vcc, s73, v128
	s_nop 1
	v_cndmask_b32_e32 v128, v128, v129, vcc
	v_rsq_f32_e32 v129, v128
	s_nop 0
	s_nop 0
	s_nop 1
	s_nop 1
	s_nop 1
	v_mov_b32_e32 v136, v129
	v_mov_b64_e32 v[128:129], s[18:19]
	v_mad_i64_i32 v[128:129], s[0:1], v137, s74, v[128:129]
	v_lshl_add_u64 v[134:135], v[192:193], 1, v[128:129]
	v_pk_mul_f32 v[130:131], v[30:31], v[136:137] op_sel_hi:[1,0]
	v_pk_mul_f32 v[128:129], v[28:29], v[136:137] op_sel_hi:[1,0]
	v_pk_mul_f32 v[138:139], v[26:27], v[136:137] op_sel_hi:[1,0]
	v_pk_mul_f32 v[140:141], v[24:25], v[136:137] op_sel_hi:[1,0]
	v_cvt_pk_bf16_f32 v128, v128, v129
	v_cvt_pk_bf16_f32 v129, v130, v131
	v_cvt_pk_bf16_f32 v130, v140, v141
	v_cvt_pk_bf16_f32 v131, v138, v139
	s_and_b64 vcc, exec, s[10:11]
	s_mov_b64 s[0:1], -1
	s_cbranch_vccnz .LBB0_355
	s_mov_b64 s[0:1], 0
	global_store_dwordx4 v[134:135], v[128:131], off

; #define LAS __attribute__((address_space(3)))
; __device__ __forceinline__ unsigned pk2(float lo, float hi) { f32x2 f = {lo, hi}; bf16x2_t b = __builtin_convertvector(f, bf16x2_t); return __builtin_bit_cast(unsigned, b); }
; __device__ __forceinline__ float row_rstd(const LAS float* RS, int ord, int lrow) {
;     const float ssum = RS[ord * 256 + lrow] + RS[2048 + ord * 256 + lrow];
;     return 1.0f / sqrtf(ssum * (1.0f / D) + 1e-6f);
;     __device__ __forceinline__ void operator()(const AccT& acc, const Unit& u, int wr, int wc, int fr, int fq) const {
;     ...
;         if (!rot) {
; #pragma unroll
;             for (int ai = 0; ai < 2; ++ai)
; #pragma unroll
;                 for (int m = 0; m < 4; ++m) {
;                     const int row = row0 + ai * 128 + m * 16;
;                     const float rstd = row_rstd(RS, u.ord, wr * 64 + fr + ai * 128 + m * 16);
;                     bf16_t* rowp = P + (size_t)row * INW + col0;
; #pragma unroll
;                     for (int bj = 0; bj < 2; ++bj) {
;                         const f32x4 v0 = acc[ai][bj][m][0] * rstd, v1 = acc[ai][bj][m][1] * rstd;
;                         u32x4 w; w.x = pk2(v0[0], v0[1]); w.y = pk2(v0[2], v0[3]); w.z = pk2(v1[0], v1[1]); w.w = pk2(v1[2], v1[3]);
;                         if (isgr) {
;                             const int sp = row & (S - 1), tl = sp & 127;
;                             bf16_t* gb = GRL + ((size_t)(((row >> 12) * 8 + (pn - 28)) * 32 + (sp >> 7))) * 32768
;                                        + (size_t)((((((bj * 4 + wc) * 4 + fq) * 4 + (tl >> 5)) * 2) * 32 + (tl & 31)) * 4);
;                             u32x2 lo2; lo2.x = w.x; lo2.y = w.y; u32x2 hi2; hi2.x = w.z; hi2.y = w.w;
;                             *(u32x2*)gb = lo2; *(u32x2*)(gb + 32 * 4) = hi2;
;                         } else *(u32x4*)(rowp + bj * 128) = w;
;                     }
;                 }
.LBB0_361:
	ds_read2st64_b32 v[128:129], v142 offset0:2 offset1:34
	v_or_b32_e32 v137, 48, v143
	s_waitcnt lgkmcnt(0)
	v_add_f32_e32 v128, v128, v129
	v_fmamk_f32 v128, v128, 0x3a000000, v236
	v_mul_f32_e32 v129, 0x4f800000, v128
	v_cmp_gt_f32_e32 vcc, s73, v128
	s_nop 1
	v_cndmask_b32_e32 v128, v128, v129, vcc
	v_rsq_f32_e32 v129, v128
	s_nop 0
	s_nop 0
	s_nop 1
	s_nop 1
	s_nop 1
	v_mov_b32_e32 v136, v129
	v_mov_b64_e32 v[128:129], s[18:19]
	v_mad_i64_i32 v[128:129], s[0:1], v137, s74, v[128:129]
	v_lshl_add_u64 v[134:135], v[192:193], 1, v[128:129]
	v_pk_mul_f32 v[130:131], v[14:15], v[136:137] op_sel_hi:[1,0]
	v_pk_mul_f32 v[128:129], v[12:13], v[136:137] op_sel_hi:[1,0]
	v_pk_mul_f32 v[138:139], v[10:11], v[136:137] op_sel_hi:[1,0]
	v_pk_mul_f32 v[140:141], v[8:9], v[136:137] op_sel_hi:[1,0]
	v_cvt_pk_bf16_f32 v128, v128, v129
	v_cvt_pk_bf16_f32 v129, v130, v131
	v_cvt_pk_bf16_f32 v130, v140, v141
	v_cvt_pk_bf16_f32 v131, v138, v139
	s_and_b64 vcc, exec, s[10:11]
	s_mov_b64 s[0:1], -1
	s_cbranch_vccnz .LBB0_363
	s_mov_b64 s[0:1], 0
	global_store_dwordx4 v[134:135], v[128:131], off

; #define LAS __attribute__((address_space(3)))
; __device__ __forceinline__ float row_rstd(const LAS float* RS, int ord, int lrow) {
;     const float ssum = RS[ord * 256 + lrow] + RS[2048 + ord * 256 + lrow];
;     return 1.0f / sqrtf(ssum * (1.0f / D) + 1e-6f);
;     __device__ __forceinline__ void operator()(const AccT& acc, const Unit& u, int wr, int wc, int fr, int fq) const {
;     ...
;         const bool kindr = pn >= 12;
;         const float* ctab = rope + (kindr ? 2 : 0) * (4096 * 64);
;         const float* stab = ctab + 4096 * 64;
;         const float sc = (pn >= 16 && pn < 20) ? 0.08838834764831845f : 1.0f;
;         const bool kmean = (pn >= 4 && pn < 8);
;         f32x4 cs[2][2];
; #pragma unroll
;         for (int bj = 0; bj < 2; ++bj)
; #pragma unroll
;             for (int n = 0; n < 2; ++n) cs[bj][n] = (f32x4){0.f, 0.f, 0.f, 0.f};
;         f32x4 cv[2][4], sv[2][4];
; #pragma unroll
;         for (int ai = 0; ai < 2; ++ai)
; #pragma unroll
;             for (int m = 0; m < 4; ++m) {
;                 const int pos = (row0 + ai * 128 + m * 16) & (S - 1);
;                 cv[ai][m] = *(const f32x4*)(ctab + pos * 64 + wc * 16 + fq * 4);
;                 sv[ai][m] = *(const f32x4*)(stab + pos * 64 + wc * 16 + fq * 4);
;             }
;         __builtin_amdgcn_sched_barrier(0);
; #pragma unroll
;         for (int ai = 0; ai < 2; ++ai)
; #pragma unroll
;             for (int m = 0; m < 4; ++m) {
;                 const int row = row0 + ai * 128 + m * 16;
;                 const float rs = sc * row_rstd(RS, u.ord, wr * 64 + fr + ai * 128 + m * 16);
;                 const f32x4 c4 = cv[ai][m] * rs;
;                 const f32x4 s4 = sv[ai][m] * rs;
;                 bf16_t* rowp = P + (size_t)row * INW + col0;
; #pragma unroll
;                 for (int bj = 0; bj < 2; ++bj) {
;                     const f32x4 x1 = acc[ai][bj][m][0], x2 = acc[ai][bj][m][1];
;                     const f32x4 o1 = x1 * c4 - x2 * s4, o2 = x1 * s4 + x2 * c4;
;                     cs[bj][0] += o1; cs[bj][1] += o2;
;                     u32x4 w; w.x = pk2(o1[0], o1[1]); w.y = pk2(o1[2], o1[3]); w.z = pk2(o2[0], o2[1]); w.w = pk2(o2[2], o2[3]);
;                     *(u32x4*)(rowp + bj * 128) = w;
;                 }
;             }
.LBB0_370:
	s_cmp_gt_i32 s92, 11
	s_cselect_b32 s0, 0x200000, 0
	s_add_u32 s0, s45, s0
	s_addc_u32 s1, s52, 0
	s_and_b32 s10, s92, -4
	s_cmp_eq_u32 s10, 16
	s_cselect_b64 vcc, -1, 0
	s_add_u32 s0, s0, s59
	s_addc_u32 s1, s1, 0
	v_mov_b32_e32 v225, v193
	v_lshlrev_b32_e32 v132, 8, v227
	v_lshl_add_u64 v[128:129], s[0:1], 0, v[224:225]
	s_mov_b64 s[0:1], 0x100000
	v_and_b32_e32 v132, 0xfcf00, v132
	v_mov_b32_e32 v133, v193
	v_lshl_add_u64 v[130:131], v[128:129], 0, s[0:1]
	v_lshl_add_u64 v[134:135], v[128:129], 0, v[132:133]
	v_lshl_add_u64 v[136:137], v[130:131], 0, v[132:133]
	global_load_dwordx4 v[188:191], v[134:135], off
	global_load_dwordx4 v[184:187], v[136:137], off
	v_or_b32_e32 v134, 0x1000, v132
	v_mov_b32_e32 v135, v193
	v_lshl_add_u64 v[136:137], v[128:129], 0, v[134:135]
	v_lshl_add_u64 v[134:135], v[130:131], 0, v[134:135]
	global_load_dwordx4 v[180:183], v[136:137], off
	global_load_dwordx4 v[176:179], v[134:135], off
	v_or_b32_e32 v134, 0x2000, v132
	v_mov_b32_e32 v135, v193
	v_lshl_add_u64 v[136:137], v[128:129], 0, v[134:135]
	v_lshl_add_u64 v[134:135], v[130:131], 0, v[134:135]
	v_or_b32_e32 v132, 0x3000, v132
	global_load_dwordx4 v[172:175], v[136:137], off
	global_load_dwordx4 v[168:171], v[134:135], off
	v_lshl_add_u64 v[134:135], v[128:129], 0, v[132:133]
	v_lshl_add_u64 v[132:133], v[130:131], 0, v[132:133]
	global_load_dwordx4 v[164:167], v[134:135], off
	global_load_dwordx4 v[160:163], v[132:133], off
	v_mov_b32_e32 v132, 0x2000
	v_lshl_add_u32 v132, v227, 6, v132
	v_and_b32_e32 v132, 0x3f3c0, v132
	v_lshlrev_b32_e32 v132, 2, v132
	v_mov_b32_e32 v133, v193
	v_lshl_add_u64 v[134:135], v[128:129], 0, v[132:133]
	v_lshl_add_u64 v[136:137], v[130:131], 0, v[132:133]
	global_load_dwordx4 v[156:159], v[134:135], off
	global_load_dwordx4 v[152:155], v[136:137], off
	v_or_b32_e32 v134, 0x1000, v132
	v_mov_b32_e32 v135, v193
	v_lshl_add_u64 v[136:137], v[128:129], 0, v[134:135]
	v_lshl_add_u64 v[134:135], v[130:131], 0, v[134:135]
	global_load_dwordx4 v[148:151], v[136:137], off
	global_load_dwordx4 v[144:147], v[134:135], off
	v_or_b32_e32 v134, 0x2000, v132
	v_mov_b32_e32 v135, v193
	v_or_b32_e32 v132, 0x3000, v132
	v_lshl_add_u64 v[136:137], v[128:129], 0, v[134:135]
	v_lshl_add_u64 v[134:135], v[130:131], 0, v[134:135]
	v_lshl_add_u64 v[128:129], v[128:129], 0, v[132:133]
	v_lshl_add_u64 v[130:131], v[130:131], 0, v[132:133]
	global_load_dwordx4 v[140:143], v[136:137], off
	s_nop 0
	global_load_dwordx4 v[136:139], v[134:135], off
	s_nop 0
	global_load_dwordx4 v[132:135], v[128:129], off
	s_nop 0
	global_load_dwordx4 v[128:131], v[130:131], off
	v_mov_b32_e32 v194, 0x3db504f3
	v_cndmask_b32_e32 v225, 1.0, v194, vcc
	v_lshl_add_u32 v244, s29, 10, v233
	v_add_u32_e32 v245, 0x2000, v244
	ds_read2_b32 v[194:195], v244 offset1:16
	ds_read2_b32 v[196:197], v245 offset1:16
	s_cmp_lg_u32 s10, 4
	s_waitcnt lgkmcnt(0)
	v_add_f32_e32 v194, v194, v196
	v_fmamk_f32 v194, v194, 0x3a000000, v236
	v_mul_f32_e32 v196, 0x4f800000, v194
	v_cmp_gt_f32_e32 vcc, s73, v194
	s_nop 1
	v_cndmask_b32_e32 v194, v194, v196, vcc
	v_rsq_f32_e32 v196, v194
	s_nop 0
	s_nop 0
	v_mov_b32_e32 v202, v192
	s_nop 0
	v_ashrrev_i32_e32 v203, 31, v192
	s_nop 0
	s_nop 1
	s_nop 0
	v_mov_b32_e32 v192, v196
	v_mul_f32_e32 v192, v225, v192
	s_waitcnt vmcnt(0)
	v_pk_mul_f32 v[246:247], v[188:189], v[192:193] op_sel_hi:[1,0]
	v_mov_b64_e32 v[188:189], s[18:19]
	v_pk_mul_f32 v[248:249], v[190:191], v[192:193] op_sel_hi:[1,0]
	v_pk_mul_f32 v[250:251], v[186:187], v[192:193] op_sel_hi:[1,0]
	v_pk_mul_f32 v[252:253], v[184:185], v[192:193] op_sel_hi:[1,0]
	v_mad_i64_i32 v[184:185], s[0:1], v227, s74, v[188:189]
	v_lshlrev_b64 v[190:191], 1, v[202:203]
	v_lshl_add_u64 v[202:203], v[184:185], 0, v[190:191]
	v_pk_mul_f32 v[186:187], v[120:121], v[252:253]
	v_pk_mul_f32 v[184:185], v[122:123], v[250:251]
	v_pk_mul_f32 v[198:199], v[120:121], v[246:247]
	v_pk_mul_f32 v[120:121], v[122:123], v[248:249]
	v_pk_fma_f32 v[184:185], v[126:127], v[248:249], v[184:185] neg_lo:[0,0,1] neg_hi:[0,0,1]
	v_pk_fma_f32 v[186:187], v[124:125], v[246:247], v[186:187] neg_lo:[0,0,1] neg_hi:[0,0,1]
	v_pk_fma_f32 v[120:121], v[126:127], v[250:251], v[120:121]
	v_pk_fma_f32 v[122:123], v[124:125], v[252:253], v[198:199]
	v_cvt_pk_bf16_f32 v124, v186, v187
	v_cvt_pk_bf16_f32 v125, v184, v185
	v_cvt_pk_bf16_f32 v126, v122, v123
	v_cvt_pk_bf16_f32 v127, v120, v121
	global_store_dwordx4 v[202:203], v[124:127], off
	s_nop 1
	v_pk_mul_f32 v[126:127], v[112:113], v[252:253]
	v_pk_mul_f32 v[112:113], v[112:113], v[246:247]
	v_pk_fma_f32 v[126:127], v[116:117], v[246:247], v[126:127] neg_lo:[0,0,1] neg_hi:[0,0,1]
	v_pk_fma_f32 v[116:117], v[116:117], v[252:253], v[112:113]
	v_add_f32_e32 v112, v195, v197
	v_fmamk_f32 v112, v112, 0x3a000000, v236
	v_pk_mul_f32 v[124:125], v[114:115], v[250:251]
	v_pk_mul_f32 v[114:115], v[114:115], v[248:249]
	v_mul_f32_e32 v113, 0x4f800000, v112
	v_cmp_gt_f32_e32 vcc, s73, v112
	v_pk_fma_f32 v[124:125], v[118:119], v[248:249], v[124:125] neg_lo:[0,0,1] neg_hi:[0,0,1]
	v_pk_fma_f32 v[118:119], v[118:119], v[250:251], v[114:115]
	v_cndmask_b32_e32 v115, v112, v113, vcc
	v_rsq_f32_e32 v192, v115
	s_nop 0
	v_cvt_pk_bf16_f32 v112, v126, v127
	v_cvt_pk_bf16_f32 v113, v124, v125
	v_cvt_pk_bf16_f32 v114, v116, v117
	s_nop 0
	s_nop 1
	s_nop 1
	v_cvt_pk_bf16_f32 v115, v118, v119
	global_store_dwordx4 v[202:203], v[112:115], off offset:256
	s_nop 1
	v_mov_b32_e32 v112, v192
	v_or_b32_e32 v113, 16, v227
	v_mul_f32_e32 v112, v225, v112
	v_pk_mul_f32 v[180:181], v[180:181], v[112:113] op_sel_hi:[1,0]
	v_pk_mul_f32 v[182:183], v[182:183], v[112:113] op_sel_hi:[1,0]
	v_pk_mul_f32 v[178:179], v[178:179], v[112:113] op_sel_hi:[1,0]
	v_pk_mul_f32 v[176:177], v[176:177], v[112:113] op_sel_hi:[1,0]
	v_mad_i64_i32 v[112:113], s[0:1], v113, s74, v[188:189]
	v_lshl_add_u64 v[194:195], v[112:113], 0, v[190:191]
	v_pk_mul_f32 v[114:115], v[104:105], v[176:177]
	v_pk_mul_f32 v[112:113], v[106:107], v[178:179]
	v_pk_mul_f32 v[196:197], v[104:105], v[180:181]
	v_pk_mul_f32 v[104:105], v[106:107], v[182:183]
	v_pk_fma_f32 v[112:113], v[110:111], v[182:183], v[112:113] neg_lo:[0,0,1] neg_hi:[0,0,1]
	v_pk_fma_f32 v[114:115], v[108:109], v[180:181], v[114:115] neg_lo:[0,0,1] neg_hi:[0,0,1]
	v_pk_fma_f32 v[104:105], v[110:111], v[178:179], v[104:105]
	v_pk_fma_f32 v[106:107], v[108:109], v[176:177], v[196:197]
	v_cvt_pk_bf16_f32 v108, v114, v115
	v_cvt_pk_bf16_f32 v109, v112, v113
	v_cvt_pk_bf16_f32 v110, v106, v107
	v_cvt_pk_bf16_f32 v111, v104, v105
	global_store_dwordx4 v[194:195], v[108:111], off
	ds_read2_b32 v[196:197], v244 offset0:32 offset1:48
	ds_read2_b32 v[198:199], v245 offset0:32 offset1:48
	v_pk_mul_f32 v[110:111], v[96:97], v[176:177]
	v_pk_mul_f32 v[96:97], v[96:97], v[180:181]
	v_pk_fma_f32 v[110:111], v[100:101], v[180:181], v[110:111] neg_lo:[0,0,1] neg_hi:[0,0,1]
	v_pk_fma_f32 v[100:101], v[100:101], v[176:177], v[96:97]
	s_waitcnt lgkmcnt(0)
; #define LAS __attribute__((address_space(3)))
; __device__ __forceinline__ float row_rstd(const LAS float* RS, int ord, int lrow) {
;     const float ssum = RS[ord * 256 + lrow] + RS[2048 + ord * 256 + lrow];
;     return 1.0f / sqrtf(ssum * (1.0f / D) + 1e-6f);
;     __device__ __forceinline__ void operator()(const AccT& acc, const Unit& u, int wr, int wc, int fr, int fq) const {
;     ...
;         const bool kindr = pn >= 12;
;         const float* ctab = rope + (kindr ? 2 : 0) * (4096 * 64);
;         const float* stab = ctab + 4096 * 64;
;         const float sc = (pn >= 16 && pn < 20) ? 0.08838834764831845f : 1.0f;
;         const bool kmean = (pn >= 4 && pn < 8);
;         f32x4 cs[2][2];
; #pragma unroll
;         for (int bj = 0; bj < 2; ++bj)
; #pragma unroll
;             for (int n = 0; n < 2; ++n) cs[bj][n] = (f32x4){0.f, 0.f, 0.f, 0.f};
;         f32x4 cv[2][4], sv[2][4];
; #pragma unroll
;         for (int ai = 0; ai < 2; ++ai)
; #pragma unroll
;             for (int m = 0; m < 4; ++m) {
;                 const int pos = (row0 + ai * 128 + m * 16) & (S - 1);
;                 cv[ai][m] = *(const f32x4*)(ctab + pos * 64 + wc * 16 + fq * 4);
;                 sv[ai][m] = *(const f32x4*)(stab + pos * 64 + wc * 16 + fq * 4);
;             }
;         __builtin_amdgcn_sched_barrier(0);
; #pragma unroll
;         for (int ai = 0; ai < 2; ++ai)
; #pragma unroll
;             for (int m = 0; m < 4; ++m) {
;                 const int row = row0 + ai * 128 + m * 16;
;                 const float rs = sc * row_rstd(RS, u.ord, wr * 64 + fr + ai * 128 + m * 16);
;                 const f32x4 c4 = cv[ai][m] * rs;
;                 const f32x4 s4 = sv[ai][m] * rs;
;                 bf16_t* rowp = P + (size_t)row * INW + col0;
; #pragma unroll
;                 for (int bj = 0; bj < 2; ++bj) {
;                     const f32x4 x1 = acc[ai][bj][m][0], x2 = acc[ai][bj][m][1];
;                     const f32x4 o1 = x1 * c4 - x2 * s4, o2 = x1 * s4 + x2 * c4;
;                     cs[bj][0] += o1; cs[bj][1] += o2;
;                     u32x4 w; w.x = pk2(o1[0], o1[1]); w.y = pk2(o1[2], o1[3]); w.z = pk2(o2[0], o2[1]); w.w = pk2(o2[2], o2[3]);
;                     *(u32x4*)(rowp + bj * 128) = w;
;                 }
;             }
	v_add_f32_e32 v96, v196, v198
	v_fmamk_f32 v96, v96, 0x3a000000, v236
	v_pk_mul_f32 v[108:109], v[98:99], v[178:179]
	v_pk_mul_f32 v[98:99], v[98:99], v[182:183]
	v_mul_f32_e32 v97, 0x4f800000, v96
	v_cmp_gt_f32_e32 vcc, s73, v96
	v_pk_fma_f32 v[108:109], v[102:103], v[182:183], v[108:109] neg_lo:[0,0,1] neg_hi:[0,0,1]
	v_pk_fma_f32 v[102:103], v[102:103], v[178:179], v[98:99]
	v_cndmask_b32_e32 v99, v96, v97, vcc
	v_rsq_f32_e32 v176, v99
	s_nop 0
	v_cvt_pk_bf16_f32 v96, v110, v111
	v_cvt_pk_bf16_f32 v97, v108, v109
	v_cvt_pk_bf16_f32 v98, v100, v101
	s_nop 0
	s_nop 1
	s_nop 1
	v_cvt_pk_bf16_f32 v99, v102, v103
	global_store_dwordx4 v[194:195], v[96:99], off offset:256
	s_nop 1
	v_mov_b32_e32 v96, v176
	v_or_b32_e32 v97, 32, v227
	v_mul_f32_e32 v96, v225, v96
	v_pk_mul_f32 v[172:173], v[172:173], v[96:97] op_sel_hi:[1,0]
	v_pk_mul_f32 v[174:175], v[174:175], v[96:97] op_sel_hi:[1,0]
	v_pk_mul_f32 v[170:171], v[170:171], v[96:97] op_sel_hi:[1,0]
	v_pk_mul_f32 v[168:169], v[168:169], v[96:97] op_sel_hi:[1,0]
	v_mad_i64_i32 v[96:97], s[0:1], v97, s74, v[188:189]
	v_lshl_add_u64 v[176:177], v[96:97], 0, v[190:191]
	v_pk_mul_f32 v[98:99], v[88:89], v[168:169]
	v_pk_mul_f32 v[96:97], v[90:91], v[170:171]
	v_pk_mul_f32 v[178:179], v[88:89], v[172:173]
	v_pk_mul_f32 v[88:89], v[90:91], v[174:175]
	v_pk_fma_f32 v[96:97], v[94:95], v[174:175], v[96:97] neg_lo:[0,0,1] neg_hi:[0,0,1]
	v_pk_fma_f32 v[98:99], v[92:93], v[172:173], v[98:99] neg_lo:[0,0,1] neg_hi:[0,0,1]
	v_pk_fma_f32 v[88:89], v[94:95], v[170:171], v[88:89]
	v_pk_fma_f32 v[90:91], v[92:93], v[168:169], v[178:179]
	v_cvt_pk_bf16_f32 v92, v98, v99
	v_cvt_pk_bf16_f32 v93, v96, v97
	v_cvt_pk_bf16_f32 v94, v90, v91
	v_cvt_pk_bf16_f32 v95, v88, v89
	global_store_dwordx4 v[176:177], v[92:95], off
	s_nop 1
	v_pk_mul_f32 v[94:95], v[80:81], v[168:169]
	v_pk_mul_f32 v[80:81], v[80:81], v[172:173]
	v_pk_fma_f32 v[94:95], v[84:85], v[172:173], v[94:95] neg_lo:[0,0,1] neg_hi:[0,0,1]
	v_pk_fma_f32 v[84:85], v[84:85], v[168:169], v[80:81]
	v_add_f32_e32 v80, v197, v199
	v_fmamk_f32 v80, v80, 0x3a000000, v236
	v_pk_mul_f32 v[92:93], v[82:83], v[170:171]
	v_pk_mul_f32 v[82:83], v[82:83], v[174:175]
	v_mul_f32_e32 v81, 0x4f800000, v80
	v_cmp_gt_f32_e32 vcc, s73, v80
	v_pk_fma_f32 v[92:93], v[86:87], v[174:175], v[92:93] neg_lo:[0,0,1] neg_hi:[0,0,1]
	v_pk_fma_f32 v[86:87], v[86:87], v[170:171], v[82:83]
	v_cndmask_b32_e32 v83, v80, v81, vcc
	v_rsq_f32_e32 v168, v83
	s_nop 0
	v_cvt_pk_bf16_f32 v80, v94, v95
	v_cvt_pk_bf16_f32 v81, v92, v93
	v_cvt_pk_bf16_f32 v82, v84, v85
	s_nop 0
	s_nop 1
	s_nop 1
	v_cvt_pk_bf16_f32 v83, v86, v87
	global_store_dwordx4 v[176:177], v[80:83], off offset:256
	s_nop 1
	v_mov_b32_e32 v80, v168
	v_or_b32_e32 v81, 48, v227
	v_mul_f32_e32 v80, v225, v80
	v_pk_mul_f32 v[164:165], v[164:165], v[80:81] op_sel_hi:[1,0]
	v_pk_mul_f32 v[166:167], v[166:167], v[80:81] op_sel_hi:[1,0]
	v_pk_mul_f32 v[162:163], v[162:163], v[80:81] op_sel_hi:[1,0]
	v_pk_mul_f32 v[160:161], v[160:161], v[80:81] op_sel_hi:[1,0]
	v_mad_i64_i32 v[80:81], s[0:1], v81, s74, v[188:189]
	v_lshl_add_u64 v[168:169], v[80:81], 0, v[190:191]
	v_pk_mul_f32 v[82:83], v[72:73], v[160:161]
	v_pk_mul_f32 v[80:81], v[74:75], v[162:163]
	v_pk_mul_f32 v[170:171], v[72:73], v[164:165]
	v_pk_mul_f32 v[72:73], v[74:75], v[166:167]
	v_pk_fma_f32 v[80:81], v[78:79], v[166:167], v[80:81] neg_lo:[0,0,1] neg_hi:[0,0,1]
	v_pk_fma_f32 v[82:83], v[76:77], v[164:165], v[82:83] neg_lo:[0,0,1] neg_hi:[0,0,1]
	v_pk_fma_f32 v[72:73], v[78:79], v[162:163], v[72:73]
	v_pk_fma_f32 v[74:75], v[76:77], v[160:161], v[170:171]
	v_cvt_pk_bf16_f32 v76, v82, v83
	v_cvt_pk_bf16_f32 v77, v80, v81
	v_cvt_pk_bf16_f32 v78, v74, v75
	v_cvt_pk_bf16_f32 v79, v72, v73
	global_store_dwordx4 v[168:169], v[76:79], off
	ds_read2_b32 v[170:171], v244 offset0:128 offset1:144
	ds_read2_b32 v[172:173], v245 offset0:128 offset1:144
	v_pk_mul_f32 v[78:79], v[64:65], v[160:161]
	v_pk_mul_f32 v[64:65], v[64:65], v[164:165]
	v_pk_fma_f32 v[78:79], v[68:69], v[164:165], v[78:79] neg_lo:[0,0,1] neg_hi:[0,0,1]
	v_pk_fma_f32 v[68:69], v[68:69], v[160:161], v[64:65]
	s_waitcnt lgkmcnt(0)
	v_add_f32_e32 v64, v170, v172
	v_fmamk_f32 v64, v64, 0x3a000000, v236
	v_pk_mul_f32 v[76:77], v[66:67], v[162:163]
	v_pk_mul_f32 v[66:67], v[66:67], v[166:167]
	v_mul_f32_e32 v65, 0x4f800000, v64
	v_cmp_gt_f32_e32 vcc, s73, v64
	v_pk_fma_f32 v[76:77], v[70:71], v[166:167], v[76:77] neg_lo:[0,0,1] neg_hi:[0,0,1]
	v_pk_fma_f32 v[70:71], v[70:71], v[162:163], v[66:67]
	v_cndmask_b32_e32 v67, v64, v65, vcc
	v_rsq_f32_e32 v160, v67
	s_nop 0
	v_cvt_pk_bf16_f32 v64, v78, v79
	v_cvt_pk_bf16_f32 v65, v76, v77
	v_cvt_pk_bf16_f32 v66, v68, v69
	s_nop 0
	s_nop 1
	s_nop 1
	v_cvt_pk_bf16_f32 v67, v70, v71
	global_store_dwordx4 v[168:169], v[64:67], off offset:256
	s_nop 1
	v_mov_b32_e32 v64, v160
	v_add_u32_e32 v65, 0x80, v227
	v_mul_f32_e32 v64, v225, v64
	v_pk_mul_f32 v[156:157], v[156:157], v[64:65] op_sel_hi:[1,0]
	v_pk_mul_f32 v[158:159], v[158:159], v[64:65] op_sel_hi:[1,0]
	v_pk_mul_f32 v[154:155], v[154:155], v[64:65] op_sel_hi:[1,0]
	v_pk_mul_f32 v[152:153], v[152:153], v[64:65] op_sel_hi:[1,0]
	v_mad_i64_i32 v[64:65], s[0:1], v65, s74, v[188:189]
	v_lshl_add_u64 v[160:161], v[64:65], 0, v[190:191]
	v_pk_mul_f32 v[66:67], v[56:57], v[152:153]
	v_pk_mul_f32 v[64:65], v[58:59], v[154:155]
	v_pk_mul_f32 v[162:163], v[56:57], v[156:157]
	v_pk_mul_f32 v[56:57], v[58:59], v[158:159]
	v_pk_fma_f32 v[64:65], v[62:63], v[158:159], v[64:65] neg_lo:[0,0,1] neg_hi:[0,0,1]
	v_pk_fma_f32 v[66:67], v[60:61], v[156:157], v[66:67] neg_lo:[0,0,1] neg_hi:[0,0,1]
	v_pk_fma_f32 v[56:57], v[62:63], v[154:155], v[56:57]
; #define LAS __attribute__((address_space(3)))
; __device__ __forceinline__ float row_rstd(const LAS float* RS, int ord, int lrow) {
;     const float ssum = RS[ord * 256 + lrow] + RS[2048 + ord * 256 + lrow];
;     return 1.0f / sqrtf(ssum * (1.0f / D) + 1e-6f);
;     __device__ __forceinline__ void operator()(const AccT& acc, const Unit& u, int wr, int wc, int fr, int fq) const {
;     ...
;         const bool kindr = pn >= 12;
;         const float* ctab = rope + (kindr ? 2 : 0) * (4096 * 64);
;         const float* stab = ctab + 4096 * 64;
;         const float sc = (pn >= 16 && pn < 20) ? 0.08838834764831845f : 1.0f;
;         const bool kmean = (pn >= 4 && pn < 8);
;         f32x4 cs[2][2];
; #pragma unroll
;         for (int bj = 0; bj < 2; ++bj)
; #pragma unroll
;             for (int n = 0; n < 2; ++n) cs[bj][n] = (f32x4){0.f, 0.f, 0.f, 0.f};
;         f32x4 cv[2][4], sv[2][4];
; #pragma unroll
;         for (int ai = 0; ai < 2; ++ai)
; #pragma unroll
;             for (int m = 0; m < 4; ++m) {
;                 const int pos = (row0 + ai * 128 + m * 16) & (S - 1);
;                 cv[ai][m] = *(const f32x4*)(ctab + pos * 64 + wc * 16 + fq * 4);
;                 sv[ai][m] = *(const f32x4*)(stab + pos * 64 + wc * 16 + fq * 4);
;             }
;         __builtin_amdgcn_sched_barrier(0);
; #pragma unroll
;         for (int ai = 0; ai < 2; ++ai)
; #pragma unroll
;             for (int m = 0; m < 4; ++m) {
;                 const int row = row0 + ai * 128 + m * 16;
;                 const float rs = sc * row_rstd(RS, u.ord, wr * 64 + fr + ai * 128 + m * 16);
;                 const f32x4 c4 = cv[ai][m] * rs;
;                 const f32x4 s4 = sv[ai][m] * rs;
;                 bf16_t* rowp = P + (size_t)row * INW + col0;
; #pragma unroll
;                 for (int bj = 0; bj < 2; ++bj) {
;                     const f32x4 x1 = acc[ai][bj][m][0], x2 = acc[ai][bj][m][1];
;                     const f32x4 o1 = x1 * c4 - x2 * s4, o2 = x1 * s4 + x2 * c4;
;                     cs[bj][0] += o1; cs[bj][1] += o2;
;                     u32x4 w; w.x = pk2(o1[0], o1[1]); w.y = pk2(o1[2], o1[3]); w.z = pk2(o2[0], o2[1]); w.w = pk2(o2[2], o2[3]);
;                     *(u32x4*)(rowp + bj * 128) = w;
;                 }
;             }
;         if (kmean) {
	v_pk_fma_f32 v[58:59], v[60:61], v[152:153], v[162:163]
	v_cvt_pk_bf16_f32 v60, v66, v67
	v_cvt_pk_bf16_f32 v61, v64, v65
	v_cvt_pk_bf16_f32 v62, v58, v59
	v_cvt_pk_bf16_f32 v63, v56, v57
	global_store_dwordx4 v[160:161], v[60:63], off
	s_nop 1
	v_pk_mul_f32 v[62:63], v[48:49], v[152:153]
	v_pk_mul_f32 v[48:49], v[48:49], v[156:157]
	v_pk_fma_f32 v[62:63], v[52:53], v[156:157], v[62:63] neg_lo:[0,0,1] neg_hi:[0,0,1]
	v_pk_fma_f32 v[52:53], v[52:53], v[152:153], v[48:49]
	v_add_f32_e32 v48, v171, v173
	v_fmamk_f32 v48, v48, 0x3a000000, v236
	v_pk_mul_f32 v[60:61], v[50:51], v[154:155]
	v_pk_mul_f32 v[50:51], v[50:51], v[158:159]
	v_mul_f32_e32 v49, 0x4f800000, v48
	v_cmp_gt_f32_e32 vcc, s73, v48
	v_pk_fma_f32 v[60:61], v[54:55], v[158:159], v[60:61] neg_lo:[0,0,1] neg_hi:[0,0,1]
	v_pk_fma_f32 v[54:55], v[54:55], v[154:155], v[50:51]
	v_cndmask_b32_e32 v51, v48, v49, vcc
	v_rsq_f32_e32 v152, v51
	s_nop 0
	v_cvt_pk_bf16_f32 v48, v62, v63
	v_cvt_pk_bf16_f32 v49, v60, v61
	v_cvt_pk_bf16_f32 v50, v52, v53
	s_nop 0
	s_nop 1
	s_nop 1
	v_cvt_pk_bf16_f32 v51, v54, v55
	global_store_dwordx4 v[160:161], v[48:51], off offset:256
	s_nop 1
	v_mov_b32_e32 v48, v152
	v_add_u32_e32 v49, 0x90, v227
	v_mul_f32_e32 v48, v225, v48
	v_pk_mul_f32 v[148:149], v[148:149], v[48:49] op_sel_hi:[1,0]
	v_pk_mul_f32 v[150:151], v[150:151], v[48:49] op_sel_hi:[1,0]
	v_pk_mul_f32 v[146:147], v[146:147], v[48:49] op_sel_hi:[1,0]
	v_pk_mul_f32 v[144:145], v[144:145], v[48:49] op_sel_hi:[1,0]
	v_mad_i64_i32 v[48:49], s[0:1], v49, s74, v[188:189]
	v_lshl_add_u64 v[152:153], v[48:49], 0, v[190:191]
	v_pk_mul_f32 v[50:51], v[40:41], v[144:145]
	v_pk_mul_f32 v[48:49], v[42:43], v[146:147]
	v_pk_mul_f32 v[154:155], v[40:41], v[148:149]
	v_pk_mul_f32 v[40:41], v[42:43], v[150:151]
	v_pk_fma_f32 v[48:49], v[46:47], v[150:151], v[48:49] neg_lo:[0,0,1] neg_hi:[0,0,1]
	v_pk_fma_f32 v[50:51], v[44:45], v[148:149], v[50:51] neg_lo:[0,0,1] neg_hi:[0,0,1]
	v_pk_fma_f32 v[40:41], v[46:47], v[146:147], v[40:41]
	v_pk_fma_f32 v[42:43], v[44:45], v[144:145], v[154:155]
	v_cvt_pk_bf16_f32 v44, v50, v51
	v_cvt_pk_bf16_f32 v45, v48, v49
	v_cvt_pk_bf16_f32 v46, v42, v43
	v_cvt_pk_bf16_f32 v47, v40, v41
	global_store_dwordx4 v[152:153], v[44:47], off
	ds_read2_b32 v[154:155], v244 offset0:160 offset1:176
	ds_read2_b32 v[156:157], v245 offset0:160 offset1:176
	v_pk_mul_f32 v[46:47], v[32:33], v[144:145]
	v_pk_mul_f32 v[32:33], v[32:33], v[148:149]
	v_pk_fma_f32 v[46:47], v[36:37], v[148:149], v[46:47] neg_lo:[0,0,1] neg_hi:[0,0,1]
	v_pk_fma_f32 v[36:37], v[36:37], v[144:145], v[32:33]
	s_waitcnt lgkmcnt(0)
	v_add_f32_e32 v32, v154, v156
	v_fmamk_f32 v32, v32, 0x3a000000, v236
	v_pk_mul_f32 v[44:45], v[34:35], v[146:147]
	v_pk_mul_f32 v[34:35], v[34:35], v[150:151]
	v_mul_f32_e32 v33, 0x4f800000, v32
	v_cmp_gt_f32_e32 vcc, s73, v32
	v_pk_fma_f32 v[44:45], v[38:39], v[150:151], v[44:45] neg_lo:[0,0,1] neg_hi:[0,0,1]
	v_pk_fma_f32 v[38:39], v[38:39], v[146:147], v[34:35]
	v_cndmask_b32_e32 v35, v32, v33, vcc
	v_rsq_f32_e32 v144, v35
	s_nop 0
	v_cvt_pk_bf16_f32 v32, v46, v47
	v_cvt_pk_bf16_f32 v33, v44, v45
	v_cvt_pk_bf16_f32 v34, v36, v37
	s_nop 0
	s_nop 1
	s_nop 1
	v_cvt_pk_bf16_f32 v35, v38, v39
	global_store_dwordx4 v[152:153], v[32:35], off offset:256
	s_nop 1
	v_mov_b32_e32 v32, v144
	v_add_u32_e32 v33, 0xa0, v227
	v_mul_f32_e32 v32, v225, v32
	v_pk_mul_f32 v[140:141], v[140:141], v[32:33] op_sel_hi:[1,0]
	v_pk_mul_f32 v[142:143], v[142:143], v[32:33] op_sel_hi:[1,0]
	v_pk_mul_f32 v[138:139], v[138:139], v[32:33] op_sel_hi:[1,0]
	v_pk_mul_f32 v[136:137], v[136:137], v[32:33] op_sel_hi:[1,0]
	v_mad_i64_i32 v[32:33], s[0:1], v33, s74, v[188:189]
	v_lshl_add_u64 v[144:145], v[32:33], 0, v[190:191]
	v_pk_mul_f32 v[34:35], v[24:25], v[136:137]
	v_pk_mul_f32 v[32:33], v[26:27], v[138:139]
	v_pk_mul_f32 v[146:147], v[24:25], v[140:141]
	v_pk_mul_f32 v[24:25], v[26:27], v[142:143]
	v_pk_fma_f32 v[32:33], v[30:31], v[142:143], v[32:33] neg_lo:[0,0,1] neg_hi:[0,0,1]
	v_pk_fma_f32 v[34:35], v[28:29], v[140:141], v[34:35] neg_lo:[0,0,1] neg_hi:[0,0,1]
	v_pk_fma_f32 v[24:25], v[30:31], v[138:139], v[24:25]
	v_pk_fma_f32 v[26:27], v[28:29], v[136:137], v[146:147]
	v_cvt_pk_bf16_f32 v28, v34, v35
	v_cvt_pk_bf16_f32 v29, v32, v33
	v_cvt_pk_bf16_f32 v30, v26, v27
	v_cvt_pk_bf16_f32 v31, v24, v25
	global_store_dwordx4 v[144:145], v[28:31], off
	s_nop 1
	v_pk_mul_f32 v[30:31], v[16:17], v[136:137]
	v_pk_mul_f32 v[16:17], v[16:17], v[140:141]
	v_pk_fma_f32 v[30:31], v[20:21], v[140:141], v[30:31] neg_lo:[0,0,1] neg_hi:[0,0,1]
	v_pk_fma_f32 v[20:21], v[20:21], v[136:137], v[16:17]
	v_add_f32_e32 v16, v155, v157
	v_fmamk_f32 v16, v16, 0x3a000000, v236
	v_pk_mul_f32 v[28:29], v[18:19], v[138:139]
	v_pk_mul_f32 v[18:19], v[18:19], v[142:143]
	v_mul_f32_e32 v17, 0x4f800000, v16
	v_cmp_gt_f32_e32 vcc, s73, v16
	v_pk_fma_f32 v[28:29], v[22:23], v[142:143], v[28:29] neg_lo:[0,0,1] neg_hi:[0,0,1]
	v_pk_fma_f32 v[22:23], v[22:23], v[138:139], v[18:19]
	v_cndmask_b32_e32 v19, v16, v17, vcc
	v_rsq_f32_e32 v136, v19
	s_nop 0
	v_cvt_pk_bf16_f32 v16, v30, v31
	v_cvt_pk_bf16_f32 v17, v28, v29
	v_cvt_pk_bf16_f32 v18, v20, v21
	s_nop 0
	s_nop 1
	s_nop 1
	v_cvt_pk_bf16_f32 v19, v22, v23
	global_store_dwordx4 v[144:145], v[16:19], off offset:256
	s_nop 1
	v_mov_b32_e32 v16, v136
	v_add_u32_e32 v17, 0xb0, v227
	v_mul_f32_e32 v16, v225, v16
	v_pk_mul_f32 v[132:133], v[132:133], v[16:17] op_sel_hi:[1,0]
	v_pk_mul_f32 v[134:135], v[134:135], v[16:17] op_sel_hi:[1,0]
	v_pk_mul_f32 v[130:131], v[130:131], v[16:17] op_sel_hi:[1,0]
	v_pk_mul_f32 v[128:129], v[128:129], v[16:17] op_sel_hi:[1,0]
	v_mad_i64_i32 v[16:17], s[0:1], v17, s74, v[188:189]
	v_lshl_add_u64 v[136:137], v[16:17], 0, v[190:191]
	v_pk_mul_f32 v[18:19], v[8:9], v[128:129]
	v_pk_mul_f32 v[16:17], v[10:11], v[130:131]
	v_pk_mul_f32 v[138:139], v[8:9], v[132:133]
	v_pk_mul_f32 v[8:9], v[10:11], v[134:135]
	v_pk_fma_f32 v[16:17], v[14:15], v[134:135], v[16:17] neg_lo:[0,0,1] neg_hi:[0,0,1]
	v_pk_fma_f32 v[18:19], v[12:13], v[132:133], v[18:19] neg_lo:[0,0,1] neg_hi:[0,0,1]
	v_pk_fma_f32 v[8:9], v[14:15], v[130:131], v[8:9]
	v_pk_fma_f32 v[10:11], v[12:13], v[128:129], v[138:139]
	v_cvt_pk_bf16_f32 v12, v18, v19
	v_cvt_pk_bf16_f32 v13, v16, v17
	v_cvt_pk_bf16_f32 v14, v10, v11
	v_cvt_pk_bf16_f32 v15, v8, v9
	global_store_dwordx4 v[136:137], v[12:15], off
	s_nop 1
	v_pk_mul_f32 v[14:15], v[0:1], v[128:129]
	v_pk_mul_f32 v[12:13], v[2:3], v[130:131]
	v_pk_fma_f32 v[14:15], v[4:5], v[132:133], v[14:15] neg_lo:[0,0,1] neg_hi:[0,0,1]
	v_pk_mul_f32 v[132:133], v[0:1], v[132:133]
	v_pk_mul_f32 v[0:1], v[2:3], v[134:135]
	v_pk_fma_f32 v[12:13], v[6:7], v[134:135], v[12:13] neg_lo:[0,0,1] neg_hi:[0,0,1]
	v_pk_fma_f32 v[0:1], v[6:7], v[130:131], v[0:1]
	v_pk_fma_f32 v[2:3], v[4:5], v[128:129], v[132:133]
	v_cvt_pk_bf16_f32 v4, v14, v15
	v_cvt_pk_bf16_f32 v5, v12, v13
	v_cvt_pk_bf16_f32 v6, v2, v3
	v_cvt_pk_bf16_f32 v7, v0, v1
	global_store_dwordx4 v[136:137], v[4:7], off offset:256
	s_cbranch_scc1 .LBB0_374
;     __device__ __forceinline__ void operator()(const AccT& acc, const Unit& u, int wr, int wc, int fr, int fq) const {
;     ...
;         if (kmean) {
; #pragma unroll
;             for (int bj = 0; bj < 2; ++bj)
; #pragma unroll
;                 for (int n = 0; n < 2; ++n)
; #pragma unroll
;                     for (int e = 0; e < 4; ++e) {
;                         float v = cs[bj][n][e];
;                         v += __shfl_xor(v, 1); v += __shfl_xor(v, 2); v += __shfl_xor(v, 4); v += __shfl_xor(v, 8);
;                         cs[bj][n][e] = v;
;                     }
	s_nop 0
	v_pk_add_f32 v[4:5], v[118:119], 0 op_sel_hi:[1,0]
	v_pk_add_f32 v[6:7], v[116:117], 0 op_sel_hi:[1,0]
	v_pk_add_f32 v[4:5], v[4:5], v[102:103]
	v_pk_add_f32 v[6:7], v[6:7], v[100:101]
	v_pk_add_f32 v[4:5], v[4:5], v[86:87]
	v_pk_add_f32 v[6:7], v[6:7], v[84:85]
	v_pk_add_f32 v[4:5], v[4:5], v[70:71]
	v_pk_add_f32 v[6:7], v[6:7], v[68:69]
	v_pk_add_f32 v[4:5], v[4:5], v[54:55]
	v_pk_add_f32 v[6:7], v[6:7], v[52:53]
	v_pk_add_f32 v[4:5], v[4:5], v[38:39]
	v_pk_add_f32 v[6:7], v[6:7], v[36:37]
	v_pk_add_f32 v[4:5], v[4:5], v[22:23]
	v_pk_add_f32 v[6:7], v[6:7], v[20:21]
	v_pk_add_f32 v[0:1], v[4:5], v[0:1]
	v_pk_add_f32 v[2:3], v[6:7], v[2:3]
	v_pk_add_f32 v[4:5], v[124:125], 0 op_sel_hi:[1,0]
	v_pk_add_f32 v[6:7], v[126:127], 0 op_sel_hi:[1,0]
	v_pk_add_f32 v[4:5], v[4:5], v[108:109]
	v_pk_add_f32 v[6:7], v[6:7], v[110:111]
	v_pk_add_f32 v[4:5], v[4:5], v[92:93]
	v_pk_add_f32 v[6:7], v[6:7], v[94:95]
	v_pk_add_f32 v[4:5], v[4:5], v[76:77]
	v_pk_add_f32 v[6:7], v[6:7], v[78:79]
	v_pk_add_f32 v[4:5], v[4:5], v[60:61]
	v_pk_add_f32 v[6:7], v[6:7], v[62:63]
	v_pk_add_f32 v[4:5], v[4:5], v[44:45]
	v_pk_add_f32 v[6:7], v[6:7], v[46:47]
	v_pk_add_f32 v[4:5], v[4:5], v[28:29]
	v_pk_add_f32 v[6:7], v[6:7], v[30:31]
	v_pk_add_f32 v[20:21], v[4:5], v[12:13]
	v_pk_add_f32 v[22:23], v[6:7], v[14:15]
	v_pk_add_f32 v[4:5], v[120:121], 0 op_sel_hi:[1,0]
	v_pk_add_f32 v[6:7], v[122:123], 0 op_sel_hi:[1,0]
	v_pk_add_f32 v[4:5], v[4:5], v[104:105]
	v_pk_add_f32 v[6:7], v[6:7], v[106:107]
	v_pk_add_f32 v[4:5], v[4:5], v[88:89]
	v_pk_add_f32 v[6:7], v[6:7], v[90:91]
	v_pk_add_f32 v[4:5], v[4:5], v[72:73]
	v_pk_add_f32 v[6:7], v[6:7], v[74:75]
	v_pk_add_f32 v[4:5], v[4:5], v[56:57]
	v_pk_add_f32 v[6:7], v[6:7], v[58:59]
	v_pk_add_f32 v[4:5], v[4:5], v[40:41]
	v_pk_add_f32 v[6:7], v[6:7], v[42:43]
	v_pk_add_f32 v[4:5], v[4:5], v[24:25]
	v_pk_add_f32 v[6:7], v[6:7], v[26:27]
	v_pk_add_f32 v[12:13], v[4:5], v[8:9]
	v_pk_add_f32 v[8:9], v[6:7], v[10:11]
	v_pk_add_f32 v[6:7], v[186:187], 0 op_sel_hi:[1,0]
	v_and_b32_e32 v11, 64, v238
	v_pk_add_f32 v[6:7], v[6:7], v[114:115]
	v_pk_add_f32 v[4:5], v[184:185], 0 op_sel_hi:[1,0]
	v_pk_add_f32 v[6:7], v[6:7], v[98:99]
	v_xor_b32_e32 v10, 1, v238
	v_add_u32_e32 v14, 64, v11
	v_pk_add_f32 v[4:5], v[4:5], v[112:113]
	v_pk_add_f32 v[6:7], v[6:7], v[82:83]
	v_cmp_lt_i32_e32 vcc, v10, v14
	v_pk_add_f32 v[4:5], v[4:5], v[96:97]
	v_pk_add_f32 v[6:7], v[6:7], v[66:67]
	v_cndmask_b32_e32 v10, v238, v10, vcc
	v_pk_add_f32 v[4:5], v[4:5], v[80:81]
	v_pk_add_f32 v[6:7], v[6:7], v[50:51]
	v_lshlrev_b32_e32 v31, 2, v10
	v_xor_b32_e32 v10, 2, v238
	v_pk_add_f32 v[4:5], v[4:5], v[64:65]
	v_pk_add_f32 v[6:7], v[6:7], v[34:35]
	v_cmp_lt_i32_e32 vcc, v10, v14
	v_pk_add_f32 v[4:5], v[4:5], v[48:49]
	v_pk_add_f32 v[6:7], v[6:7], v[18:19]
	v_cndmask_b32_e32 v10, v238, v10, vcc
	v_pk_add_f32 v[4:5], v[4:5], v[32:33]
	v_lshlrev_b32_e32 v32, 2, v10
	ds_bpermute_b32 v10, v31, v6
	ds_bpermute_b32 v11, v31, v7
	v_xor_b32_e32 v15, 4, v238
	v_cmp_lt_i32_e32 vcc, v15, v14
	v_pk_add_f32 v[4:5], v[4:5], v[16:17]
	ds_bpermute_b32 v28, v31, v20
	s_waitcnt lgkmcnt(1)
	v_pk_add_f32 v[6:7], v[6:7], v[10:11]
	ds_bpermute_b32 v10, v32, v6
	ds_bpermute_b32 v11, v32, v7
	v_cndmask_b32_e32 v15, v238, v15, vcc
	v_lshlrev_b32_e32 v33, 2, v15
	v_xor_b32_e32 v15, 8, v238
	v_cmp_lt_i32_e32 vcc, v15, v14
	ds_bpermute_b32 v14, v31, v4
	s_waitcnt lgkmcnt(1)
	v_pk_add_f32 v[6:7], v[6:7], v[10:11]
	v_cndmask_b32_e32 v16, v238, v15, vcc
	ds_bpermute_b32 v15, v31, v5
	ds_bpermute_b32 v10, v33, v6
	ds_bpermute_b32 v11, v33, v7
	v_lshlrev_b32_e32 v34, 2, v16
	ds_bpermute_b32 v29, v31, v21
	s_waitcnt lgkmcnt(3)
	v_pk_add_f32 v[14:15], v[4:5], v[14:15]
	ds_bpermute_b32 v16, v32, v14
	ds_bpermute_b32 v17, v32, v15
	s_waitcnt lgkmcnt(3)
	v_pk_add_f32 v[4:5], v[6:7], v[10:11]
	ds_bpermute_b32 v10, v31, v8
	ds_bpermute_b32 v11, v31, v9
	ds_bpermute_b32 v30, v31, v0
	s_waitcnt lgkmcnt(3)
	v_pk_add_f32 v[14:15], v[14:15], v[16:17]
	ds_bpermute_b32 v16, v33, v14
	ds_bpermute_b32 v17, v33, v15
	s_waitcnt lgkmcnt(3)
	v_pk_add_f32 v[18:19], v[8:9], v[10:11]
	ds_bpermute_b32 v24, v32, v18
	ds_bpermute_b32 v25, v32, v19
	ds_bpermute_b32 v6, v34, v4
	s_waitcnt lgkmcnt(3)
	v_pk_add_f32 v[8:9], v[14:15], v[16:17]
	ds_bpermute_b32 v14, v31, v12
	ds_bpermute_b32 v15, v31, v13
	s_waitcnt lgkmcnt(3)
	v_pk_add_f32 v[16:17], v[18:19], v[24:25]
	ds_bpermute_b32 v18, v33, v16
	ds_bpermute_b32 v19, v33, v17
	ds_bpermute_b32 v7, v34, v5
	s_waitcnt lgkmcnt(3)
	v_pk_add_f32 v[24:25], v[12:13], v[14:15]
	ds_bpermute_b32 v26, v32, v24
	ds_bpermute_b32 v27, v32, v25
	s_waitcnt lgkmcnt(3)
	v_pk_add_f32 v[12:13], v[16:17], v[18:19]
	ds_bpermute_b32 v16, v31, v22
	ds_bpermute_b32 v17, v31, v23
	ds_bpermute_b32 v10, v34, v8
	s_waitcnt lgkmcnt(3)
	v_pk_add_f32 v[18:19], v[24:25], v[26:27]
	ds_bpermute_b32 v24, v33, v18
	ds_bpermute_b32 v25, v33, v19
	s_waitcnt lgkmcnt(3)
	v_pk_add_f32 v[22:23], v[22:23], v[16:17]
	ds_bpermute_b32 v26, v32, v22
	ds_bpermute_b32 v27, v32, v23
	ds_bpermute_b32 v11, v34, v9
	s_waitcnt lgkmcnt(3)
	v_pk_add_f32 v[16:17], v[18:19], v[24:25]
	ds_bpermute_b32 v14, v34, v12
	ds_bpermute_b32 v15, v34, v13
	s_waitcnt lgkmcnt(3)
	v_pk_add_f32 v[22:23], v[22:23], v[26:27]
	v_pk_add_f32 v[26:27], v[20:21], v[28:29]
	ds_bpermute_b32 v24, v33, v22
	ds_bpermute_b32 v25, v33, v23
	ds_bpermute_b32 v28, v32, v26
	ds_bpermute_b32 v29, v32, v27
	ds_bpermute_b32 v18, v34, v16
	ds_bpermute_b32 v19, v34, v17
	s_waitcnt lgkmcnt(4)
	v_pk_add_f32 v[20:21], v[22:23], v[24:25]
	ds_bpermute_b32 v22, v34, v20
	s_waitcnt lgkmcnt(3)
	v_pk_add_f32 v[24:25], v[26:27], v[28:29]
	ds_bpermute_b32 v28, v31, v2
	ds_bpermute_b32 v29, v31, v3
	ds_bpermute_b32 v31, v31, v1
	ds_bpermute_b32 v26, v33, v24
	ds_bpermute_b32 v27, v33, v25
	ds_bpermute_b32 v23, v34, v21
	s_waitcnt lgkmcnt(4)
	v_pk_add_f32 v[2:3], v[2:3], v[28:29]
	s_waitcnt lgkmcnt(3)
	v_pk_add_f32 v[28:29], v[0:1], v[30:31]
	ds_bpermute_b32 v30, v32, v28
	s_waitcnt lgkmcnt(2)
	v_pk_add_f32 v[24:25], v[24:25], v[26:27]
	ds_bpermute_b32 v26, v32, v2
	ds_bpermute_b32 v27, v32, v3
	ds_bpermute_b32 v31, v32, v29
	ds_bpermute_b32 v0, v34, v24
	ds_bpermute_b32 v1, v34, v25
	s_waitcnt lgkmcnt(3)
	v_pk_add_f32 v[2:3], v[2:3], v[26:27]
	s_waitcnt lgkmcnt(2)
	v_pk_add_f32 v[28:29], v[28:29], v[30:31]
	ds_bpermute_b32 v26, v33, v2
	ds_bpermute_b32 v27, v33, v3
	ds_bpermute_b32 v30, v33, v28
	ds_bpermute_b32 v31, v33, v29
	s_waitcnt lgkmcnt(2)
	v_pk_add_f32 v[2:3], v[2:3], v[26:27]
	ds_bpermute_b32 v26, v34, v2
	s_waitcnt lgkmcnt(1)
	v_pk_add_f32 v[28:29], v[28:29], v[30:31]
	ds_bpermute_b32 v27, v34, v3
	ds_bpermute_b32 v30, v34, v28
	ds_bpermute_b32 v31, v34, v29
	s_and_saveexec_b64 s[0:1], s[6:7]
	s_cbranch_execz .LBB0_373
;     __device__ __forceinline__ void operator()(const AccT& acc, const Unit& u, int wr, int wc, int fr, int fq) const {
;     ...
;             if (fr == 0) {
;                 float* kp = KMP + ((size_t)wr * 32 + u.pm) * 1024 + (pn - 4) * 256 + wc * 32 + 8 * fq;
; #pragma unroll
;                 for (int bj = 0; bj < 2; ++bj) { *(f32x4*)(kp + bj * 128) = cs[bj][0]; *(f32x4*)(kp + bj * 128 + 4) = cs[bj][1]; }
;             }
	s_ashr_i32 s29, s28, 31
	s_lshl_b64 s[10:11], s[28:29], 12
	s_add_u32 s14, s54, s10
	s_addc_u32 s15, s53, s11
	s_lshl_b64 s[10:11], s[90:91], 2
	s_add_u32 s10, s14, s10
	s_addc_u32 s11, s15, s11
	s_add_u32 s10, s10, s79
	s_addc_u32 s11, s11, 0
	v_mov_b32_e32 v227, v193
	v_pk_add_f32 v[6:7], v[4:5], v[6:7]
	v_lshl_add_u64 v[4:5], s[10:11], 0, v[226:227]
	s_mov_b64 s[10:11], 0x283ff000
	v_pk_add_f32 v[8:9], v[8:9], v[10:11]
	v_lshl_add_u64 v[10:11], v[4:5], 0, s[10:11]
	s_mov_b32 s10, 0x283ff000
	v_add_co_u32_e32 v4, vcc, s10, v4
	s_waitcnt lgkmcnt(0)
	v_pk_add_f32 v[28:29], v[28:29], v[30:31]
	v_addc_co_u32_e32 v5, vcc, 0, v5, vcc
	v_pk_add_f32 v[26:27], v[2:3], v[26:27]
	v_pk_add_f32 v[2:3], v[24:25], v[0:1]
	v_pk_add_f32 v[0:1], v[20:21], v[22:23]
	v_pk_add_f32 v[16:17], v[16:17], v[18:19]
	v_pk_add_f32 v[14:15], v[12:13], v[14:15]
	global_store_dwordx4 v[4:5], v[6:9], off
	global_store_dwordx4 v[10:11], v[14:17], off offset:16
	global_store_dwordx4 v[10:11], v[0:3], off offset:512
	global_store_dwordx4 v[10:11], v[26:29], off offset:528

; #define LAS __attribute__((address_space(3)))
; __device__ __forceinline__ int otid() { int x = threadIdx.x; asm volatile("" : "+v"(x)); return x; }
; __device__ __forceinline__ unsigned char* opq_ptr(unsigned char* q) { int z = 0; asm volatile("" : "+s"(z)); return q + z; }
; __device__ __forceinline__ float ret_log2g(int h) { const double g = 1.0 - ldexp(1.0, -(5 + h)); return (float)log2(g); }
; __device__ __forceinline__ void ret_kv_item(const Params& p, LAS unsigned char* lds, int b, int h, int n) {
;     unsigned char* wsb = opq_ptr(p.ws);
;     const bf16_t* PROJ = (const bf16_t*)(wsb + WS_PROJ);
;     float* KV = (float*)(wsb + WS_HID);
;     const int tid = otid(), wave = __builtin_amdgcn_readfirstlane(tid >> 6), lane = tid & 63, r = lane & 31, hh = lane >> 5;
;     const int q4 = (lane & 15) >> 2, p4 = lane & 3, b16 = (lane >> 4) & 1;
;     const size_t tok0 = (size_t)b * S + n * 128;
;     const float lg2 = ret_log2g(h);
;     LAS unsigned char* Kl = lds + RK_K; LAS unsigned char* Vl = lds + RK_V;
;     __syncthreads();
;     u32x4 kin[4], vin[8];
; #pragma unroll
;     for (int i = 0; i < 4; ++i) { const int c = tid + 512 * i, row = c >> 4, cc = c & 15; kin[i] = *(const u32x4*)(PROJ + (tok0 + row) * INW + C_KR + h * 128 + cc * 8); }
; #pragma unroll
;     for (int i = 0; i < 8; ++i) { const int c = tid + 512 * i, row = c >> 5, cc = c & 31; vin[i] = *(const u32x4*)(PROJ + (tok0 + row) * INW + C_VR + h * 256 + cc * 8); }
.LBB0_500:
	s_mov_b32 s1, 0
	s_ashr_i32 s0, s4, 8
	s_bfe_u32 s13, s4, 0x30005
	s_and_b32 s5, s4, 31
	s_ashr_i32 s8, s1, 31
	s_add_u32 s10, s76, s1
	s_addc_u32 s11, s77, s8
	v_mov_b32_e32 v76, v234
	s_add_u32 s8, s10, 0x18400000
	s_addc_u32 s9, s11, 0
	v_readfirstlane_b32 s1, v76
	s_ashr_i32 s12, s1, 6
	s_ashr_i32 s1, s0, 31
	s_lshl_b64 s[0:1], s[0:1], 12
	s_lshl_b32 s14, s5, 7
	s_or_b32 s0, s0, s14
	s_sub_i32 s14, -5, s13
	v_ldexp_f64 v[0:1], 1.0, s14
	v_add_f64 v[0:1], -v[0:1], 1.0
	v_frexp_mant_f64_e32 v[2:3], v[0:1]
	v_cmp_gt_f64_e32 vcc, s[92:93], v[2:3]
	v_frexp_exp_i32_f64_e32 v4, v[0:1]
	v_ashrrev_i32_e32 v70, 4, v76
	v_cndmask_b32_e64 v5, 0, 1, vcc
	v_ldexp_f64 v[2:3], v[2:3], v5
	v_add_f64 v[6:7], v[2:3], 1.0
	v_add_f64 v[8:9], v[6:7], -1.0
	v_subbrev_co_u32_e32 v16, vcc, 0, v4, vcc
	v_add_f64 v[4:5], v[2:3], -1.0
	v_add_f64 v[2:3], v[2:3], -v[8:9]
	v_rcp_f64_e32 v[8:9], v[6:7]
	v_cmp_class_f64_e64 vcc, v[0:1], s85
	v_ashrrev_i32_e32 v71, 31, v70
	v_mov_b64_e32 v[44:45], s[8:9]
	v_fma_f64 v[10:11], -v[6:7], v[8:9], 1.0
	v_fmac_f64_e32 v[8:9], v[10:11], v[8:9]
	v_fma_f64 v[10:11], -v[6:7], v[8:9], 1.0
	v_fmac_f64_e32 v[8:9], v[10:11], v[8:9]
	v_mul_f64 v[10:11], v[4:5], v[8:9]
	v_mul_f64 v[12:13], v[6:7], v[10:11]
	v_fma_f64 v[6:7], v[10:11], v[6:7], -v[12:13]
	v_fmac_f64_e32 v[6:7], v[10:11], v[2:3]
	v_add_f64 v[2:3], v[12:13], v[6:7]
	v_add_f64 v[14:15], v[4:5], -v[2:3]
	v_add_f64 v[12:13], v[2:3], -v[12:13]
	v_add_f64 v[4:5], v[4:5], -v[14:15]
	v_add_f64 v[2:3], v[4:5], -v[2:3]
	v_add_f64 v[4:5], v[12:13], -v[6:7]
	v_add_f64 v[2:3], v[4:5], v[2:3]
	v_add_f64 v[2:3], v[14:15], v[2:3]
	v_mul_f64 v[2:3], v[8:9], v[2:3]
	v_add_f64 v[4:5], v[10:11], v[2:3]
	v_add_f64 v[6:7], v[4:5], -v[10:11]
	v_add_f64 v[2:3], v[2:3], -v[6:7]
	v_mul_f64 v[6:7], v[4:5], v[4:5]
	v_mov_b64_e32 v[8:9], v[204:205]
	v_fmac_f64_e32 v[8:9], s[52:53], v[6:7]
	v_mov_b64_e32 v[10:11], v[206:207]
	v_fmac_f64_e32 v[10:11], v[6:7], v[8:9]
	v_mov_b64_e32 v[8:9], v[208:209]
	v_fmac_f64_e32 v[8:9], v[6:7], v[10:11]
	v_mov_b64_e32 v[10:11], v[210:211]
	v_fmac_f64_e32 v[10:11], v[6:7], v[8:9]
	v_mov_b64_e32 v[8:9], v[212:213]
	v_fmac_f64_e32 v[8:9], v[6:7], v[10:11]
	v_mov_b64_e32 v[10:11], v[214:215]
	v_fmac_f64_e32 v[10:11], v[6:7], v[8:9]
	v_ldexp_f64 v[8:9], v[4:5], 1
	v_mul_f64 v[4:5], v[4:5], v[6:7]
	v_mul_f64 v[4:5], v[4:5], v[10:11]
	v_add_f64 v[6:7], v[8:9], v[4:5]
	v_add_f64 v[8:9], v[6:7], -v[8:9]
	v_ldexp_f64 v[2:3], v[2:3], 1
	v_add_f64 v[4:5], v[4:5], -v[8:9]
	v_add_f64 v[2:3], v[2:3], v[4:5]
	v_add_f64 v[4:5], v[6:7], v[2:3]
	v_add_f64 v[6:7], v[4:5], -v[6:7]
	v_mul_f64 v[8:9], v[4:5], s[82:83]
	v_add_f64 v[2:3], v[2:3], -v[6:7]
	v_fma_f64 v[10:11], v[4:5], s[82:83], -v[8:9]
	v_fmac_f64_e32 v[10:11], s[82:83], v[2:3]
	v_fmac_f64_e32 v[10:11], s[88:89], v[4:5]
	v_cvt_f64_i32_e32 v[6:7], v16
	v_add_f64 v[2:3], v[8:9], v[10:11]
	v_add_f64 v[4:5], v[2:3], -v[8:9]
	v_add_f64 v[8:9], v[2:3], v[6:7]
	v_add_f64 v[4:5], v[10:11], -v[4:5]
	v_add_f64 v[10:11], v[8:9], -v[6:7]
	v_add_f64 v[12:13], v[10:11], -v[8:9]
	v_add_f64 v[6:7], v[12:13], v[6:7]
	v_add_f64 v[2:3], v[2:3], -v[10:11]
	v_add_f64 v[2:3], v[2:3], v[6:7]
	v_add_f64 v[2:3], v[4:5], v[2:3]
	v_add_f64 v[2:3], v[8:9], v[2:3]
	v_cndmask_b32_e32 v2, v2, v0, vcc
	v_cndmask_b32_e32 v3, v3, v1, vcc
	v_cmp_ngt_f64_e32 vcc, 0, v[0:1]
	s_lshl_b32 s90, s13, 8
	v_lshlrev_b32_e32 v8, 4, v76
	v_cndmask_b32_e32 v3, v241, v3, vcc
	v_cmp_nge_f64_e32 vcc, 0, v[0:1]
	v_and_b32_e32 v192, 0xf0, v8
	v_add_u32_e32 v9, 0x200, v76
	v_cndmask_b32_e32 v48, 0, v2, vcc
	v_cmp_neq_f64_e32 vcc, 0, v[0:1]
	v_lshl_add_u64 v[0:1], s[0:1], 0, v[70:71]
	v_ashrrev_i32_e32 v64, 4, v9
	v_cndmask_b32_e32 v49, v235, v3, vcc
	v_mad_u64_u32 v[2:3], s[8:9], v0, s74, v[44:45]
	v_mad_i32_i24 v3, v1, s74, v3
	v_lshl_add_u64 v[0:1], v[2:3], 0, s[90:91]
	v_lshl_add_u64 v[0:1], v[0:1], 0, v[192:193]
	v_add_co_u32_e32 v0, vcc, s51, v0
	v_ashrrev_i32_e32 v65, 31, v64
	s_nop 0
	v_addc_co_u32_e32 v1, vcc, 0, v1, vcc
	s_barrier
	global_load_dwordx4 v[40:43], v[0:1], off
	v_lshl_add_u64 v[0:1], s[0:1], 0, v[64:65]
	v_mad_u64_u32 v[2:3], s[8:9], v0, s74, v[44:45]
	v_mad_i32_i24 v3, v1, s74, v3
	v_lshl_add_u64 v[0:1], v[2:3], 0, s[90:91]
	v_lshl_add_u64 v[0:1], v[0:1], 0, v[192:193]
	v_add_u32_e32 v16, 0x400, v76
	v_add_co_u32_e32 v0, vcc, s51, v0
	v_ashrrev_i32_e32 v58, 4, v16
	s_nop 0
	v_addc_co_u32_e32 v1, vcc, 0, v1, vcc
	v_ashrrev_i32_e32 v59, 31, v58
	global_load_dwordx4 v[28:31], v[0:1], off
	v_lshl_add_u64 v[0:1], s[0:1], 0, v[58:59]
	v_mad_u64_u32 v[2:3], s[8:9], v0, s74, v[44:45]
	v_mad_i32_i24 v3, v1, s74, v3
	v_lshl_add_u64 v[0:1], v[2:3], 0, s[90:91]
	v_lshl_add_u64 v[0:1], v[0:1], 0, v[192:193]
	v_add_u32_e32 v20, 0x600, v76
	v_add_co_u32_e32 v0, vcc, s51, v0
	v_ashrrev_i32_e32 v50, 4, v20
	s_nop 0
	v_addc_co_u32_e32 v1, vcc, 0, v1, vcc
	v_ashrrev_i32_e32 v51, 31, v50
	global_load_dwordx4 v[12:15], v[0:1], off
	v_lshl_add_u64 v[0:1], s[0:1], 0, v[50:51]
	v_ashrrev_i32_e32 v52, 5, v76
	v_mad_u64_u32 v[2:3], s[8:9], v0, s74, v[44:45]
	v_ashrrev_i32_e32 v53, 31, v52
	v_mad_i32_i24 v3, v1, s74, v3
	v_lshl_add_u64 v[4:5], s[0:1], 0, v[52:53]
	v_ashrrev_i32_e32 v56, 5, v9
	v_lshl_add_u64 v[0:1], v[2:3], 0, s[90:91]
	v_mad_u64_u32 v[6:7], s[8:9], v4, s74, v[44:45]
	v_ashrrev_i32_e32 v57, 31, v56
	v_lshl_add_u64 v[0:1], v[0:1], 0, v[192:193]
	v_mad_i32_i24 v7, v5, s74, v7
	s_lshl_b32 s90, s13, 9
	v_and_b32_e32 v54, 0x1f0, v8
	v_lshl_add_u64 v[8:9], s[0:1], 0, v[56:57]
	v_ashrrev_i32_e32 v60, 5, v16
	v_add_co_u32_e32 v0, vcc, s51, v0
	v_lshl_add_u64 v[4:5], v[6:7], 0, s[90:91]
	v_mov_b32_e32 v55, v193
	v_mad_u64_u32 v[10:11], s[8:9], v8, s74, v[44:45]
; #define LAS __attribute__((address_space(3)))
; __device__ __forceinline__ unsigned pk2(float lo, float hi) { f32x2 f = {lo, hi}; bf16x2_t b = __builtin_convertvector(f, bf16x2_t); return __builtin_bit_cast(unsigned, b); }
; __device__ __forceinline__ float bflo(unsigned u) { return __uint_as_float(u << 16); }
; __device__ __forceinline__ float bfhi(unsigned u) { return __uint_as_float(u & 0xffff0000u); }
; __device__ __forceinline__ void ret_kv_item(const Params& p, LAS unsigned char* lds, int b, int h, int n) {
;     ...
;     for (int i = 0; i < 4; ++i) { const int c = tid + 512 * i, row = c >> 4, cc = c & 15; kin[i] = *(const u32x4*)(PROJ + (tok0 + row) * INW + C_KR + h * 128 + cc * 8); }
; #pragma unroll
;     for (int i = 0; i < 8; ++i) { const int c = tid + 512 * i, row = c >> 5, cc = c & 31; vin[i] = *(const u32x4*)(PROJ + (tok0 + row) * INW + C_VR + h * 256 + cc * 8); }
;     __builtin_amdgcn_sched_barrier(0);
; #pragma unroll
;     for (int i = 0; i < 4; ++i) {
;         const int c = tid + 512 * i, row = c >> 4, cc = c & 15;
;         const u32x4 t = kin[i];
;         const float z = __builtin_amdgcn_exp2f((float)(127 - row) * lg2);
;         u32x4 o; o.x = pk2(bflo(t.x) * z, bfhi(t.x) * z); o.y = pk2(bflo(t.y) * z, bfhi(t.y) * z); o.z = pk2(bflo(t.z) * z, bfhi(t.z) * z); o.w = pk2(bflo(t.w) * z, bfhi(t.w) * z);
;         *(LAS u32x4*)(Kl + row * RK_KS + cc * 16) = o;
;     }
; #pragma unroll
;     for (int i = 0; i < 8; ++i) {
;         const int c = tid + 512 * i, row = c >> 5, cc = c & 31;
;         *(LAS u32x4*)(Vl + row * RK_VS + cc * 16) = vin[i];
;     }
	v_ashrrev_i32_e32 v61, 31, v60
	v_addc_co_u32_e32 v1, vcc, 0, v1, vcc
	v_lshl_add_u64 v[4:5], v[4:5], 0, v[54:55]
	v_mad_i32_i24 v11, v9, s74, v11
	v_lshl_add_u64 v[16:17], s[0:1], 0, v[60:61]
	v_ashrrev_i32_e32 v62, 5, v20
	v_add_co_u32_e32 v4, vcc, s51, v4
	v_lshl_add_u64 v[8:9], v[10:11], 0, s[90:91]
	v_mad_u64_u32 v[18:19], s[8:9], v16, s74, v[44:45]
	v_ashrrev_i32_e32 v63, 31, v62
	v_add_u32_e32 v24, 0x800, v76
	v_addc_co_u32_e32 v5, vcc, 0, v5, vcc
	v_lshl_add_u64 v[8:9], v[8:9], 0, v[54:55]
	v_mad_i32_i24 v19, v17, s74, v19
	v_lshl_add_u64 v[20:21], s[0:1], 0, v[62:63]
	v_ashrrev_i32_e32 v66, 5, v24
	v_add_co_u32_e32 v8, vcc, s51, v8
	v_lshl_add_u64 v[16:17], v[18:19], 0, s[90:91]
	v_mad_u64_u32 v[22:23], s[8:9], v20, s74, v[44:45]
	v_ashrrev_i32_e32 v67, 31, v66
	v_add_u32_e32 v32, 0xa00, v76
	v_addc_co_u32_e32 v9, vcc, 0, v9, vcc
	v_lshl_add_u64 v[16:17], v[16:17], 0, v[54:55]
	v_mad_i32_i24 v23, v21, s74, v23
	v_lshl_add_u64 v[24:25], s[0:1], 0, v[66:67]
	v_ashrrev_i32_e32 v68, 5, v32
	v_add_co_u32_e32 v16, vcc, s51, v16
	v_lshl_add_u64 v[20:21], v[22:23], 0, s[90:91]
	v_mad_u64_u32 v[26:27], s[8:9], v24, s74, v[44:45]
	v_ashrrev_i32_e32 v69, 31, v68
	v_add_u32_e32 v36, 0xc00, v76
	v_addc_co_u32_e32 v17, vcc, 0, v17, vcc
	v_lshl_add_u64 v[20:21], v[20:21], 0, v[54:55]
	v_mad_i32_i24 v27, v25, s74, v27
	v_lshl_add_u64 v[32:33], s[0:1], 0, v[68:69]
	v_ashrrev_i32_e32 v72, 5, v36
	v_add_co_u32_e32 v20, vcc, s51, v20
	v_lshl_add_u64 v[24:25], v[26:27], 0, s[90:91]
	v_mad_u64_u32 v[34:35], s[8:9], v32, s74, v[44:45]
	v_ashrrev_i32_e32 v73, 31, v72
	v_add_u32_e32 v46, 0xe00, v76
	v_addc_co_u32_e32 v21, vcc, 0, v21, vcc
	v_lshl_add_u64 v[24:25], v[24:25], 0, v[54:55]
	v_mad_i32_i24 v35, v33, s74, v35
	v_lshl_add_u64 v[36:37], s[0:1], 0, v[72:73]
	v_ashrrev_i32_e32 v74, 5, v46
	v_add_co_u32_e32 v24, vcc, s51, v24
	v_lshl_add_u64 v[32:33], v[34:35], 0, s[90:91]
	v_mad_u64_u32 v[38:39], s[8:9], v36, s74, v[44:45]
	v_ashrrev_i32_e32 v75, 31, v74
	v_addc_co_u32_e32 v25, vcc, 0, v25, vcc
	v_lshl_add_u64 v[32:33], v[32:33], 0, v[54:55]
	v_mad_i32_i24 v39, v37, s74, v39
	v_lshl_add_u64 v[46:47], s[0:1], 0, v[74:75]
	v_add_co_u32_e32 v32, vcc, s51, v32
	v_lshl_add_u64 v[36:37], v[38:39], 0, s[90:91]
	v_mad_u64_u32 v[44:45], s[0:1], v46, s74, v[44:45]
	v_addc_co_u32_e32 v33, vcc, 0, v33, vcc
	v_lshl_add_u64 v[36:37], v[36:37], 0, v[54:55]
	v_mad_i32_i24 v45, v47, s74, v45
	v_add_co_u32_e32 v36, vcc, s51, v36
	v_lshl_add_u64 v[44:45], v[44:45], 0, s[90:91]
	s_nop 0
	v_addc_co_u32_e32 v37, vcc, 0, v37, vcc
	v_lshl_add_u64 v[44:45], v[44:45], 0, v[54:55]
	v_add_co_u32_e32 v44, vcc, s51, v44
	global_load_dwordx4 v[0:3], v[0:1], off
	s_nop 0
	v_addc_co_u32_e32 v45, vcc, 0, v45, vcc
	global_load_dwordx4 v[4:7], v[4:5], off offset:2048
	v_bfe_u32 v77, v76, 2, 2
	global_load_dwordx4 v[8:11], v[8:9], off offset:2048
	v_and_b32_e32 v51, 16, v76
	global_load_dwordx4 v[16:19], v[16:17], off offset:2048
	v_cvt_f32_f64_e32 v49, v[48:49]
	global_load_dwordx4 v[20:23], v[20:21], off offset:2048
	s_nop 0
	global_load_dwordx4 v[24:27], v[24:25], off offset:2048
	s_nop 0
	global_load_dwordx4 v[32:35], v[32:33], off offset:2048
	s_nop 0
	global_load_dwordx4 v[36:39], v[36:37], off offset:2048
	s_nop 0
	global_load_dwordx4 v[44:47], v[44:45], off offset:2048
	v_sub_u32_e32 v53, 0x7f, v70
	v_cvt_f32_i32_e32 v53, v53
	s_waitcnt vmcnt(0)
	v_lshlrev_b32_e32 v80, 16, v40
	v_and_b32_e32 v81, 0xffff0000, v40
	v_add_u32_e32 v48, 0, v192
	v_mul_f32_e32 v53, v49, v53
	v_exp_f32_e32 v78, v53
	v_mad_u64_u32 v[70:71], s[0:1], v70, s72, v[48:49]
	v_pk_mul_f32 v[80:81], v[78:79], v[80:81] op_sel_hi:[0,1]
	v_cvt_pk_bf16_f32 v40, v80, v81
	v_lshlrev_b32_e32 v80, 16, v41
	v_and_b32_e32 v81, 0xffff0000, v41
	v_pk_mul_f32 v[80:81], v[78:79], v[80:81] op_sel_hi:[0,1]
	v_cvt_pk_bf16_f32 v41, v80, v81
	v_lshlrev_b32_e32 v80, 16, v42
	v_and_b32_e32 v81, 0xffff0000, v42
	v_pk_mul_f32 v[80:81], v[78:79], v[80:81] op_sel_hi:[0,1]
	v_cvt_pk_bf16_f32 v42, v80, v81
	v_lshlrev_b32_e32 v80, 16, v43
	v_and_b32_e32 v81, 0xffff0000, v43
	v_pk_mul_f32 v[78:79], v[78:79], v[80:81] op_sel_hi:[0,1]
	v_cvt_pk_bf16_f32 v43, v78, v79
	ds_write_b128 v70, v[40:43]
	v_sub_u32_e32 v40, 0x7f, v64
	v_cvt_f32_i32_e32 v40, v40
	v_lshlrev_b32_e32 v42, 16, v28
	v_and_b32_e32 v43, 0xffff0000, v28
	v_mul_f32_e32 v40, v49, v40
	v_exp_f32_e32 v40, v40
	s_nop 0
	v_pk_mul_f32 v[42:43], v[40:41], v[42:43] op_sel_hi:[0,1]
	v_cvt_pk_bf16_f32 v28, v42, v43
	v_lshlrev_b32_e32 v42, 16, v29
	v_and_b32_e32 v43, 0xffff0000, v29
	v_pk_mul_f32 v[42:43], v[40:41], v[42:43] op_sel_hi:[0,1]
	v_cvt_pk_bf16_f32 v29, v42, v43
	v_lshlrev_b32_e32 v42, 16, v30
	v_and_b32_e32 v43, 0xffff0000, v30
	v_pk_mul_f32 v[42:43], v[40:41], v[42:43] op_sel_hi:[0,1]
	v_cvt_pk_bf16_f32 v30, v42, v43
	v_lshlrev_b32_e32 v42, 16, v31
	v_and_b32_e32 v43, 0xffff0000, v31
	v_pk_mul_f32 v[40:41], v[40:41], v[42:43] op_sel_hi:[0,1]
	v_cvt_pk_bf16_f32 v31, v40, v41
	v_mad_u64_u32 v[40:41], s[0:1], v64, s72, v[48:49]
	ds_write_b128 v40, v[28:31]
	v_sub_u32_e32 v28, 0x7f, v58
	v_cvt_f32_i32_e32 v28, v28
	v_lshlrev_b32_e32 v30, 16, v12
	v_and_b32_e32 v31, 0xffff0000, v12
	v_bfe_u32 v64, v76, 5, 1
	v_mul_f32_e32 v28, v49, v28
	v_exp_f32_e32 v28, v28
	s_nop 0
	v_pk_mul_f32 v[30:31], v[28:29], v[30:31] op_sel_hi:[0,1]
	v_cvt_pk_bf16_f32 v12, v30, v31
	v_lshlrev_b32_e32 v30, 16, v13
	v_and_b32_e32 v31, 0xffff0000, v13
	v_pk_mul_f32 v[30:31], v[28:29], v[30:31] op_sel_hi:[0,1]
	v_cvt_pk_bf16_f32 v13, v30, v31
	v_lshlrev_b32_e32 v30, 16, v14
	v_and_b32_e32 v31, 0xffff0000, v14
	v_pk_mul_f32 v[30:31], v[28:29], v[30:31] op_sel_hi:[0,1]
	v_cvt_pk_bf16_f32 v14, v30, v31
; #define LAS __attribute__((address_space(3)))
; #define MFMA32(a, b, c) __builtin_amdgcn_mfma_f32_32x32x16_bf16((a), (b), (c), 0, 0, 0)
; __device__ __forceinline__ void ret_kv_item(const Params& p, LAS unsigned char* lds, int b, int h, int n) {
;     ...
;         *(LAS u32x4*)(Kl + row * RK_KS + cc * 16) = o;
;     }
; #pragma unroll
;     for (int i = 0; i < 8; ++i) {
;         const int c = tid + 512 * i, row = c >> 5, cc = c & 31;
;         *(LAS u32x4*)(Vl + row * RK_VS + cc * 16) = vin[i];
;     }
;     __syncthreads();
;     f32x16 acc[4];
; #pragma unroll
;     for (int dt = 0; dt < 4; ++dt)
; #pragma unroll
;         for (int i = 0; i < 16; ++i) acc[dt][i] = 0.f;
; #pragma unroll
;     for (int ks = 0; ks < 8; ++ks) {
;         const int m0 = 16 * ks + 8 * hh + q4;
;         const bf16x8 af = tr_read2(Vl + m0 * RK_VS + (32 * wave + 16 * b16 + 4 * p4) * 2, 4 * RK_VS);
;         bf16x8 bfr[4];
; #pragma unroll
;         for (int dt = 0; dt < 4; ++dt) bfr[dt] = tr_read2(Kl + m0 * RK_KS + (32 * dt + 16 * b16 + 4 * p4) * 2, 4 * RK_KS);
;         if (ks & 1) __builtin_amdgcn_sched_barrier(0);
; #pragma unroll
;         for (int dt = 0; dt < 4; ++dt) acc[dt] = MFMA32(af, bfr[dt], acc[dt]);
	v_lshlrev_b32_e32 v30, 16, v15
	v_and_b32_e32 v31, 0xffff0000, v15
	v_pk_mul_f32 v[28:29], v[28:29], v[30:31] op_sel_hi:[0,1]
	v_cvt_pk_bf16_f32 v15, v28, v29
	v_mad_u64_u32 v[28:29], s[0:1], v58, s72, v[48:49]
	ds_write_b128 v28, v[12:15]
	v_sub_u32_e32 v12, 0x7f, v50
	v_cvt_f32_i32_e32 v12, v12
	v_lshlrev_b32_e32 v14, 16, v0
	v_and_b32_e32 v15, 0xffff0000, v0
	v_mul_f32_e32 v12, v49, v12
	v_exp_f32_e32 v12, v12
	s_nop 0
	v_pk_mul_f32 v[14:15], v[12:13], v[14:15] op_sel_hi:[0,1]
	v_cvt_pk_bf16_f32 v0, v14, v15
	v_lshlrev_b32_e32 v14, 16, v1
	v_and_b32_e32 v15, 0xffff0000, v1
	v_pk_mul_f32 v[14:15], v[12:13], v[14:15] op_sel_hi:[0,1]
	v_cvt_pk_bf16_f32 v1, v14, v15
	v_lshlrev_b32_e32 v14, 16, v2
	v_and_b32_e32 v15, 0xffff0000, v2
	v_pk_mul_f32 v[14:15], v[12:13], v[14:15] op_sel_hi:[0,1]
	v_cvt_pk_bf16_f32 v2, v14, v15
	v_lshlrev_b32_e32 v14, 16, v3
	v_and_b32_e32 v15, 0xffff0000, v3
	v_pk_mul_f32 v[12:13], v[12:13], v[14:15] op_sel_hi:[0,1]
	v_cvt_pk_bf16_f32 v3, v12, v13
	v_mad_u64_u32 v[12:13], s[0:1], v50, s72, v[48:49]
	ds_write_b128 v12, v[0:3]
	v_add_u32_e32 v0, 0, v54
	v_mad_u64_u32 v[2:3], s[0:1], v52, s94, v[0:1]
	ds_write_b128 v2, v[4:7] offset:40960
	v_mad_u64_u32 v[2:3], s[0:1], v56, s94, v[0:1]
	ds_write_b128 v2, v[8:11] offset:40960
	v_mad_u64_u32 v[2:3], s[0:1], v60, s94, v[0:1]
	ds_write_b128 v2, v[16:19] offset:40960
	v_mad_u64_u32 v[2:3], s[0:1], v62, s94, v[0:1]
	ds_write_b128 v2, v[20:23] offset:40960
	v_mad_u64_u32 v[2:3], s[0:1], v66, s94, v[0:1]
	ds_write_b128 v2, v[24:27] offset:40960
	v_mad_u64_u32 v[2:3], s[0:1], v68, s94, v[0:1]
	ds_write_b128 v2, v[32:35] offset:40960
	v_mad_u64_u32 v[2:3], s[0:1], v72, s94, v[0:1]
	v_mad_u64_u32 v[0:1], s[0:1], v74, s94, v[0:1]
	ds_write_b128 v2, v[36:39] offset:40960
	ds_write_b128 v0, v[44:47] offset:40960
	v_lshlrev_b32_e32 v0, 2, v76
	s_lshl_b32 s0, s12, 5
	v_and_b32_e32 v5, 12, v0
	v_lshl_or_b32 v4, v64, 3, v77
	v_or3_b32 v0, s0, v51, v5
	v_or_b32_e32 v5, v5, v51
	v_lshlrev_b32_e32 v0, 1, v0
	v_mul_u32_u24_e32 v1, 0x240, v4
	v_mul_u32_u24_e32 v4, 0x140, v4
	v_lshlrev_b32_e32 v5, 1, v5
	v_add3_u32 v74, 0, v0, v1
	v_add3_u32 v65, 0, v4, v5
	s_waitcnt lgkmcnt(0)
	s_barrier
	ds_read_b64_tr_b16 v[0:1], v74 offset:40960
	ds_read_b64_tr_b16 v[2:3], v74 offset:43264
	ds_read_b64_tr_b16 v[4:5], v65
	ds_read_b64_tr_b16 v[6:7], v65 offset:1280
	ds_read_b64_tr_b16 v[8:9], v65 offset:64
	ds_read_b64_tr_b16 v[10:11], v65 offset:1344
	ds_read_b64_tr_b16 v[12:13], v65 offset:128
	ds_read_b64_tr_b16 v[14:15], v65 offset:1408
	ds_read_b64_tr_b16 v[66:67], v65 offset:192
	ds_read_b64_tr_b16 v[68:69], v65 offset:1472
	s_waitcnt lgkmcnt(6)
	v_mfma_f32_32x32x16_bf16 v[48:63], v[0:3], v[4:7], 0
	v_add_u32_e32 v75, 0x2400, v74
	s_waitcnt lgkmcnt(4)
	v_mfma_f32_32x32x16_bf16 v[32:47], v[0:3], v[8:11], 0
	s_waitcnt lgkmcnt(2)
	v_mfma_f32_32x32x16_bf16 v[16:31], v[0:3], v[12:15], 0
	s_waitcnt lgkmcnt(0)
	v_mfma_f32_32x32x16_bf16 v[0:15], v[0:3], v[66:69], 0
	ds_read_b64_tr_b16 v[66:67], v74 offset:50176
	ds_read_b64_tr_b16 v[68:69], v74 offset:52480
	ds_read_b64_tr_b16 v[70:71], v65 offset:5120
	ds_read_b64_tr_b16 v[72:73], v65 offset:6400
	ds_read_b64_tr_b16 v[78:79], v65 offset:5184
	ds_read_b64_tr_b16 v[80:81], v65 offset:6464
	ds_read_b64_tr_b16 v[82:83], v65 offset:5248
	ds_read_b64_tr_b16 v[84:85], v65 offset:6528
	ds_read_b64_tr_b16 v[86:87], v65 offset:5312
	ds_read_b64_tr_b16 v[88:89], v65 offset:6592
	s_waitcnt lgkmcnt(6)
	v_mfma_f32_32x32x16_bf16 v[48:63], v[66:69], v[70:73], v[48:63]
	v_add_u32_e32 v77, 0x4800, v74
	v_add_u32_e32 v90, 0x6c00, v74
	s_waitcnt lgkmcnt(4)
	v_mfma_f32_32x32x16_bf16 v[32:47], v[66:69], v[78:81], v[32:47]
	s_waitcnt lgkmcnt(2)
	v_mfma_f32_32x32x16_bf16 v[16:31], v[66:69], v[82:85], v[16:31]
	s_waitcnt lgkmcnt(0)
	v_mfma_f32_32x32x16_bf16 v[0:15], v[66:69], v[86:89], v[0:15]
	ds_read_b64_tr_b16 v[66:67], v74 offset:59392
	ds_read_b64_tr_b16 v[68:69], v74 offset:61696
	ds_read_b64_tr_b16 v[70:71], v65 offset:10240
	ds_read_b64_tr_b16 v[72:73], v65 offset:11520
	ds_read_b64_tr_b16 v[78:79], v65 offset:10304
	ds_read_b64_tr_b16 v[80:81], v65 offset:11584
	ds_read_b64_tr_b16 v[82:83], v65 offset:10368
	ds_read_b64_tr_b16 v[84:85], v65 offset:11648
	ds_read_b64_tr_b16 v[86:87], v65 offset:10432
	ds_read_b64_tr_b16 v[88:89], v65 offset:11712
	s_waitcnt lgkmcnt(6)
	v_mfma_f32_32x32x16_bf16 v[48:63], v[66:69], v[70:73], v[48:63]
	s_waitcnt lgkmcnt(4)
	v_mfma_f32_32x32x16_bf16 v[32:47], v[66:69], v[78:81], v[32:47]
	s_waitcnt lgkmcnt(2)
	v_mfma_f32_32x32x16_bf16 v[16:31], v[66:69], v[82:85], v[16:31]
	s_waitcnt lgkmcnt(0)
	v_mfma_f32_32x32x16_bf16 v[0:15], v[66:69], v[86:89], v[0:15]
	ds_read_b64_tr_b16 v[66:67], v75 offset:59392
	ds_read_b64_tr_b16 v[68:69], v75 offset:61696
	ds_read_b64_tr_b16 v[70:71], v65 offset:15360
	ds_read_b64_tr_b16 v[72:73], v65 offset:16640
	ds_read_b64_tr_b16 v[78:79], v65 offset:15424
	ds_read_b64_tr_b16 v[80:81], v65 offset:16704
	ds_read_b64_tr_b16 v[82:83], v65 offset:15488
	ds_read_b64_tr_b16 v[84:85], v65 offset:16768
	ds_read_b64_tr_b16 v[86:87], v65 offset:15552
	ds_read_b64_tr_b16 v[88:89], v65 offset:16832
	s_waitcnt lgkmcnt(6)
	v_mfma_f32_32x32x16_bf16 v[48:63], v[66:69], v[70:73], v[48:63]
	v_add_u32_e32 v75, 0x9000, v74
	v_add_u32_e32 v74, 0xb400, v74
	s_waitcnt lgkmcnt(4)
	v_mfma_f32_32x32x16_bf16 v[32:47], v[66:69], v[78:81], v[32:47]
	s_waitcnt lgkmcnt(2)
	v_mfma_f32_32x32x16_bf16 v[16:31], v[66:69], v[82:85], v[16:31]
	s_waitcnt lgkmcnt(0)
; #define MFMA32(a, b, c) __builtin_amdgcn_mfma_f32_32x32x16_bf16((a), (b), (c), 0, 0, 0)
; __device__ __forceinline__ void ret_kv_item(const Params& p, LAS unsigned char* lds, int b, int h, int n) {
;     ...
; #pragma unroll
;     for (int ks = 0; ks < 8; ++ks) {
;         const int m0 = 16 * ks + 8 * hh + q4;
;         const bf16x8 af = tr_read2(Vl + m0 * RK_VS + (32 * wave + 16 * b16 + 4 * p4) * 2, 4 * RK_VS);
;         bf16x8 bfr[4];
; #pragma unroll
;         for (int dt = 0; dt < 4; ++dt) bfr[dt] = tr_read2(Kl + m0 * RK_KS + (32 * dt + 16 * b16 + 4 * p4) * 2, 4 * RK_KS);
;         if (ks & 1) __builtin_amdgcn_sched_barrier(0);
; #pragma unroll
;         for (int dt = 0; dt < 4; ++dt) acc[dt] = MFMA32(af, bfr[dt], acc[dt]);
;     }
;     float* kvp = KV + ((size_t)((b * 8 + h) * 32 + n)) * (256 * 128);
	v_mfma_f32_32x32x16_bf16 v[0:15], v[66:69], v[86:89], v[0:15]
	ds_read_b64_tr_b16 v[66:67], v77 offset:59392
	ds_read_b64_tr_b16 v[68:69], v77 offset:61696
	ds_read_b64_tr_b16 v[70:71], v65 offset:20480
	ds_read_b64_tr_b16 v[72:73], v65 offset:21760
	ds_read_b64_tr_b16 v[78:79], v65 offset:20544
	ds_read_b64_tr_b16 v[80:81], v65 offset:21824
	ds_read_b64_tr_b16 v[82:83], v65 offset:20608
	ds_read_b64_tr_b16 v[84:85], v65 offset:21888
	ds_read_b64_tr_b16 v[86:87], v65 offset:20672
	ds_read_b64_tr_b16 v[88:89], v65 offset:21952
	s_waitcnt lgkmcnt(6)
	v_mfma_f32_32x32x16_bf16 v[48:63], v[66:69], v[70:73], v[48:63]
	s_waitcnt lgkmcnt(4)
	v_mfma_f32_32x32x16_bf16 v[32:47], v[66:69], v[78:81], v[32:47]
	s_waitcnt lgkmcnt(2)
	v_mfma_f32_32x32x16_bf16 v[16:31], v[66:69], v[82:85], v[16:31]
	s_waitcnt lgkmcnt(0)
	v_mfma_f32_32x32x16_bf16 v[0:15], v[66:69], v[86:89], v[0:15]
	ds_read_b64_tr_b16 v[66:67], v90 offset:59392
	ds_read_b64_tr_b16 v[68:69], v90 offset:61696
	ds_read_b64_tr_b16 v[70:71], v65 offset:25600
	ds_read_b64_tr_b16 v[72:73], v65 offset:26880
	ds_read_b64_tr_b16 v[78:79], v65 offset:25664
	ds_read_b64_tr_b16 v[80:81], v65 offset:26944
	ds_read_b64_tr_b16 v[82:83], v65 offset:25728
	ds_read_b64_tr_b16 v[84:85], v65 offset:27008
	ds_read_b64_tr_b16 v[86:87], v65 offset:25792
	ds_read_b64_tr_b16 v[88:89], v65 offset:27072
	s_waitcnt lgkmcnt(6)
	v_mfma_f32_32x32x16_bf16 v[48:63], v[66:69], v[70:73], v[48:63]
	s_waitcnt lgkmcnt(4)
	v_mfma_f32_32x32x16_bf16 v[32:47], v[66:69], v[78:81], v[32:47]
	s_waitcnt lgkmcnt(2)
	v_mfma_f32_32x32x16_bf16 v[16:31], v[66:69], v[82:85], v[16:31]
	s_waitcnt lgkmcnt(0)
	v_mfma_f32_32x32x16_bf16 v[0:15], v[66:69], v[86:89], v[0:15]
	ds_read_b64_tr_b16 v[66:67], v75 offset:59392
	ds_read_b64_tr_b16 v[68:69], v75 offset:61696
	ds_read_b64_tr_b16 v[70:71], v65 offset:30720
	ds_read_b64_tr_b16 v[72:73], v65 offset:32000
	ds_read_b64_tr_b16 v[78:79], v65 offset:30784
	ds_read_b64_tr_b16 v[80:81], v65 offset:32064
	ds_read_b64_tr_b16 v[82:83], v65 offset:30848
	ds_read_b64_tr_b16 v[84:85], v65 offset:32128
	ds_read_b64_tr_b16 v[86:87], v65 offset:30912
	ds_read_b64_tr_b16 v[88:89], v65 offset:32192
	s_waitcnt lgkmcnt(6)
	v_mfma_f32_32x32x16_bf16 v[48:63], v[66:69], v[70:73], v[48:63]
	s_waitcnt lgkmcnt(4)
	v_mfma_f32_32x32x16_bf16 v[32:47], v[66:69], v[78:81], v[32:47]
	s_waitcnt lgkmcnt(2)
	v_mfma_f32_32x32x16_bf16 v[16:31], v[66:69], v[82:85], v[16:31]
	s_waitcnt lgkmcnt(0)
	v_mfma_f32_32x32x16_bf16 v[0:15], v[66:69], v[86:89], v[0:15]
	ds_read_b64_tr_b16 v[66:67], v74 offset:59392
	ds_read_b64_tr_b16 v[68:69], v74 offset:61696
	ds_read_b64_tr_b16 v[70:71], v65 offset:35840
	ds_read_b64_tr_b16 v[72:73], v65 offset:37120
	ds_read_b64_tr_b16 v[78:79], v65 offset:35904
	ds_read_b64_tr_b16 v[80:81], v65 offset:37184
	ds_read_b64_tr_b16 v[82:83], v65 offset:35968
	ds_read_b64_tr_b16 v[84:85], v65 offset:37248
	ds_read_b64_tr_b16 v[86:87], v65 offset:36032
	ds_read_b64_tr_b16 v[88:89], v65 offset:37312
	s_and_b32 s0, s4, 0xffffff00
	s_lshl_b32 s1, s13, 5
	s_or_b32 s0, s1, s0
	s_or_b32 s0, s0, s5
	s_ashr_i32 s1, s0, 31
	s_lshl_b64 s[0:1], s[0:1], 17
	s_add_u32 s0, s10, s0
	v_and_b32_e32 v65, 31, v76
	v_lshlrev_b32_e32 v64, 9, v64
	s_addc_u32 s1, s11, s1
	s_lshl_b32 s5, s12, 12
	v_or3_b32 v64, v64, s5, v65
	s_waitcnt lgkmcnt(6)
	v_mfma_f32_32x32x16_bf16 v[48:63], v[66:69], v[70:73], v[48:63]
	v_ashrrev_i32_e32 v65, 31, v64
	v_lshl_add_u64 v[64:65], v[64:65], 2, s[0:1]
	s_mov_b64 s[0:1], 0x12c00000
	s_add_i32 s4, s4, s20
	s_cmpk_gt_i32 s4, 0x1ff
	s_waitcnt lgkmcnt(4)
	v_mfma_f32_32x32x16_bf16 v[32:47], v[66:69], v[78:81], v[32:47]
	s_waitcnt lgkmcnt(2)
	v_mfma_f32_32x32x16_bf16 v[16:31], v[66:69], v[82:85], v[16:31]
	s_waitcnt lgkmcnt(0)
; __device__ __forceinline__ int crow(int reg, int h) { return (reg & 3) + 8 * (reg >> 2) + 4 * h; }
; __device__ __forceinline__ void ret_kv_item(const Params& p, LAS unsigned char* lds, int b, int h, int n) {
;     ...
;     float* kvp = KV + ((size_t)((b * 8 + h) * 32 + n)) * (256 * 128);
; #pragma unroll
;     for (int dt = 0; dt < 4; ++dt)
; #pragma unroll
;         for (int i = 0; i < 16; ++i) kvp[(32 * wave + crow(i, hh)) * 128 + 32 * dt + r] = acc[dt][i];
	v_mfma_f32_32x32x16_bf16 v[0:15], v[66:69], v[86:89], v[0:15]
	v_lshl_add_u64 v[66:67], v[64:65], 0, s[0:1]
	s_mov_b32 s0, 0x12c01000
	v_add_co_u32_e32 v68, vcc, s0, v64
	s_mov_b32 s0, 0x12c02000
	s_nop 0
	v_addc_co_u32_e32 v69, vcc, 0, v65, vcc
	v_add_co_u32_e32 v70, vcc, s0, v64
	s_mov_b32 s0, 0x12c03000
	s_nop 0
	v_addc_co_u32_e32 v71, vcc, 0, v65, vcc
	v_add_co_u32_e32 v64, vcc, s0, v64
	s_nop 1
	v_addc_co_u32_e32 v65, vcc, 0, v65, vcc
	global_store_dword v[68:69], v48, off offset:-4096
	global_store_dword v[66:67], v49, off offset:512
	global_store_dword v[66:67], v50, off offset:1024
	global_store_dword v[66:67], v51, off offset:1536
	global_store_dword v[68:69], v52, off
	global_store_dword v[68:69], v53, off offset:512
	global_store_dword v[68:69], v54, off offset:1024
	global_store_dword v[68:69], v55, off offset:1536
	global_store_dword v[64:65], v56, off offset:-4096
	global_store_dword v[70:71], v57, off offset:512
	global_store_dword v[70:71], v58, off offset:1024
	global_store_dword v[70:71], v59, off offset:1536
	global_store_dword v[64:65], v60, off
	global_store_dword v[64:65], v61, off offset:512
	global_store_dword v[64:65], v62, off offset:1024
	global_store_dword v[64:65], v63, off offset:1536
	global_store_dword v[66:67], v32, off offset:128
	global_store_dword v[66:67], v33, off offset:640
	global_store_dword v[66:67], v34, off offset:1152
	global_store_dword v[66:67], v35, off offset:1664
	global_store_dword v[68:69], v36, off offset:128
	global_store_dword v[68:69], v37, off offset:640
	global_store_dword v[68:69], v38, off offset:1152
	global_store_dword v[68:69], v39, off offset:1664
	global_store_dword v[70:71], v40, off offset:128
	global_store_dword v[70:71], v41, off offset:640
	global_store_dword v[70:71], v42, off offset:1152
	global_store_dword v[70:71], v43, off offset:1664
	global_store_dword v[64:65], v44, off offset:128
	global_store_dword v[64:65], v45, off offset:640
	global_store_dword v[64:65], v46, off offset:1152
	global_store_dword v[64:65], v47, off offset:1664
	global_store_dword v[66:67], v16, off offset:256
	global_store_dword v[66:67], v17, off offset:768
	global_store_dword v[66:67], v18, off offset:1280
	global_store_dword v[66:67], v19, off offset:1792
	global_store_dword v[68:69], v20, off offset:256
	global_store_dword v[68:69], v21, off offset:768
	global_store_dword v[68:69], v22, off offset:1280
	global_store_dword v[68:69], v23, off offset:1792
	global_store_dword v[70:71], v24, off offset:256
	global_store_dword v[70:71], v25, off offset:768
	global_store_dword v[70:71], v26, off offset:1280
	global_store_dword v[70:71], v27, off offset:1792
	global_store_dword v[64:65], v28, off offset:256
	global_store_dword v[64:65], v29, off offset:768
	global_store_dword v[64:65], v30, off offset:1280
	global_store_dword v[64:65], v31, off offset:1792
	global_store_dword v[66:67], v0, off offset:384
	global_store_dword v[66:67], v1, off offset:896
	global_store_dword v[66:67], v2, off offset:1408
	global_store_dword v[66:67], v3, off offset:1920
	global_store_dword v[68:69], v4, off offset:384
	global_store_dword v[68:69], v5, off offset:896
	global_store_dword v[68:69], v6, off offset:1408
	global_store_dword v[68:69], v7, off offset:1920
	global_store_dword v[70:71], v8, off offset:384
	global_store_dword v[70:71], v9, off offset:896
	global_store_dword v[70:71], v10, off offset:1408
	global_store_dword v[70:71], v11, off offset:1920
	global_store_dword v[64:65], v12, off offset:384
	global_store_dword v[64:65], v13, off offset:896
	global_store_dword v[64:65], v14, off offset:1408
	global_store_dword v[64:65], v15, off offset:1920
	s_cbranch_scc0 .LBB0_500

; #define LAS __attribute__((address_space(3)))
; __device__ __forceinline__ unsigned pk2(float lo, float hi) { f32x2 f = {lo, hi}; bf16x2_t b = __builtin_convertvector(f, bf16x2_t); return __builtin_bit_cast(unsigned, b); }
; __device__ __forceinline__ float siluf_(float x) { return x * sigmoidf_(x); }
; __device__ __forceinline__ float row_rstd(const LAS float* RS, int ord, int lrow) {
;     const float ssum = RS[ord * 256 + lrow] + RS[2048 + ord * 256 + lrow];
;     return 1.0f / sqrtf(ssum * (1.0f / D) + 1e-6f);
; }
;     __device__ __forceinline__ void operator()(const AccT& acc, const Unit& u, int wr, int wc, int fr, int fq) const {
;         const int row0 = u.pm * 256 + wr * 64 + fr, col0 = u.pn * 128 + wc * 32 + 8 * fq;
; #pragma unroll
;         for (int ai = 0; ai < 2; ++ai)
; #pragma unroll
;             for (int m = 0; m < 4; ++m) {
;                 const int row = row0 + ai * 128 + m * 16;
;                 const float rstd = row_rstd(RS, u.ord, wr * 64 + fr + ai * 128 + m * 16);
;                 bf16_t* rowp = H + (size_t)row * DFF + col0;
;                 float v[8];
; #pragma unroll
;                 for (int n = 0; n < 2; ++n)
; #pragma unroll
;                     for (int e = 0; e < 4; ++e) v[4 * n + e] = siluf_(acc[ai][0][m][n][e] * rstd) * (acc[ai][1][m][n][e] * rstd);
;                 u32x4 w; w.x = pk2(v[0], v[1]); w.y = pk2(v[2], v[3]); w.z = pk2(v[4], v[5]); w.w = pk2(v[6], v[7]);
;                 *(u32x4*)((char*)H + tiled_off(row, col0, DFF / 64)) = w;
;             }
;     }
.LBB0_822:
	v_lshl_add_u32 v144, s49, 10, v141
	v_add_u32_e32 v145, 0x2000, v144
	ds_read2_b32 v[134:135], v144 offset1:16
	ds_read2_b32 v[136:137], v145 offset1:16
	s_lshl_b32 s6, s50, 7
	s_or_b32 s6, s6, s39
	s_ashr_i32 s24, s6, 6
	v_lshl_add_u32 v143, s52, 8, v139
	s_waitcnt lgkmcnt(0)
	v_add_f32_e32 v134, v134, v136
	v_fmamk_f32 v134, v134, 0x3a000000, v236
	v_cmp_gt_f32_e32 vcc, s73, v134
	v_mul_f32_e32 v136, 0x4f800000, v134
	v_ashrrev_i32_e32 v132, 7, v143
	v_cndmask_b32_e32 v134, v134, v136, vcc
	v_rsq_f32_e32 v136, v134
	s_nop 0
	v_mul_lo_u32 v132, v132, s58
	s_ashr_i32 s25, s24, 31
	v_ashrrev_i32_e32 v133, 31, v132
	v_lshl_add_u64 v[132:133], v[132:133], 0, s[24:25]
	v_lshlrev_b64 v[132:133], 14, v[132:133]
	s_mov_b32 s88, 0xffda0d24
	s_mov_b32 s89, 0x3c7777d0
	s_mov_b32 s79, 0x30000
	s_mov_b32 s54, 0x40000
	v_mov_b32_e32 v134, v136
	v_pk_mul_f32 v[124:125], v[124:125], v[134:135] op_sel_hi:[1,0]
	v_pk_mul_f32 v[120:121], v[120:121], v[134:135] op_sel_hi:[1,0]
	v_mul_f32_e32 v136, 0xbfb8aa3b, v124
	v_exp_f32_e32 v136, v136
	v_pk_mul_f32 v[122:123], v[122:123], v[134:135] op_sel_hi:[1,0]
	v_pk_mul_f32 v[116:117], v[116:117], v[134:135] op_sel_hi:[1,0]
	v_pk_mul_f32 v[112:113], v[112:113], v[134:135] op_sel_hi:[1,0]
	v_add_f32_e32 v136, 1.0, v136
	v_rcp_f32_e32 v146, v136
	v_mul_f32_e32 v136, 0xbfb8aa3b, v125
	v_exp_f32_e32 v136, v136
	v_pk_mul_f32 v[114:115], v[114:115], v[134:135] op_sel_hi:[1,0]
	v_add_f32_e32 v136, 1.0, v136
	v_rcp_f32_e32 v147, v136
	s_nop 0
	v_pk_mul_f32 v[124:125], v[124:125], v[146:147]
	s_nop 0
	v_pk_mul_f32 v[120:121], v[120:121], v[124:125]
	v_pk_mul_f32 v[124:125], v[126:127], v[134:135] op_sel_hi:[1,0]
	s_nop 0
	v_mul_f32_e32 v126, 0xbfb8aa3b, v124
	v_mul_f32_e32 v127, 0xbfb8aa3b, v125
	v_exp_f32_e32 v126, v126
	v_exp_f32_e32 v127, v127
	v_add_f32_e32 v126, 1.0, v126
	v_add_f32_e32 v127, 1.0, v127
	v_rcp_f32_e32 v126, v126
	v_rcp_f32_e32 v127, v127
	s_nop 0
	v_pk_mul_f32 v[124:125], v[124:125], v[126:127]
	s_nop 0
	v_pk_mul_f32 v[122:123], v[122:123], v[124:125]
	v_mul_f32_e32 v124, 0xbfb8aa3b, v116
	v_mul_f32_e32 v125, 0xbfb8aa3b, v117
	v_exp_f32_e32 v124, v124
	v_exp_f32_e32 v125, v125
	v_add_f32_e32 v124, 1.0, v124
	v_add_f32_e32 v125, 1.0, v125
	v_rcp_f32_e32 v124, v124
	v_rcp_f32_e32 v125, v125
	s_nop 0
	v_pk_mul_f32 v[116:117], v[116:117], v[124:125]
	s_nop 0
	v_pk_mul_f32 v[112:113], v[112:113], v[116:117]
	v_pk_mul_f32 v[116:117], v[118:119], v[134:135] op_sel_hi:[1,0]
	s_nop 0
	v_mul_f32_e32 v118, 0xbfb8aa3b, v116
	v_mul_f32_e32 v119, 0xbfb8aa3b, v117
	v_exp_f32_e32 v118, v118
	v_exp_f32_e32 v119, v119
	v_add_f32_e32 v118, 1.0, v118
	v_add_f32_e32 v119, 1.0, v119
	v_rcp_f32_e32 v118, v118
	v_rcp_f32_e32 v119, v119
	s_nop 0
	v_pk_mul_f32 v[116:117], v[116:117], v[118:119]
	s_nop 0
	v_pk_mul_f32 v[114:115], v[114:115], v[116:117]
	v_cvt_pk_bf16_f32 v118, v112, v113
	v_lshlrev_b32_e32 v112, 6, v143
	v_cvt_pk_bf16_f32 v119, v114, v115
	v_and_or_b32 v114, v112, s87, v138
	v_lshlrev_b32_e32 v112, 2, v143
	v_and_b32_e32 v115, 32, v112
	v_bitop3_b32 v192, v114, s43, v115 bitop3:0xde
	v_lshl_add_u64 v[112:113], s[10:11], 0, v[132:133]
	v_cvt_pk_bf16_f32 v116, v120, v121
	v_cvt_pk_bf16_f32 v117, v122, v123
	v_lshl_add_u64 v[120:121], v[112:113], 0, v[192:193]
	global_store_dwordx4 v[120:121], v[116:119], off
	s_nop 1
	v_add_f32_e32 v116, v135, v137
	v_fmamk_f32 v116, v116, 0x3a000000, v236
	v_cmp_gt_f32_e32 vcc, s73, v116
	v_mul_f32_e32 v117, 0x4f800000, v116
	s_nop 0
	v_cndmask_b32_e32 v116, v116, v117, vcc
	v_rsq_f32_e32 v117, v116
	s_nop 0
	s_nop 0
	s_nop 0
	s_nop 1
	s_nop 1
	s_nop 0
	v_mov_b32_e32 v116, v117
	v_pk_mul_f32 v[108:109], v[108:109], v[116:117] op_sel_hi:[1,0]
	s_nop 0
	v_mul_f32_e32 v117, 0xbfb8aa3b, v108
	v_exp_f32_e32 v117, v117
	s_nop 0
	v_add_f32_e32 v117, 1.0, v117
	v_rcp_f32_e32 v118, v117
	v_mul_f32_e32 v117, 0xbfb8aa3b, v109
	v_exp_f32_e32 v117, v117
	s_nop 0
	v_add_f32_e32 v117, 1.0, v117
	v_rcp_f32_e32 v119, v117
	v_pk_mul_f32 v[104:105], v[104:105], v[116:117] op_sel_hi:[1,0]
	v_pk_mul_f32 v[106:107], v[106:107], v[116:117] op_sel_hi:[1,0]
	v_pk_mul_f32 v[100:101], v[100:101], v[116:117] op_sel_hi:[1,0]
	v_pk_mul_f32 v[108:109], v[108:109], v[118:119]
	v_pk_mul_f32 v[96:97], v[96:97], v[116:117] op_sel_hi:[1,0]
	v_pk_mul_f32 v[104:105], v[104:105], v[108:109]
	v_pk_mul_f32 v[108:109], v[110:111], v[116:117] op_sel_hi:[1,0]
	v_pk_mul_f32 v[98:99], v[98:99], v[116:117] op_sel_hi:[1,0]
	v_mul_f32_e32 v110, 0xbfb8aa3b, v108
	v_mul_f32_e32 v111, 0xbfb8aa3b, v109
	v_exp_f32_e32 v110, v110
	v_exp_f32_e32 v111, v111
	v_add_f32_e32 v110, 1.0, v110
	v_add_f32_e32 v111, 1.0, v111
	v_rcp_f32_e32 v110, v110
	v_rcp_f32_e32 v111, v111
	s_nop 0
	v_pk_mul_f32 v[108:109], v[108:109], v[110:111]
	s_nop 0
	v_pk_mul_f32 v[106:107], v[106:107], v[108:109]
	v_mul_f32_e32 v108, 0xbfb8aa3b, v100
	v_mul_f32_e32 v109, 0xbfb8aa3b, v101
	v_exp_f32_e32 v108, v108
	v_exp_f32_e32 v109, v109
	v_add_f32_e32 v108, 1.0, v108
	v_add_f32_e32 v109, 1.0, v109
	v_rcp_f32_e32 v108, v108
	v_rcp_f32_e32 v109, v109
	s_nop 0
	v_pk_mul_f32 v[100:101], v[100:101], v[108:109]
	s_nop 0
	v_pk_mul_f32 v[100:101], v[96:97], v[100:101]
	v_pk_mul_f32 v[96:97], v[102:103], v[116:117] op_sel_hi:[1,0]
	v_or_b32_e32 v108, 16, v143
	v_mul_f32_e32 v102, 0xbfb8aa3b, v96
	v_mul_f32_e32 v103, 0xbfb8aa3b, v97
	v_exp_f32_e32 v102, v102
	v_exp_f32_e32 v103, v103
	v_add_f32_e32 v102, 1.0, v102
	v_add_f32_e32 v103, 1.0, v103
	v_rcp_f32_e32 v102, v102
	v_rcp_f32_e32 v103, v103
	s_nop 0
	v_pk_mul_f32 v[96:97], v[96:97], v[102:103]
	s_nop 0
	v_pk_mul_f32 v[102:103], v[98:99], v[96:97]
	v_cvt_pk_bf16_f32 v98, v100, v101
	v_lshrrev_b32_e32 v100, 3, v108
	v_and_or_b32 v100, v100, 10, s42
	v_lshlrev_b32_e32 v100, 10, v100
	v_bitop3_b32 v192, v114, v100, v115 bitop3:0xde
	v_cvt_pk_bf16_f32 v96, v104, v105
	v_cvt_pk_bf16_f32 v97, v106, v107
	v_cvt_pk_bf16_f32 v99, v102, v103
	v_lshl_add_u64 v[100:101], v[112:113], 0, v[192:193]
	global_store_dwordx4 v[100:101], v[96:99], off
	ds_read2_b32 v[96:97], v144 offset0:32 offset1:48
	ds_read2_b32 v[98:99], v145 offset0:32 offset1:48
	s_waitcnt lgkmcnt(0)
; #define LAS __attribute__((address_space(3)))
; __device__ __forceinline__ unsigned pk2(float lo, float hi) { f32x2 f = {lo, hi}; bf16x2_t b = __builtin_convertvector(f, bf16x2_t); return __builtin_bit_cast(unsigned, b); }
; __device__ __forceinline__ float siluf_(float x) { return x * sigmoidf_(x); }
; __device__ __forceinline__ float row_rstd(const LAS float* RS, int ord, int lrow) {
;     const float ssum = RS[ord * 256 + lrow] + RS[2048 + ord * 256 + lrow];
;     return 1.0f / sqrtf(ssum * (1.0f / D) + 1e-6f);
; }
;     __device__ __forceinline__ void operator()(const AccT& acc, const Unit& u, int wr, int wc, int fr, int fq) const {
;         const int row0 = u.pm * 256 + wr * 64 + fr, col0 = u.pn * 128 + wc * 32 + 8 * fq;
; #pragma unroll
;         for (int ai = 0; ai < 2; ++ai)
; #pragma unroll
;             for (int m = 0; m < 4; ++m) {
;                 const int row = row0 + ai * 128 + m * 16;
;                 const float rstd = row_rstd(RS, u.ord, wr * 64 + fr + ai * 128 + m * 16);
;                 bf16_t* rowp = H + (size_t)row * DFF + col0;
;                 float v[8];
; #pragma unroll
;                 for (int n = 0; n < 2; ++n)
; #pragma unroll
;                     for (int e = 0; e < 4; ++e) v[4 * n + e] = siluf_(acc[ai][0][m][n][e] * rstd) * (acc[ai][1][m][n][e] * rstd);
;                 u32x4 w; w.x = pk2(v[0], v[1]); w.y = pk2(v[2], v[3]); w.z = pk2(v[4], v[5]); w.w = pk2(v[6], v[7]);
;                 *(u32x4*)((char*)H + tiled_off(row, col0, DFF / 64)) = w;
;             }
;     }
	v_add_f32_e32 v96, v96, v98
	v_fmamk_f32 v96, v96, 0x3a000000, v236
	v_cmp_gt_f32_e32 vcc, s73, v96
	v_mul_f32_e32 v98, 0x4f800000, v96
	s_nop 0
	v_cndmask_b32_e32 v96, v96, v98, vcc
	v_rsq_f32_e32 v98, v96
	s_nop 0
	s_nop 0
	s_nop 0
	s_nop 1
	s_nop 1
	s_nop 0
	v_mov_b32_e32 v96, v98
	v_pk_mul_f32 v[92:93], v[92:93], v[96:97] op_sel_hi:[1,0]
	v_pk_mul_f32 v[88:89], v[88:89], v[96:97] op_sel_hi:[1,0]
	v_mul_f32_e32 v98, 0xbfb8aa3b, v92
	v_exp_f32_e32 v98, v98
	v_pk_mul_f32 v[90:91], v[90:91], v[96:97] op_sel_hi:[1,0]
	v_pk_mul_f32 v[84:85], v[84:85], v[96:97] op_sel_hi:[1,0]
	v_pk_mul_f32 v[80:81], v[80:81], v[96:97] op_sel_hi:[1,0]
	v_add_f32_e32 v98, 1.0, v98
	v_rcp_f32_e32 v100, v98
	v_mul_f32_e32 v98, 0xbfb8aa3b, v93
	v_exp_f32_e32 v98, v98
	v_pk_mul_f32 v[82:83], v[82:83], v[96:97] op_sel_hi:[1,0]
	v_add_f32_e32 v98, 1.0, v98
	v_rcp_f32_e32 v101, v98
	s_nop 0
	v_pk_mul_f32 v[92:93], v[92:93], v[100:101]
	s_nop 0
	v_pk_mul_f32 v[88:89], v[88:89], v[92:93]
	v_pk_mul_f32 v[92:93], v[94:95], v[96:97] op_sel_hi:[1,0]
	s_nop 0
	v_mul_f32_e32 v94, 0xbfb8aa3b, v92
	v_mul_f32_e32 v95, 0xbfb8aa3b, v93
	v_exp_f32_e32 v94, v94
	v_exp_f32_e32 v95, v95
	v_add_f32_e32 v94, 1.0, v94
	v_add_f32_e32 v95, 1.0, v95
	v_rcp_f32_e32 v94, v94
	v_rcp_f32_e32 v95, v95
	s_nop 0
	v_pk_mul_f32 v[92:93], v[92:93], v[94:95]
	s_nop 0
	v_pk_mul_f32 v[90:91], v[90:91], v[92:93]
	v_mul_f32_e32 v92, 0xbfb8aa3b, v84
	v_mul_f32_e32 v93, 0xbfb8aa3b, v85
	v_exp_f32_e32 v92, v92
	v_exp_f32_e32 v93, v93
	v_add_f32_e32 v92, 1.0, v92
	v_add_f32_e32 v93, 1.0, v93
	v_rcp_f32_e32 v92, v92
	v_rcp_f32_e32 v93, v93
	s_nop 0
	v_pk_mul_f32 v[84:85], v[84:85], v[92:93]
	s_nop 0
	v_pk_mul_f32 v[84:85], v[80:81], v[84:85]
	v_pk_mul_f32 v[80:81], v[86:87], v[96:97] op_sel_hi:[1,0]
	v_or_b32_e32 v92, 32, v143
	v_mul_f32_e32 v86, 0xbfb8aa3b, v80
	v_mul_f32_e32 v87, 0xbfb8aa3b, v81
	v_exp_f32_e32 v86, v86
	v_exp_f32_e32 v87, v87
	v_add_f32_e32 v86, 1.0, v86
	v_add_f32_e32 v87, 1.0, v87
	v_rcp_f32_e32 v86, v86
	v_rcp_f32_e32 v87, v87
	s_nop 0
	v_pk_mul_f32 v[80:81], v[80:81], v[86:87]
	s_nop 0
	v_pk_mul_f32 v[86:87], v[82:83], v[80:81]
	v_cvt_pk_bf16_f32 v82, v84, v85
	v_lshrrev_b32_e32 v84, 3, v92
	v_and_or_b32 v84, v84, 12, s42
	v_lshlrev_b32_e32 v84, 10, v84
	v_bitop3_b32 v192, v114, v84, v115 bitop3:0xde
	v_cvt_pk_bf16_f32 v80, v88, v89
	v_cvt_pk_bf16_f32 v81, v90, v91
	v_cvt_pk_bf16_f32 v83, v86, v87
	v_lshl_add_u64 v[84:85], v[112:113], 0, v[192:193]
	global_store_dwordx4 v[84:85], v[80:83], off
	s_nop 1
	v_add_f32_e32 v80, v97, v99
	v_fmamk_f32 v80, v80, 0x3a000000, v236
	v_cmp_gt_f32_e32 vcc, s73, v80
	v_mul_f32_e32 v81, 0x4f800000, v80
	s_nop 0
	v_cndmask_b32_e32 v80, v80, v81, vcc
	v_rsq_f32_e32 v81, v80
	s_nop 0
	s_nop 0
	s_nop 0
	s_nop 1
	s_nop 1
	s_nop 0
	v_mov_b32_e32 v80, v81
	v_pk_mul_f32 v[76:77], v[76:77], v[80:81] op_sel_hi:[1,0]
	s_nop 0
	v_mul_f32_e32 v81, 0xbfb8aa3b, v76
	v_exp_f32_e32 v81, v81
	s_nop 0
	v_add_f32_e32 v81, 1.0, v81
	v_rcp_f32_e32 v82, v81
	v_mul_f32_e32 v81, 0xbfb8aa3b, v77
	v_exp_f32_e32 v81, v81
	s_nop 0
	v_add_f32_e32 v81, 1.0, v81
	v_rcp_f32_e32 v83, v81
	v_pk_mul_f32 v[72:73], v[72:73], v[80:81] op_sel_hi:[1,0]
	v_pk_mul_f32 v[74:75], v[74:75], v[80:81] op_sel_hi:[1,0]
	v_pk_mul_f32 v[68:69], v[68:69], v[80:81] op_sel_hi:[1,0]
	v_pk_mul_f32 v[76:77], v[76:77], v[82:83]
	v_pk_mul_f32 v[64:65], v[64:65], v[80:81] op_sel_hi:[1,0]
	v_pk_mul_f32 v[72:73], v[72:73], v[76:77]
	v_pk_mul_f32 v[76:77], v[78:79], v[80:81] op_sel_hi:[1,0]
	v_pk_mul_f32 v[66:67], v[66:67], v[80:81] op_sel_hi:[1,0]
	v_mul_f32_e32 v78, 0xbfb8aa3b, v76
	v_mul_f32_e32 v79, 0xbfb8aa3b, v77
	v_exp_f32_e32 v78, v78
	v_exp_f32_e32 v79, v79
	v_add_f32_e32 v78, 1.0, v78
	v_add_f32_e32 v79, 1.0, v79
	v_rcp_f32_e32 v78, v78
	v_rcp_f32_e32 v79, v79
	s_nop 0
	v_pk_mul_f32 v[76:77], v[76:77], v[78:79]
	s_nop 0
	v_pk_mul_f32 v[74:75], v[74:75], v[76:77]
	v_mul_f32_e32 v76, 0xbfb8aa3b, v68
	v_mul_f32_e32 v77, 0xbfb8aa3b, v69
	v_exp_f32_e32 v76, v76
	v_exp_f32_e32 v77, v77
	v_add_f32_e32 v76, 1.0, v76
	v_add_f32_e32 v77, 1.0, v77
	v_rcp_f32_e32 v76, v76
	v_rcp_f32_e32 v77, v77
	s_nop 0
	v_pk_mul_f32 v[68:69], v[68:69], v[76:77]
	s_nop 0
	v_pk_mul_f32 v[68:69], v[64:65], v[68:69]
	v_pk_mul_f32 v[64:65], v[70:71], v[80:81] op_sel_hi:[1,0]
	v_or_b32_e32 v76, 48, v143
	v_mul_f32_e32 v70, 0xbfb8aa3b, v64
	v_mul_f32_e32 v71, 0xbfb8aa3b, v65
	v_exp_f32_e32 v70, v70
	v_exp_f32_e32 v71, v71
	v_add_f32_e32 v70, 1.0, v70
	v_add_f32_e32 v71, 1.0, v71
	v_rcp_f32_e32 v70, v70
	v_rcp_f32_e32 v71, v71
	s_nop 0
	v_pk_mul_f32 v[64:65], v[64:65], v[70:71]
	s_nop 0
	v_pk_mul_f32 v[70:71], v[66:67], v[64:65]
	v_cvt_pk_bf16_f32 v66, v68, v69
	v_lshrrev_b32_e32 v68, 3, v76
	v_and_or_b32 v68, v68, 14, s42
	v_lshlrev_b32_e32 v68, 10, v68
	v_bitop3_b32 v192, v114, v68, v115 bitop3:0xde
	v_cvt_pk_bf16_f32 v64, v72, v73
	v_cvt_pk_bf16_f32 v65, v74, v75
	v_cvt_pk_bf16_f32 v67, v70, v71
	v_lshl_add_u64 v[68:69], v[112:113], 0, v[192:193]
	global_store_dwordx4 v[68:69], v[64:67], off
	ds_read2_b32 v[66:67], v144 offset0:128 offset1:144
	ds_read2_b32 v[68:69], v145 offset0:128 offset1:144
	v_add_u32_e32 v72, 0x80, v143
	v_ashrrev_i32_e32 v64, 7, v72
	v_mul_lo_u32 v64, v64, s58
	v_ashrrev_i32_e32 v65, 31, v64
	s_waitcnt lgkmcnt(0)
; #define LAS __attribute__((address_space(3)))
; __device__ __forceinline__ unsigned pk2(float lo, float hi) { f32x2 f = {lo, hi}; bf16x2_t b = __builtin_convertvector(f, bf16x2_t); return __builtin_bit_cast(unsigned, b); }
; __device__ __forceinline__ float siluf_(float x) { return x * sigmoidf_(x); }
; __device__ __forceinline__ float row_rstd(const LAS float* RS, int ord, int lrow) {
;     const float ssum = RS[ord * 256 + lrow] + RS[2048 + ord * 256 + lrow];
;     return 1.0f / sqrtf(ssum * (1.0f / D) + 1e-6f);
;     __device__ __forceinline__ void operator()(const AccT& acc, const Unit& u, int wr, int wc, int fr, int fq) const {
;     ...
;                 const float rstd = row_rstd(RS, u.ord, wr * 64 + fr + ai * 128 + m * 16);
;                 bf16_t* rowp = H + (size_t)row * DFF + col0;
;                 float v[8];
; #pragma unroll
;                 for (int n = 0; n < 2; ++n)
; #pragma unroll
;                     for (int e = 0; e < 4; ++e) v[4 * n + e] = siluf_(acc[ai][0][m][n][e] * rstd) * (acc[ai][1][m][n][e] * rstd);
;                 u32x4 w; w.x = pk2(v[0], v[1]); w.y = pk2(v[2], v[3]); w.z = pk2(v[4], v[5]); w.w = pk2(v[6], v[7]);
;                 *(u32x4*)((char*)H + tiled_off(row, col0, DFF / 64)) = w;
	v_add_f32_e32 v66, v66, v68
	v_fmamk_f32 v66, v66, 0x3a000000, v236
	v_cmp_gt_f32_e32 vcc, s73, v66
	v_mul_f32_e32 v68, 0x4f800000, v66
	v_lshl_add_u64 v[64:65], v[64:65], 0, s[24:25]
	v_cndmask_b32_e32 v66, v66, v68, vcc
	v_rsq_f32_e32 v68, v66
	s_nop 0
	v_lshlrev_b64 v[64:65], 14, v[64:65]
	s_nop 0
	s_nop 1
	s_nop 1
	s_nop 0
	v_mov_b32_e32 v66, v68
	v_pk_mul_f32 v[60:61], v[60:61], v[66:67] op_sel_hi:[1,0]
	v_pk_mul_f32 v[56:57], v[56:57], v[66:67] op_sel_hi:[1,0]
	v_mul_f32_e32 v68, 0xbfb8aa3b, v60
	v_exp_f32_e32 v68, v68
	v_pk_mul_f32 v[58:59], v[58:59], v[66:67] op_sel_hi:[1,0]
	v_pk_mul_f32 v[52:53], v[52:53], v[66:67] op_sel_hi:[1,0]
	v_pk_mul_f32 v[48:49], v[48:49], v[66:67] op_sel_hi:[1,0]
	v_add_f32_e32 v68, 1.0, v68
	v_rcp_f32_e32 v70, v68
	v_mul_f32_e32 v68, 0xbfb8aa3b, v61
	v_exp_f32_e32 v68, v68
	v_pk_mul_f32 v[50:51], v[50:51], v[66:67] op_sel_hi:[1,0]
	v_add_f32_e32 v68, 1.0, v68
	v_rcp_f32_e32 v71, v68
	s_nop 0
	v_pk_mul_f32 v[60:61], v[60:61], v[70:71]
	s_nop 0
	v_pk_mul_f32 v[56:57], v[56:57], v[60:61]
	v_pk_mul_f32 v[60:61], v[62:63], v[66:67] op_sel_hi:[1,0]
	s_nop 0
	v_mul_f32_e32 v62, 0xbfb8aa3b, v60
	v_mul_f32_e32 v63, 0xbfb8aa3b, v61
	v_exp_f32_e32 v62, v62
	v_exp_f32_e32 v63, v63
	v_add_f32_e32 v62, 1.0, v62
	v_add_f32_e32 v63, 1.0, v63
	v_rcp_f32_e32 v62, v62
	v_rcp_f32_e32 v63, v63
	s_nop 0
	v_pk_mul_f32 v[60:61], v[60:61], v[62:63]
	s_nop 0
	v_pk_mul_f32 v[58:59], v[58:59], v[60:61]
	v_mul_f32_e32 v60, 0xbfb8aa3b, v52
	v_mul_f32_e32 v61, 0xbfb8aa3b, v53
	v_exp_f32_e32 v60, v60
	v_exp_f32_e32 v61, v61
	v_add_f32_e32 v60, 1.0, v60
	v_add_f32_e32 v61, 1.0, v61
	v_rcp_f32_e32 v60, v60
	v_rcp_f32_e32 v61, v61
	s_nop 0
	v_pk_mul_f32 v[52:53], v[52:53], v[60:61]
	s_nop 0
	v_pk_mul_f32 v[48:49], v[48:49], v[52:53]
	v_pk_mul_f32 v[52:53], v[54:55], v[66:67] op_sel_hi:[1,0]
	s_nop 0
	v_mul_f32_e32 v54, 0xbfb8aa3b, v52
	v_mul_f32_e32 v55, 0xbfb8aa3b, v53
	v_exp_f32_e32 v54, v54
	v_exp_f32_e32 v55, v55
	v_add_f32_e32 v54, 1.0, v54
	v_add_f32_e32 v55, 1.0, v55
	v_rcp_f32_e32 v54, v54
	v_rcp_f32_e32 v55, v55
	s_nop 0
	v_pk_mul_f32 v[52:53], v[52:53], v[54:55]
	s_nop 0
	v_pk_mul_f32 v[50:51], v[50:51], v[52:53]
	v_cvt_pk_bf16_f32 v54, v48, v49
	v_lshlrev_b32_e32 v48, 6, v72
	v_cvt_pk_bf16_f32 v55, v50, v51
	v_and_or_b32 v50, v48, s87, v138
	v_lshlrev_b32_e32 v48, 2, v72
	v_and_b32_e32 v51, 32, v48
	v_bitop3_b32 v192, v50, s43, v51 bitop3:0xde
	v_lshl_add_u64 v[48:49], s[10:11], 0, v[64:65]
	v_cvt_pk_bf16_f32 v52, v56, v57
	v_cvt_pk_bf16_f32 v53, v58, v59
	v_lshl_add_u64 v[56:57], v[48:49], 0, v[192:193]
	global_store_dwordx4 v[56:57], v[52:55], off
	s_nop 1
	v_add_f32_e32 v52, v67, v69
	v_fmamk_f32 v52, v52, 0x3a000000, v236
	v_cmp_gt_f32_e32 vcc, s73, v52
	v_mul_f32_e32 v53, 0x4f800000, v52
	s_nop 0
	v_cndmask_b32_e32 v52, v52, v53, vcc
	v_rsq_f32_e32 v53, v52
	s_nop 0
	s_nop 0
	s_nop 0
	s_nop 1
	s_nop 1
	s_nop 0
	v_mov_b32_e32 v52, v53
	v_pk_mul_f32 v[44:45], v[44:45], v[52:53] op_sel_hi:[1,0]
	s_nop 0
	v_mul_f32_e32 v53, 0xbfb8aa3b, v44
	v_exp_f32_e32 v53, v53
	s_nop 0
	v_add_f32_e32 v53, 1.0, v53
	v_rcp_f32_e32 v54, v53
	v_mul_f32_e32 v53, 0xbfb8aa3b, v45
	v_exp_f32_e32 v53, v53
	s_nop 0
	v_add_f32_e32 v53, 1.0, v53
	v_rcp_f32_e32 v55, v53
	v_pk_mul_f32 v[40:41], v[40:41], v[52:53] op_sel_hi:[1,0]
	v_pk_mul_f32 v[42:43], v[42:43], v[52:53] op_sel_hi:[1,0]
	v_pk_mul_f32 v[36:37], v[36:37], v[52:53] op_sel_hi:[1,0]
	v_pk_mul_f32 v[44:45], v[44:45], v[54:55]
	v_pk_mul_f32 v[32:33], v[32:33], v[52:53] op_sel_hi:[1,0]
	v_pk_mul_f32 v[40:41], v[40:41], v[44:45]
	v_pk_mul_f32 v[44:45], v[46:47], v[52:53] op_sel_hi:[1,0]
	v_pk_mul_f32 v[34:35], v[34:35], v[52:53] op_sel_hi:[1,0]
	v_mul_f32_e32 v46, 0xbfb8aa3b, v44
	v_mul_f32_e32 v47, 0xbfb8aa3b, v45
	v_exp_f32_e32 v46, v46
	v_exp_f32_e32 v47, v47
	v_add_f32_e32 v46, 1.0, v46
	v_add_f32_e32 v47, 1.0, v47
	v_rcp_f32_e32 v46, v46
	v_rcp_f32_e32 v47, v47
	s_nop 0
	v_pk_mul_f32 v[44:45], v[44:45], v[46:47]
	s_nop 0
	v_pk_mul_f32 v[42:43], v[42:43], v[44:45]
	v_mul_f32_e32 v44, 0xbfb8aa3b, v36
	v_mul_f32_e32 v45, 0xbfb8aa3b, v37
	v_exp_f32_e32 v44, v44
	v_exp_f32_e32 v45, v45
	v_add_f32_e32 v44, 1.0, v44
	v_add_f32_e32 v45, 1.0, v45
	v_rcp_f32_e32 v44, v44
	v_rcp_f32_e32 v45, v45
	s_nop 0
	v_pk_mul_f32 v[36:37], v[36:37], v[44:45]
	s_nop 0
	v_pk_mul_f32 v[36:37], v[32:33], v[36:37]
	v_pk_mul_f32 v[32:33], v[38:39], v[52:53] op_sel_hi:[1,0]
	v_add_u32_e32 v44, 0x90, v143
	v_mul_f32_e32 v38, 0xbfb8aa3b, v32
	v_mul_f32_e32 v39, 0xbfb8aa3b, v33
	v_exp_f32_e32 v38, v38
	v_exp_f32_e32 v39, v39
	v_add_f32_e32 v38, 1.0, v38
	v_add_f32_e32 v39, 1.0, v39
	v_rcp_f32_e32 v38, v38
	v_rcp_f32_e32 v39, v39
	s_nop 0
	v_pk_mul_f32 v[32:33], v[32:33], v[38:39]
	s_nop 0
	v_pk_mul_f32 v[38:39], v[34:35], v[32:33]
	v_cvt_pk_bf16_f32 v34, v36, v37
	v_lshrrev_b32_e32 v36, 3, v44
	v_and_or_b32 v36, v36, 14, s42
	v_lshlrev_b32_e32 v36, 10, v36
	v_bitop3_b32 v192, v50, v36, v51 bitop3:0xde
	v_cvt_pk_bf16_f32 v32, v40, v41
	v_cvt_pk_bf16_f32 v33, v42, v43
	v_cvt_pk_bf16_f32 v35, v38, v39
	v_lshl_add_u64 v[36:37], v[48:49], 0, v[192:193]
	global_store_dwordx4 v[36:37], v[32:35], off
	ds_read2_b32 v[32:33], v144 offset0:160 offset1:176
	ds_read2_b32 v[34:35], v145 offset0:160 offset1:176
	s_waitcnt lgkmcnt(0)
; #define LAS __attribute__((address_space(3)))
; __device__ __forceinline__ unsigned pk2(float lo, float hi) { f32x2 f = {lo, hi}; bf16x2_t b = __builtin_convertvector(f, bf16x2_t); return __builtin_bit_cast(unsigned, b); }
; __device__ __forceinline__ float siluf_(float x) { return x * sigmoidf_(x); }
; __device__ __forceinline__ float row_rstd(const LAS float* RS, int ord, int lrow) {
;     const float ssum = RS[ord * 256 + lrow] + RS[2048 + ord * 256 + lrow];
;     return 1.0f / sqrtf(ssum * (1.0f / D) + 1e-6f);
;     __device__ __forceinline__ void operator()(const AccT& acc, const Unit& u, int wr, int wc, int fr, int fq) const {
;     ...
;                 const float rstd = row_rstd(RS, u.ord, wr * 64 + fr + ai * 128 + m * 16);
;                 bf16_t* rowp = H + (size_t)row * DFF + col0;
;                 float v[8];
; #pragma unroll
;                 for (int n = 0; n < 2; ++n)
; #pragma unroll
;                     for (int e = 0; e < 4; ++e) v[4 * n + e] = siluf_(acc[ai][0][m][n][e] * rstd) * (acc[ai][1][m][n][e] * rstd);
;                 u32x4 w; w.x = pk2(v[0], v[1]); w.y = pk2(v[2], v[3]); w.z = pk2(v[4], v[5]); w.w = pk2(v[6], v[7]);
;                 *(u32x4*)((char*)H + tiled_off(row, col0, DFF / 64)) = w;
	v_add_f32_e32 v32, v32, v34
	v_fmamk_f32 v32, v32, 0x3a000000, v236
	v_cmp_gt_f32_e32 vcc, s73, v32
	v_mul_f32_e32 v34, 0x4f800000, v32
	s_nop 0
	v_cndmask_b32_e32 v32, v32, v34, vcc
	v_rsq_f32_e32 v34, v32
	s_nop 0
	s_nop 0
	s_nop 0
	s_nop 1
	s_nop 1
	s_nop 0
	v_mov_b32_e32 v32, v34
	v_pk_mul_f32 v[28:29], v[28:29], v[32:33] op_sel_hi:[1,0]
	v_pk_mul_f32 v[24:25], v[24:25], v[32:33] op_sel_hi:[1,0]
	v_mul_f32_e32 v34, 0xbfb8aa3b, v28
	v_exp_f32_e32 v34, v34
	v_pk_mul_f32 v[26:27], v[26:27], v[32:33] op_sel_hi:[1,0]
	v_pk_mul_f32 v[20:21], v[20:21], v[32:33] op_sel_hi:[1,0]
	v_pk_mul_f32 v[16:17], v[16:17], v[32:33] op_sel_hi:[1,0]
	v_add_f32_e32 v34, 1.0, v34
	v_rcp_f32_e32 v36, v34
	v_mul_f32_e32 v34, 0xbfb8aa3b, v29
	v_exp_f32_e32 v34, v34
	v_pk_mul_f32 v[18:19], v[18:19], v[32:33] op_sel_hi:[1,0]
	v_add_f32_e32 v34, 1.0, v34
	v_rcp_f32_e32 v37, v34
	s_nop 0
	v_pk_mul_f32 v[28:29], v[28:29], v[36:37]
	s_nop 0
	v_pk_mul_f32 v[24:25], v[24:25], v[28:29]
	v_pk_mul_f32 v[28:29], v[30:31], v[32:33] op_sel_hi:[1,0]
	s_nop 0
	v_mul_f32_e32 v30, 0xbfb8aa3b, v28
	v_mul_f32_e32 v31, 0xbfb8aa3b, v29
	v_exp_f32_e32 v30, v30
	v_exp_f32_e32 v31, v31
	v_add_f32_e32 v30, 1.0, v30
	v_add_f32_e32 v31, 1.0, v31
	v_rcp_f32_e32 v30, v30
	v_rcp_f32_e32 v31, v31
	s_nop 0
	v_pk_mul_f32 v[28:29], v[28:29], v[30:31]
	s_nop 0
	v_pk_mul_f32 v[26:27], v[26:27], v[28:29]
	v_mul_f32_e32 v28, 0xbfb8aa3b, v20
	v_mul_f32_e32 v29, 0xbfb8aa3b, v21
	v_exp_f32_e32 v28, v28
	v_exp_f32_e32 v29, v29
	v_add_f32_e32 v28, 1.0, v28
	v_add_f32_e32 v29, 1.0, v29
	v_rcp_f32_e32 v28, v28
	v_rcp_f32_e32 v29, v29
	s_nop 0
	v_pk_mul_f32 v[20:21], v[20:21], v[28:29]
	s_nop 0
	v_pk_mul_f32 v[20:21], v[16:17], v[20:21]
	v_pk_mul_f32 v[16:17], v[22:23], v[32:33] op_sel_hi:[1,0]
	v_add_u32_e32 v28, 0xa0, v143
	v_mul_f32_e32 v22, 0xbfb8aa3b, v16
	v_mul_f32_e32 v23, 0xbfb8aa3b, v17
	v_exp_f32_e32 v22, v22
	v_exp_f32_e32 v23, v23
	v_add_f32_e32 v22, 1.0, v22
	v_add_f32_e32 v23, 1.0, v23
	v_rcp_f32_e32 v22, v22
	v_rcp_f32_e32 v23, v23
	s_nop 0
	v_pk_mul_f32 v[16:17], v[16:17], v[22:23]
	s_nop 0
	v_pk_mul_f32 v[22:23], v[18:19], v[16:17]
	v_cvt_pk_bf16_f32 v18, v20, v21
	v_lshrrev_b32_e32 v20, 3, v28
	v_and_or_b32 v20, v20, 14, s42
	v_lshlrev_b32_e32 v20, 10, v20
	v_bitop3_b32 v192, v50, v20, v51 bitop3:0xde
	v_cvt_pk_bf16_f32 v16, v24, v25
	v_cvt_pk_bf16_f32 v17, v26, v27
	v_cvt_pk_bf16_f32 v19, v22, v23
	v_lshl_add_u64 v[20:21], v[48:49], 0, v[192:193]
	global_store_dwordx4 v[20:21], v[16:19], off
	s_nop 1
	v_add_f32_e32 v16, v33, v35
	v_fmamk_f32 v16, v16, 0x3a000000, v236
	v_cmp_gt_f32_e32 vcc, s73, v16
	v_mul_f32_e32 v17, 0x4f800000, v16
	s_nop 0
	v_cndmask_b32_e32 v16, v16, v17, vcc
	v_rsq_f32_e32 v17, v16
	s_nop 0
	s_nop 0
	s_nop 0
	s_nop 1
	s_nop 1
	s_mov_b64 s[6:7], -1
	v_mov_b32_e32 v16, v17
	v_pk_mul_f32 v[12:13], v[12:13], v[16:17] op_sel_hi:[1,0]
	s_andn2_b64 vcc, exec, s[0:1]
	v_mul_f32_e32 v17, 0xbfb8aa3b, v12
	v_exp_f32_e32 v17, v17
	s_nop 0
	v_add_f32_e32 v17, 1.0, v17
	v_rcp_f32_e32 v18, v17
	v_mul_f32_e32 v17, 0xbfb8aa3b, v13
	v_exp_f32_e32 v17, v17
	s_nop 0
	v_add_f32_e32 v17, 1.0, v17
	v_rcp_f32_e32 v19, v17
	v_pk_mul_f32 v[8:9], v[8:9], v[16:17] op_sel_hi:[1,0]
	v_pk_mul_f32 v[10:11], v[10:11], v[16:17] op_sel_hi:[1,0]
	v_pk_mul_f32 v[4:5], v[4:5], v[16:17] op_sel_hi:[1,0]
	v_pk_mul_f32 v[12:13], v[12:13], v[18:19]
	v_pk_mul_f32 v[0:1], v[0:1], v[16:17] op_sel_hi:[1,0]
	v_pk_mul_f32 v[8:9], v[8:9], v[12:13]
	v_pk_mul_f32 v[12:13], v[14:15], v[16:17] op_sel_hi:[1,0]
	v_pk_mul_f32 v[2:3], v[2:3], v[16:17] op_sel_hi:[1,0]
	v_mul_f32_e32 v14, 0xbfb8aa3b, v12
	v_mul_f32_e32 v15, 0xbfb8aa3b, v13
	v_exp_f32_e32 v14, v14
	v_exp_f32_e32 v15, v15
	v_add_f32_e32 v14, 1.0, v14
	v_add_f32_e32 v15, 1.0, v15
	v_rcp_f32_e32 v14, v14
	v_rcp_f32_e32 v15, v15
	s_nop 0
	v_pk_mul_f32 v[12:13], v[12:13], v[14:15]
	s_nop 0
	v_pk_mul_f32 v[10:11], v[10:11], v[12:13]
	v_mul_f32_e32 v12, 0xbfb8aa3b, v4
	v_mul_f32_e32 v13, 0xbfb8aa3b, v5
	v_exp_f32_e32 v12, v12
	v_exp_f32_e32 v13, v13
	v_add_f32_e32 v12, 1.0, v12
	v_add_f32_e32 v13, 1.0, v13
	v_rcp_f32_e32 v12, v12
	v_rcp_f32_e32 v13, v13
	s_nop 0
	v_pk_mul_f32 v[4:5], v[4:5], v[12:13]
	s_nop 0
	v_pk_mul_f32 v[4:5], v[0:1], v[4:5]
	v_pk_mul_f32 v[0:1], v[6:7], v[16:17] op_sel_hi:[1,0]
	v_add_u32_e32 v12, 0xb0, v143
	v_mul_f32_e32 v6, 0xbfb8aa3b, v0
	v_mul_f32_e32 v7, 0xbfb8aa3b, v1
	v_exp_f32_e32 v6, v6
	v_exp_f32_e32 v7, v7
	v_add_f32_e32 v6, 1.0, v6
	v_add_f32_e32 v7, 1.0, v7
	v_rcp_f32_e32 v6, v6
	v_rcp_f32_e32 v7, v7
	s_nop 0
	v_pk_mul_f32 v[0:1], v[0:1], v[6:7]
	s_nop 0
	v_pk_mul_f32 v[6:7], v[2:3], v[0:1]
	v_cvt_pk_bf16_f32 v2, v4, v5
	v_lshrrev_b32_e32 v4, 3, v12
	v_and_or_b32 v4, v4, 14, s42
	v_lshlrev_b32_e32 v4, 10, v4
	v_bitop3_b32 v192, v50, v4, v51 bitop3:0xde
	v_cvt_pk_bf16_f32 v0, v8, v9
	v_cvt_pk_bf16_f32 v1, v10, v11
	v_cvt_pk_bf16_f32 v3, v6, v7
	v_lshl_add_u64 v[4:5], v[48:49], 0, v[192:193]
	global_store_dwordx4 v[4:5], v[0:3], off
	s_cbranch_vccnz .LBB0_815
	s_andn2_b64 vcc, exec, s[8:9]
	s_cbranch_vccnz .LBB0_814
	s_barrier
	s_branch .LBB0_814

; #define PHASE_ENV unsigned char* ws = opq_ptr(p.ws); const int G = opq_int((int)gridDim.x), ngw = G * 8; (void)ws; (void)ngw
; template <bool F32OUT>
; __device__ __forceinline__ void rms_row(const float* xrow, const float* g, void* orow, int lane) {
;     const f32x4* xr = (const f32x4*)xrow + lane;
;     f32x4 v[8]; float s = 0.f;
; #pragma unroll
;     for (int j = 0; j < 8; ++j) { v[j] = xr[64 * j]; s += (v[j].x * v[j].x + v[j].y * v[j].y) + (v[j].z * v[j].z + v[j].w * v[j].w); }
;     const float rstd = 1.0f / sqrtf(wave_sum(s) * (1.0f / D) + 1e-6f);
; __global__ void __launch_bounds__(512, 2) mega_fwd(Params p) {
;     ...
;     { PHASE_IDS; PHASE_ENV;
;     for (int m = gw; m < M; m += ngw) rms_row<true>(P_X + (size_t)m * D, p.in[14], p.out + (size_t)m * D, lane); }
.LBB0_957:
	s_nop 0
	v_lshl_add_u64 v[0:1], s[6:7], 0, v[16:17]
	v_add_co_u32_e64 v58, s[0:1], s3, v0
	v_add_co_u32_e32 v56, vcc, 0xcc00000, v0
	s_nop 0
	v_addc_co_u32_e64 v59, s[0:1], 0, v1, s[0:1]
	v_addc_co_u32_e32 v57, vcc, 0, v1, vcc
	global_load_dwordx4 v[4:7], v[58:59], off
	global_load_dwordx4 v[12:15], v[58:59], off offset:1024
	global_load_dwordx4 v[8:11], v[58:59], off offset:2048
	global_load_dwordx4 v[36:39], v[56:57], off
	global_load_dwordx4 v[40:43], v[56:57], off offset:1024
	global_load_dwordx4 v[44:47], v[56:57], off offset:2048
	global_load_dwordx4 v[48:51], v[56:57], off offset:3072
	global_load_dwordx4 v[0:3], v[58:59], off offset:3072
	global_load_dwordx4 v[52:55], v[18:19], off
	v_lshl_add_u64 v[56:57], s[10:11], 0, v[16:17]
	s_add_i32 s2, s2, s4
	s_add_u32 s6, s6, s8
	s_addc_u32 s7, s7, s9
	s_add_u32 s10, s10, s8
	s_addc_u32 s11, s11, s9
	s_cmpk_gt_i32 s2, 0x1fff
	s_waitcnt vmcnt(0)
	v_mul_f32_e32 v81, v4, v4
	v_pk_mul_f32 v[58:59], v[14:15], v[14:15]
	v_pk_mul_f32 v[60:61], v[12:13], v[12:13]
	v_mul_f32_e32 v62, v9, v9
	v_mul_f32_e32 v64, v11, v11
	v_mov_b32_e32 v68, v37
	v_mov_b32_e32 v69, v41
	v_mov_b32_e32 v72, v39
	v_mov_b32_e32 v73, v43
	v_mul_f32_e32 v89, v2, v2
	v_mul_f32_e32 v90, v3, v3
	v_mov_b32_e32 v66, v36
	v_mov_b32_e32 v67, v40
	v_mov_b32_e32 v70, v38
	v_mov_b32_e32 v71, v42
	v_pk_mul_f32 v[74:75], v[46:47], v[46:47]
	v_pk_mul_f32 v[76:77], v[44:45], v[44:45]
	v_pk_mov_b32 v[82:83], v[60:61], v[58:59] op_sel:[1,0]
	v_mov_b32_e32 v61, v59
	v_pk_fma_f32 v[58:59], v[8:9], v[8:9], v[62:63] op_sel_hi:[1,1,0]
	v_pk_fma_f32 v[62:63], v[10:11], v[10:11], v[64:65] op_sel_hi:[1,1,0]
	v_pk_mul_f32 v[64:65], v[68:69], v[68:69]
	v_pk_mul_f32 v[68:69], v[72:73], v[72:73]
	v_pk_mov_b32 v[72:73], v[76:77], v[74:75] op_sel:[1,0]
	v_mov_b32_e32 v77, v75
	v_mov_b32_e32 v59, v89
	v_mov_b32_e32 v63, v90
	v_pk_fma_f32 v[64:65], v[66:67], v[66:67], v[64:65]
	v_pk_fma_f32 v[66:67], v[70:71], v[70:71], v[68:69]
	v_mul_f32_e32 v78, v49, v49
	v_mul_f32_e32 v80, v51, v51
	v_pk_add_f32 v[68:69], v[72:73], v[76:77]
	v_pk_add_f32 v[58:59], v[58:59], v[62:63]
	v_pk_add_f32 v[62:63], v[64:65], v[66:67]
	v_mul_f32_e32 v84, v5, v5
	v_mul_f32_e32 v85, v6, v6
	v_mul_f32_e32 v86, v7, v7
	v_pk_fma_f32 v[74:75], v[48:49], v[48:49], v[78:79] op_sel_hi:[1,1,0]
	v_pk_fma_f32 v[78:79], v[50:51], v[50:51], v[80:81] op_sel_hi:[1,1,0]
	v_pk_add_f32 v[64:65], v[68:69], v[68:69] op_sel:[0,1] op_sel_hi:[1,0]
	v_pk_add_f32 v[62:63], v[62:63], v[62:63] op_sel:[0,1] op_sel_hi:[1,0]
	v_mov_b32_e32 v75, v85
	v_mov_b32_e32 v79, v86
	v_mov_b32_e32 v65, v84
	v_mov_b32_e32 v63, v81
	v_pk_add_f32 v[66:67], v[74:75], v[78:79]
	v_pk_add_f32 v[62:63], v[62:63], v[64:65]
	v_pk_add_f32 v[60:61], v[82:83], v[60:61]
	v_pk_add_f32 v[62:63], v[62:63], v[66:67]
	v_mul_f32_e32 v87, v0, v0
	v_mul_f32_e32 v88, v1, v1
	v_pk_add_f32 v[60:61], v[60:61], v[60:61] op_sel:[0,1] op_sel_hi:[1,0]
	v_pk_add_f32 v[62:63], v[62:63], v[62:63] op_sel:[0,1] op_sel_hi:[1,0]
	v_mov_b32_e32 v61, v88
	v_mov_b32_e32 v63, v87
	v_pk_add_f32 v[60:61], v[62:63], v[60:61]
	s_nop 0
	v_pk_add_f32 v[58:59], v[60:61], v[58:59]
	s_nop 0
	v_add_f32_e32 v58, v58, v59
	ds_bpermute_b32 v59, v28, v58
	s_waitcnt lgkmcnt(0)
	v_add_f32_e32 v58, v58, v59
	ds_bpermute_b32 v59, v29, v58
	s_waitcnt lgkmcnt(0)
	v_add_f32_e32 v58, v58, v59
	ds_bpermute_b32 v59, v30, v58
	s_waitcnt lgkmcnt(0)
	v_add_f32_e32 v58, v58, v59
	ds_bpermute_b32 v59, v31, v58
	s_waitcnt lgkmcnt(0)
	v_add_f32_e32 v58, v58, v59
	ds_bpermute_b32 v59, v32, v58
	s_waitcnt lgkmcnt(0)
	v_add_f32_e32 v58, v58, v59
	ds_bpermute_b32 v59, v33, v58
	s_waitcnt lgkmcnt(0)
; __device__ __forceinline__ unsigned pk2(float lo, float hi) { f32x2 f = {lo, hi}; bf16x2_t b = __builtin_convertvector(f, bf16x2_t); return __builtin_bit_cast(unsigned, b); }
; template <bool F32OUT>
; __device__ __forceinline__ void rms_row(const float* xrow, const float* g, void* orow, int lane) {
;     ...
;     const float rstd = 1.0f / sqrtf(wave_sum(s) * (1.0f / D) + 1e-6f);
;     const f32x4* gr = (const f32x4*)g + lane;
; #pragma unroll
;     for (int j = 0; j < 8; ++j) {
;         const f32x4 gg = gr[64 * j];
;         const f32x4 o = v[j] * rstd * gg;
;         if (F32OUT) ((f32x4*)orow)[lane + 64 * j] = o;
;         else { u32x2 w; w.x = pk2(o.x, o.y); w.y = pk2(o.z, o.w); ((u32x2*)orow)[lane + 64 * j] = w; }
	v_add_f32_e32 v58, v58, v59
	v_fmamk_f32 v58, v58, 0x3a000000, v34
	v_mul_f32_e32 v59, 0x4f800000, v58
	v_cmp_gt_f32_e32 vcc, s5, v58
	s_nop 1
	v_cndmask_b32_e32 v58, v58, v59, vcc
	v_sqrt_f32_e32 v59, v58
	s_nop 0
	v_add_u32_e32 v60, -1, v59
	v_add_u32_e32 v61, 1, v59
	v_fma_f32 v62, -v60, v59, v58
	v_fma_f32 v63, -v61, v59, v58
	v_cmp_ge_f32_e64 s[0:1], 0, v62
	s_nop 1
	v_cndmask_b32_e64 v59, v59, v60, s[0:1]
	v_cmp_lt_f32_e64 s[0:1], 0, v63
	s_nop 1
	v_cndmask_b32_e64 v59, v59, v61, s[0:1]
	v_mul_f32_e32 v60, 0x37800000, v59
	v_cndmask_b32_e32 v59, v59, v60, vcc
	v_cmp_class_f32_e32 vcc, v58, v35
	s_nop 1
	v_cndmask_b32_e32 v58, v59, v58, vcc
	v_div_scale_f32 v59, s[0:1], v58, v58, 1.0
	v_rcp_f32_e32 v61, v59
	v_div_scale_f32 v60, vcc, 1.0, v58, 1.0
	v_fma_f32 v62, -v59, v61, 1.0
	v_fmac_f32_e32 v61, v62, v61
	v_mul_f32_e32 v62, v60, v61
	v_fma_f32 v63, -v59, v62, v60
	v_fmac_f32_e32 v62, v63, v61
	v_fma_f32 v59, -v59, v62, v60
	v_div_fmas_f32 v59, v59, v61, v62
	v_div_fixup_f32 v58, v59, v58, 1.0
	v_pk_mul_f32 v[36:37], v[36:37], v[58:59] op_sel_hi:[1,0]
	v_pk_mul_f32 v[38:39], v[38:39], v[58:59] op_sel_hi:[1,0]
	v_pk_mul_f32 v[36:37], v[52:53], v[36:37]
	v_pk_mul_f32 v[38:39], v[54:55], v[38:39]
	global_store_dwordx4 v[56:57], v[36:39], off
	global_load_dwordx4 v[36:39], v[18:19], off offset:1024
	v_pk_mul_f32 v[42:43], v[42:43], v[58:59] op_sel_hi:[1,0]
	v_pk_mul_f32 v[40:41], v[40:41], v[58:59] op_sel_hi:[1,0]
	v_pk_mul_f32 v[6:7], v[6:7], v[58:59] op_sel_hi:[1,0]
	v_pk_mul_f32 v[4:5], v[4:5], v[58:59] op_sel_hi:[1,0]
	v_pk_mul_f32 v[14:15], v[14:15], v[58:59] op_sel_hi:[1,0]
	v_pk_mul_f32 v[12:13], v[12:13], v[58:59] op_sel_hi:[1,0]
	v_pk_mul_f32 v[10:11], v[10:11], v[58:59] op_sel_hi:[1,0]
	v_pk_mul_f32 v[8:9], v[8:9], v[58:59] op_sel_hi:[1,0]
	v_pk_mul_f32 v[2:3], v[2:3], v[58:59] op_sel_hi:[1,0]
	v_pk_mul_f32 v[0:1], v[0:1], v[58:59] op_sel_hi:[1,0]
	s_waitcnt vmcnt(0)
	v_pk_mul_f32 v[36:37], v[36:37], v[40:41]
	v_pk_mul_f32 v[38:39], v[38:39], v[42:43]
	global_store_dwordx4 v[56:57], v[36:39], off offset:1024
	global_load_dwordx4 v[36:39], v[18:19], off offset:2048
	v_pk_mul_f32 v[40:41], v[46:47], v[58:59] op_sel_hi:[1,0]
	v_pk_mul_f32 v[42:43], v[44:45], v[58:59] op_sel_hi:[1,0]
	s_waitcnt vmcnt(0)
	v_pk_mul_f32 v[38:39], v[38:39], v[40:41]
	v_pk_mul_f32 v[36:37], v[36:37], v[42:43]
	global_store_dwordx4 v[56:57], v[36:39], off offset:2048
	global_load_dwordx4 v[36:39], v[18:19], off offset:3072
	v_pk_mul_f32 v[40:41], v[50:51], v[58:59] op_sel_hi:[1,0]
	v_pk_mul_f32 v[42:43], v[48:49], v[58:59] op_sel_hi:[1,0]
	s_waitcnt vmcnt(0)
	v_pk_mul_f32 v[38:39], v[38:39], v[40:41]
	v_pk_mul_f32 v[36:37], v[36:37], v[42:43]
	global_store_dwordx4 v[56:57], v[36:39], off offset:3072
	global_load_dwordx4 v[36:39], v[20:21], off
	v_add_co_u32_e32 v40, vcc, s12, v56
	s_waitcnt vmcnt(0)
	v_pk_mul_f32 v[4:5], v[36:37], v[4:5]
	v_addc_co_u32_e32 v41, vcc, 0, v57, vcc
	v_pk_mul_f32 v[6:7], v[38:39], v[6:7]
	global_store_dwordx4 v[40:41], v[4:7], off
	global_load_dwordx4 v[4:7], v[22:23], off
	s_waitcnt vmcnt(0)
	v_pk_mul_f32 v[4:5], v[12:13], v[4:5]
	v_pk_mul_f32 v[6:7], v[14:15], v[6:7]
	global_store_dwordx4 v[40:41], v[4:7], off offset:1024
	global_load_dwordx4 v[4:7], v[24:25], off
	s_waitcnt vmcnt(0)
	v_pk_mul_f32 v[4:5], v[8:9], v[4:5]
	v_pk_mul_f32 v[6:7], v[10:11], v[6:7]
	global_store_dwordx4 v[40:41], v[4:7], off offset:2048
	global_load_dwordx4 v[4:7], v[26:27], off
	s_waitcnt vmcnt(0)
	v_pk_mul_f32 v[0:1], v[0:1], v[4:5]
	v_pk_mul_f32 v[2:3], v[2:3], v[6:7]
	global_store_dwordx4 v[40:41], v[0:3], off offset:3072
	s_cbranch_scc0 .LBB0_957
